# GEMM K-loops: removed the back-to-back s_setprio 0 / s_setprio 1 pair in the middle of each 32-MFMA block (priority stays raised across the block); on top of v56
# baseline (speedup 1.0000x reference)
; #define PG8_STAGE(bufoff, gbase, voff) do { _Pragma("unroll") for (int _i = 0; _i < 2; ++_i) \
;         __builtin_amdgcn_global_load_lds((const unsigned*)((const char*)(gbase) + (voff)[_i]), (PG8_LAS unsigned*)(lds + (bufoff) + ldsw + _i * 8192), 16, 0, 0); } while (0)
; #define PG8_LDA(dst, b, h) do { _Pragma("unroll") for (int m = 0; m < 4; ++m) _Pragma("unroll") for (int k = 0; k < 2; ++k) dst[m][k] = *(const PG8_LAS bf16x8*)(lds + PG8_SA(b, h) + aoff + m * 2048 + k * 1024); } while (0)
; #define PG8_LDB(dst, b, h) do { _Pragma("unroll") for (int n = 0; n < 2; ++n) _Pragma("unroll") for (int k = 0; k < 2; ++k) dst[n][k] = *(const PG8_LAS bf16x8*)(lds + PG8_SB(b, h) + boff + n * 2048 + k * 1024); } while (0)
; #define PG8_MMA(ai, bj, At, Bt) do { __builtin_amdgcn_s_setprio(1); _Pragma("unroll") for (int m = 0; m < 4; ++m) _Pragma("unroll") for (int n = 0; n < 2; ++n) _Pragma("unroll") for (int k = 0; k < 2; ++k) \
;         acc[ai][bj][m][n] = __builtin_amdgcn_mfma_f32_16x16x32_bf16(Bt[n][k], At[m][k], acc[ai][bj][m][n], 0, 0, 0); __builtin_amdgcn_s_setprio(0); } while (0)
; #define PG8_WAIT_V(n) asm volatile("s_waitcnt vmcnt(" #n ")" ::: "memory")
; #define PG8_WAIT_L(n) asm volatile("s_waitcnt lgkmcnt(" #n ")" ::: "memory")
; #define PG8_BAR __builtin_amdgcn_s_barrier()
; #define PG8_SCHED __builtin_amdgcn_sched_barrier(0)
; template <class Epi, class Sched, bool ALIGN_EPI = false, bool SP2 = false>
; __device__ __forceinline__ void gemm_phase(PG8_LAS unsigned char* lds, const Gemm g, const Sched& S, const Epi& E) {
;     ...
;             const char* a2 = last ? nA : cA + (size_t)(t + 2) * kstep; const char* b2 = last ? nB : cB + (size_t)(t + 2) * kstep;
;             const char* a3 = a2 + kstep; const char* b3 = b2 + kstep;
;             if (last && has_next) S.a_ready(nxt);
;             if constexpr (SP2) {
;             PG8_LDB(B0, 0, 0); PG8_LDB(B1, 0, 1); PG8_SCHED; PG8_LDA(At, 0, 0); PG8_STAGE(PG8_SA(1, 1), a1 + hstep, voffA);
;             PG8_WAIT_V(8); PG8_WAIT_L(0); PG8_BAR; PG8_MMA(0, 0, At, B0); PG8_MMA(0, 1, At, B1); PG8_BAR; PG8_SCHED;
;             PG8_LDA(At, 0, 1); PG8_STAGE(PG8_SB(0, 0), b2, voffB); PG8_STAGE(PG8_SB(0, 1), b2 + hstep, voffB); PG8_STAGE(PG8_SA(0, 0), a2, voffA);
.LBB0_36:
	s_add_i32 s87, s50, 2
	s_add_u32 s64, s48, 0x80
	s_addc_u32 s51, s49, 0
	s_add_i32 s66, 0, 0x10000
	s_cmp_eq_u32 s61, s50
	s_cselect_b32 s51, s43, s51
	s_cselect_b32 s50, s42, s64
	s_cselect_b32 s65, s45, s86
	s_cselect_b32 s64, s44, s85
	s_add_i32 s67, 0, 0x14000
	v_add_u32_e32 v160, s66, v145
	v_add_u32_e32 v176, s67, v145
	ds_read_b128 v[148:151], v160
	ds_read_b128 v[152:155], v160 offset:1024
	ds_read_b128 v[156:159], v160 offset:2048
	ds_read_b128 v[160:163], v160 offset:3072
	ds_read_b128 v[164:167], v176
	ds_read_b128 v[168:171], v176 offset:1024
	ds_read_b128 v[172:175], v176 offset:2048
	ds_read_b128 v[176:179], v176 offset:3072
	v_lshl_add_u64 v[192:193], s[48:49], 0, v[140:141]
	s_add_i32 m0, s54, 0xc000
	ds_read_b128 v[180:183], v147
	ds_read_b128 v[184:187], v147 offset:1024
	ds_read_b128 v[188:191], v147 offset:2048
	ds_read_b128 v[208:211], v147 offset:3072
	ds_read_b128 v[212:215], v147 offset:4096
	ds_read_b128 v[216:219], v147 offset:5120
	ds_read_b128 v[220:223], v147 offset:6144
	ds_read_b128 v[236:239], v147 offset:7168
	global_load_lds_dwordx4 v[192:193], off
	v_lshl_add_u64 v[192:193], s[48:49], 0, v[142:143]
	s_add_i32 m0, s54, 0xe000
	s_nop 0
	global_load_lds_dwordx4 v[192:193], off
	s_waitcnt vmcnt(8)
	s_waitcnt lgkmcnt(0)
	s_barrier
	s_setprio 1
	s_waitcnt lgkmcnt(0)
	v_mfma_f32_16x16x32_bf16 v[122:125], v[148:151], v[180:183], v[122:125]
	v_mfma_f32_16x16x32_bf16 v[126:129], v[156:159], v[180:183], v[126:129]
	v_mfma_f32_16x16x32_bf16 v[110:113], v[148:151], v[188:191], v[110:113]
	v_mfma_f32_16x16x32_bf16 v[106:109], v[156:159], v[188:191], v[106:109]
	v_mfma_f32_16x16x32_bf16 v[94:97], v[148:151], v[212:215], v[94:97]
	v_mfma_f32_16x16x32_bf16 v[90:93], v[156:159], v[212:215], v[90:93]
	v_mfma_f32_16x16x32_bf16 v[78:81], v[148:151], v[220:223], v[78:81]
	v_mfma_f32_16x16x32_bf16 v[74:77], v[156:159], v[220:223], v[74:77]
	v_mfma_f32_16x16x32_bf16 v[122:125], v[152:155], v[184:187], v[122:125]
	v_mfma_f32_16x16x32_bf16 v[126:129], v[160:163], v[184:187], v[126:129]
	v_mfma_f32_16x16x32_bf16 v[110:113], v[152:155], v[208:211], v[110:113]
	v_mfma_f32_16x16x32_bf16 v[106:109], v[160:163], v[208:211], v[106:109]
	v_mfma_f32_16x16x32_bf16 v[94:97], v[152:155], v[216:219], v[94:97]
	v_mfma_f32_16x16x32_bf16 v[90:93], v[160:163], v[216:219], v[90:93]
	v_mfma_f32_16x16x32_bf16 v[78:81], v[152:155], v[236:239], v[78:81]
	v_mfma_f32_16x16x32_bf16 v[74:77], v[160:163], v[236:239], v[74:77]
	v_mfma_f32_16x16x32_bf16 v[118:121], v[164:167], v[180:183], v[118:121]
	v_mfma_f32_16x16x32_bf16 v[114:117], v[172:175], v[180:183], v[114:117]
	v_mfma_f32_16x16x32_bf16 v[102:105], v[164:167], v[188:191], v[102:105]
	v_mfma_f32_16x16x32_bf16 v[98:101], v[172:175], v[188:191], v[98:101]
	v_mfma_f32_16x16x32_bf16 v[86:89], v[164:167], v[212:215], v[86:89]
	v_mfma_f32_16x16x32_bf16 v[82:85], v[172:175], v[212:215], v[82:85]
	v_mfma_f32_16x16x32_bf16 v[70:73], v[164:167], v[220:223], v[70:73]
	v_mfma_f32_16x16x32_bf16 v[66:69], v[172:175], v[220:223], v[66:69]
	v_mfma_f32_16x16x32_bf16 v[118:121], v[168:171], v[184:187], v[118:121]
	v_mfma_f32_16x16x32_bf16 v[114:117], v[176:179], v[184:187], v[114:117]
	v_mfma_f32_16x16x32_bf16 v[102:105], v[168:171], v[208:211], v[102:105]
	v_mfma_f32_16x16x32_bf16 v[98:101], v[176:179], v[208:211], v[98:101]
	v_mfma_f32_16x16x32_bf16 v[86:89], v[168:171], v[216:219], v[86:89]
	v_mfma_f32_16x16x32_bf16 v[82:85], v[176:179], v[216:219], v[82:85]
	v_mfma_f32_16x16x32_bf16 v[70:73], v[168:171], v[236:239], v[70:73]
	v_mfma_f32_16x16x32_bf16 v[66:69], v[176:179], v[236:239], v[66:69]
	s_setprio 0
	s_barrier
	s_add_i32 s66, s66, s53
	v_lshl_add_u64 v[192:193], s[64:65], 0, v[0:1]
	s_mov_b32 m0, s66
	ds_read_b128 v[180:183], v147 offset:16384
	ds_read_b128 v[184:187], v147 offset:17408
	ds_read_b128 v[188:191], v147 offset:18432
	ds_read_b128 v[208:211], v147 offset:19456
	ds_read_b128 v[212:215], v147 offset:20480
	ds_read_b128 v[216:219], v147 offset:21504
	ds_read_b128 v[220:223], v147 offset:22528
	ds_read_b128 v[236:239], v147 offset:23552
	global_load_lds_dwordx4 v[192:193], off
	s_add_i32 m0, s66, 0x2000
	v_lshl_add_u64 v[198:199], s[64:65], 0, v[134:135]
	s_add_u32 s64, s64, s4
	s_addc_u32 s65, s65, s5
	s_add_i32 s66, s67, s53
	global_load_lds_dwordx4 v[198:199], off
	v_lshl_add_u64 v[200:201], s[64:65], 0, v[0:1]
	s_mov_b32 m0, s66
	v_lshl_add_u64 v[202:203], s[64:65], 0, v[134:135]
	global_load_lds_dwordx4 v[200:201], off
	s_add_i32 m0, s66, 0x2000
	v_lshl_add_u64 v[204:205], s[50:51], 0, v[138:139]
	global_load_lds_dwordx4 v[202:203], off
	s_mov_b32 m0, s54
	v_lshl_add_u64 v[224:225], s[50:51], 0, v[136:137]
	global_load_lds_dwordx4 v[204:205], off
	s_mov_b32 m0, s55
	s_nop 0
	global_load_lds_dwordx4 v[224:225], off
	s_waitcnt vmcnt(8)
	s_waitcnt lgkmcnt(0)
	s_barrier
; #define PG8_STAGE(bufoff, gbase, voff) do { _Pragma("unroll") for (int _i = 0; _i < 2; ++_i) \
;         __builtin_amdgcn_global_load_lds((const unsigned*)((const char*)(gbase) + (voff)[_i]), (PG8_LAS unsigned*)(lds + (bufoff) + ldsw + _i * 8192), 16, 0, 0); } while (0)
; #define PG8_LDA(dst, b, h) do { _Pragma("unroll") for (int m = 0; m < 4; ++m) _Pragma("unroll") for (int k = 0; k < 2; ++k) dst[m][k] = *(const PG8_LAS bf16x8*)(lds + PG8_SA(b, h) + aoff + m * 2048 + k * 1024); } while (0)
; #define PG8_LDB(dst, b, h) do { _Pragma("unroll") for (int n = 0; n < 2; ++n) _Pragma("unroll") for (int k = 0; k < 2; ++k) dst[n][k] = *(const PG8_LAS bf16x8*)(lds + PG8_SB(b, h) + boff + n * 2048 + k * 1024); } while (0)
; #define PG8_MMA(ai, bj, At, Bt) do { __builtin_amdgcn_s_setprio(1); _Pragma("unroll") for (int m = 0; m < 4; ++m) _Pragma("unroll") for (int n = 0; n < 2; ++n) _Pragma("unroll") for (int k = 0; k < 2; ++k) \
;         acc[ai][bj][m][n] = __builtin_amdgcn_mfma_f32_16x16x32_bf16(Bt[n][k], At[m][k], acc[ai][bj][m][n], 0, 0, 0); __builtin_amdgcn_s_setprio(0); } while (0)
; #define PG8_WAIT_V(n) asm volatile("s_waitcnt vmcnt(" #n ")" ::: "memory")
; #define PG8_WAIT_L(n) asm volatile("s_waitcnt lgkmcnt(" #n ")" ::: "memory")
; #define PG8_BAR __builtin_amdgcn_s_barrier()
; #define PG8_SCHED __builtin_amdgcn_sched_barrier(0)
; template <class Epi, class Sched, bool ALIGN_EPI = false, bool SP2 = false>
; __device__ __forceinline__ void gemm_phase(PG8_LAS unsigned char* lds, const Gemm g, const Sched& S, const Epi& E) {
;     ...
;             PG8_WAIT_V(8); PG8_WAIT_L(0); PG8_BAR; PG8_MMA(1, 0, At, B0); PG8_MMA(1, 1, At, B1); PG8_BAR; PG8_SCHED;
;             PG8_LDB(B0, 1, 0); PG8_LDB(B1, 1, 1); PG8_SCHED; PG8_LDA(At, 1, 0); PG8_STAGE(PG8_SA(0, 1), a2 + hstep, voffA);
;             PG8_WAIT_V(8); PG8_WAIT_L(0); PG8_BAR; PG8_MMA(0, 0, At, B0); PG8_MMA(0, 1, At, B1); PG8_BAR; PG8_SCHED;
	s_setprio 1
	s_waitcnt lgkmcnt(0)
	v_mfma_f32_16x16x32_bf16 v[62:65], v[148:151], v[180:183], v[62:65]
	v_mfma_f32_16x16x32_bf16 v[58:61], v[156:159], v[180:183], v[58:61]
	v_mfma_f32_16x16x32_bf16 v[46:49], v[148:151], v[188:191], v[46:49]
	v_mfma_f32_16x16x32_bf16 v[42:45], v[156:159], v[188:191], v[42:45]
	v_mfma_f32_16x16x32_bf16 v[30:33], v[148:151], v[212:215], v[30:33]
	v_mfma_f32_16x16x32_bf16 v[26:29], v[156:159], v[212:215], v[26:29]
	v_mfma_f32_16x16x32_bf16 v[14:17], v[148:151], v[220:223], v[14:17]
	v_mfma_f32_16x16x32_bf16 v[10:13], v[156:159], v[220:223], v[10:13]
	v_mfma_f32_16x16x32_bf16 v[62:65], v[152:155], v[184:187], v[62:65]
	v_mfma_f32_16x16x32_bf16 v[58:61], v[160:163], v[184:187], v[58:61]
	v_mfma_f32_16x16x32_bf16 v[46:49], v[152:155], v[208:211], v[46:49]
	v_mfma_f32_16x16x32_bf16 v[42:45], v[160:163], v[208:211], v[42:45]
	v_mfma_f32_16x16x32_bf16 v[30:33], v[152:155], v[216:219], v[30:33]
	v_mfma_f32_16x16x32_bf16 v[26:29], v[160:163], v[216:219], v[26:29]
	v_mfma_f32_16x16x32_bf16 v[14:17], v[152:155], v[236:239], v[14:17]
	v_mfma_f32_16x16x32_bf16 v[10:13], v[160:163], v[236:239], v[10:13]
	v_mfma_f32_16x16x32_bf16 v[54:57], v[164:167], v[180:183], v[54:57]
	v_mfma_f32_16x16x32_bf16 v[50:53], v[172:175], v[180:183], v[50:53]
	v_mfma_f32_16x16x32_bf16 v[38:41], v[164:167], v[188:191], v[38:41]
	v_mfma_f32_16x16x32_bf16 v[34:37], v[172:175], v[188:191], v[34:37]
	v_mfma_f32_16x16x32_bf16 v[22:25], v[164:167], v[212:215], v[22:25]
	v_mfma_f32_16x16x32_bf16 v[18:21], v[172:175], v[212:215], v[18:21]
	v_mfma_f32_16x16x32_bf16 v[6:9], v[164:167], v[220:223], v[6:9]
	v_mfma_f32_16x16x32_bf16 v[2:5], v[172:175], v[220:223], v[2:5]
	v_mfma_f32_16x16x32_bf16 v[54:57], v[168:171], v[184:187], v[54:57]
	v_mfma_f32_16x16x32_bf16 v[50:53], v[176:179], v[184:187], v[50:53]
	v_mfma_f32_16x16x32_bf16 v[38:41], v[168:171], v[208:211], v[38:41]
	v_mfma_f32_16x16x32_bf16 v[34:37], v[176:179], v[208:211], v[34:37]
	v_mfma_f32_16x16x32_bf16 v[22:25], v[168:171], v[216:219], v[22:25]
	v_mfma_f32_16x16x32_bf16 v[18:21], v[176:179], v[216:219], v[18:21]
	v_mfma_f32_16x16x32_bf16 v[6:9], v[168:171], v[236:239], v[6:9]
	v_mfma_f32_16x16x32_bf16 v[2:5], v[176:179], v[236:239], v[2:5]
	s_setprio 0
	s_barrier
	s_add_i32 s64, 0, 0x18000
	s_add_i32 s65, 0, 0x1c000
	v_add_u32_e32 v160, s64, v145
	v_add_u32_e32 v176, s65, v145
	ds_read_b128 v[148:151], v160
	ds_read_b128 v[152:155], v160 offset:1024
	ds_read_b128 v[156:159], v160 offset:2048
	ds_read_b128 v[160:163], v160 offset:3072
	ds_read_b128 v[164:167], v176
	ds_read_b128 v[168:171], v176 offset:1024
	ds_read_b128 v[172:175], v176 offset:2048
	ds_read_b128 v[176:179], v176 offset:3072
	s_add_u32 s50, s50, s4
	s_addc_u32 s51, s51, s5
	s_mov_b32 m0, s56
	v_lshl_add_u64 v[228:229], s[50:51], 0, v[138:139]
	ds_read_b128 v[180:183], v147 offset:32768
	ds_read_b128 v[184:187], v147 offset:33792
	ds_read_b128 v[188:191], v147 offset:34816
	ds_read_b128 v[208:211], v147 offset:35840
	ds_read_b128 v[212:215], v147 offset:36864
	ds_read_b128 v[216:219], v147 offset:37888
	ds_read_b128 v[220:223], v147 offset:38912
	ds_read_b128 v[236:239], v147 offset:39936
	global_load_lds_dwordx4 v[228:229], off
	v_lshl_add_u64 v[228:229], s[50:51], 0, v[136:137]
	s_mov_b32 m0, s57
	s_nop 0
	global_load_lds_dwordx4 v[228:229], off
	s_waitcnt vmcnt(8)
	s_waitcnt lgkmcnt(0)
	s_barrier
	s_setprio 1
	s_waitcnt lgkmcnt(0)
	v_mfma_f32_16x16x32_bf16 v[122:125], v[148:151], v[180:183], v[122:125]
	v_mfma_f32_16x16x32_bf16 v[126:129], v[156:159], v[180:183], v[126:129]
	v_mfma_f32_16x16x32_bf16 v[110:113], v[148:151], v[188:191], v[110:113]
	v_mfma_f32_16x16x32_bf16 v[106:109], v[156:159], v[188:191], v[106:109]
	v_mfma_f32_16x16x32_bf16 v[94:97], v[148:151], v[212:215], v[94:97]
	v_mfma_f32_16x16x32_bf16 v[90:93], v[156:159], v[212:215], v[90:93]
	v_mfma_f32_16x16x32_bf16 v[78:81], v[148:151], v[220:223], v[78:81]
	v_mfma_f32_16x16x32_bf16 v[74:77], v[156:159], v[220:223], v[74:77]
	v_mfma_f32_16x16x32_bf16 v[122:125], v[152:155], v[184:187], v[122:125]
	v_mfma_f32_16x16x32_bf16 v[126:129], v[160:163], v[184:187], v[126:129]
	v_mfma_f32_16x16x32_bf16 v[110:113], v[152:155], v[208:211], v[110:113]
	v_mfma_f32_16x16x32_bf16 v[106:109], v[160:163], v[208:211], v[106:109]
	v_mfma_f32_16x16x32_bf16 v[94:97], v[152:155], v[216:219], v[94:97]
	v_mfma_f32_16x16x32_bf16 v[90:93], v[160:163], v[216:219], v[90:93]
	v_mfma_f32_16x16x32_bf16 v[78:81], v[152:155], v[236:239], v[78:81]
	v_mfma_f32_16x16x32_bf16 v[74:77], v[160:163], v[236:239], v[74:77]
	v_mfma_f32_16x16x32_bf16 v[118:121], v[164:167], v[180:183], v[118:121]
	v_mfma_f32_16x16x32_bf16 v[114:117], v[172:175], v[180:183], v[114:117]
	v_mfma_f32_16x16x32_bf16 v[102:105], v[164:167], v[188:191], v[102:105]
	v_mfma_f32_16x16x32_bf16 v[98:101], v[172:175], v[188:191], v[98:101]
	v_mfma_f32_16x16x32_bf16 v[86:89], v[164:167], v[212:215], v[86:89]
	v_mfma_f32_16x16x32_bf16 v[82:85], v[172:175], v[212:215], v[82:85]
	v_mfma_f32_16x16x32_bf16 v[70:73], v[164:167], v[220:223], v[70:73]
	v_mfma_f32_16x16x32_bf16 v[66:69], v[172:175], v[220:223], v[66:69]
	v_mfma_f32_16x16x32_bf16 v[118:121], v[168:171], v[184:187], v[118:121]
	v_mfma_f32_16x16x32_bf16 v[114:117], v[176:179], v[184:187], v[114:117]
	v_mfma_f32_16x16x32_bf16 v[102:105], v[168:171], v[208:211], v[102:105]
	v_mfma_f32_16x16x32_bf16 v[98:101], v[176:179], v[208:211], v[98:101]
	v_mfma_f32_16x16x32_bf16 v[86:89], v[168:171], v[216:219], v[86:89]
	v_mfma_f32_16x16x32_bf16 v[82:85], v[176:179], v[216:219], v[82:85]
	v_mfma_f32_16x16x32_bf16 v[70:73], v[168:171], v[236:239], v[70:73]
	v_mfma_f32_16x16x32_bf16 v[66:69], v[176:179], v[236:239], v[66:69]
	s_setprio 0
	s_barrier
; #define PG8_STAGE(bufoff, gbase, voff) do { _Pragma("unroll") for (int _i = 0; _i < 2; ++_i) \
;         __builtin_amdgcn_global_load_lds((const unsigned*)((const char*)(gbase) + (voff)[_i]), (PG8_LAS unsigned*)(lds + (bufoff) + ldsw + _i * 8192), 16, 0, 0); } while (0)
; #define PG8_LDA(dst, b, h) do { _Pragma("unroll") for (int m = 0; m < 4; ++m) _Pragma("unroll") for (int k = 0; k < 2; ++k) dst[m][k] = *(const PG8_LAS bf16x8*)(lds + PG8_SA(b, h) + aoff + m * 2048 + k * 1024); } while (0)
; #define PG8_MMA(ai, bj, At, Bt) do { __builtin_amdgcn_s_setprio(1); _Pragma("unroll") for (int m = 0; m < 4; ++m) _Pragma("unroll") for (int n = 0; n < 2; ++n) _Pragma("unroll") for (int k = 0; k < 2; ++k) \
;         acc[ai][bj][m][n] = __builtin_amdgcn_mfma_f32_16x16x32_bf16(Bt[n][k], At[m][k], acc[ai][bj][m][n], 0, 0, 0); __builtin_amdgcn_s_setprio(0); } while (0)
; #define PG8_WAIT_V(n) asm volatile("s_waitcnt vmcnt(" #n ")" ::: "memory")
; #define PG8_WAIT_L(n) asm volatile("s_waitcnt lgkmcnt(" #n ")" ::: "memory")
; #define PG8_BAR __builtin_amdgcn_s_barrier()
; #define PG8_SCHED __builtin_amdgcn_sched_barrier(0)
; template <class Epi, class Sched, bool ALIGN_EPI = false, bool SP2 = false>
; __device__ __forceinline__ void gemm_phase(PG8_LAS unsigned char* lds, const Gemm g, const Sched& S, const Epi& E) {
;     ...
;             PG8_LDA(At, 1, 1); PG8_STAGE(PG8_SB(1, 0), b3, voffB); PG8_STAGE(PG8_SB(1, 1), b3 + hstep, voffB); PG8_STAGE(PG8_SA(1, 0), a3, voffA);
;             PG8_WAIT_V(8); PG8_WAIT_L(0); PG8_BAR; PG8_MMA(1, 0, At, B0); PG8_MMA(1, 1, At, B1); PG8_BAR; PG8_SCHED;
	s_add_i32 s50, s64, s53
	v_lshl_add_u64 v[192:193], v[192:193], 0, s[26:27]
	s_mov_b32 m0, s50
	ds_read_b128 v[180:183], v147 offset:49152
	ds_read_b128 v[184:187], v147 offset:50176
	ds_read_b128 v[188:191], v147 offset:51200
	ds_read_b128 v[208:211], v147 offset:52224
	ds_read_b128 v[212:215], v147 offset:53248
	ds_read_b128 v[216:219], v147 offset:54272
	ds_read_b128 v[220:223], v147 offset:55296
	ds_read_b128 v[236:239], v147 offset:56320
	global_load_lds_dwordx4 v[192:193], off
	v_lshl_add_u64 v[192:193], v[198:199], 0, s[26:27]
	s_add_i32 m0, s50, 0x2000
	s_add_i32 s50, s65, s53
	global_load_lds_dwordx4 v[192:193], off
	v_lshl_add_u64 v[192:193], v[200:201], 0, s[26:27]
	s_mov_b32 m0, s50
	s_nop 0
	global_load_lds_dwordx4 v[192:193], off
	v_lshl_add_u64 v[192:193], v[202:203], 0, s[26:27]
	s_add_i32 m0, s50, 0x2000
	s_nop 0
	global_load_lds_dwordx4 v[192:193], off
	v_lshl_add_u64 v[192:193], v[204:205], 0, s[26:27]
	s_mov_b32 m0, s59
	s_nop 0
	global_load_lds_dwordx4 v[192:193], off
	v_lshl_add_u64 v[192:193], v[224:225], 0, s[26:27]
	s_mov_b32 m0, s60
	s_nop 0
	global_load_lds_dwordx4 v[192:193], off
	s_waitcnt vmcnt(8)
	s_waitcnt lgkmcnt(0)
	s_barrier
	s_setprio 1
	s_waitcnt lgkmcnt(0)
	v_mfma_f32_16x16x32_bf16 v[62:65], v[148:151], v[180:183], v[62:65]
	v_mfma_f32_16x16x32_bf16 v[58:61], v[156:159], v[180:183], v[58:61]
	v_mfma_f32_16x16x32_bf16 v[46:49], v[148:151], v[188:191], v[46:49]
	v_mfma_f32_16x16x32_bf16 v[42:45], v[156:159], v[188:191], v[42:45]
	v_mfma_f32_16x16x32_bf16 v[30:33], v[148:151], v[212:215], v[30:33]
	v_mfma_f32_16x16x32_bf16 v[26:29], v[156:159], v[212:215], v[26:29]
	v_mfma_f32_16x16x32_bf16 v[14:17], v[148:151], v[220:223], v[14:17]
	v_mfma_f32_16x16x32_bf16 v[10:13], v[156:159], v[220:223], v[10:13]
	v_mfma_f32_16x16x32_bf16 v[62:65], v[152:155], v[184:187], v[62:65]
	v_mfma_f32_16x16x32_bf16 v[58:61], v[160:163], v[184:187], v[58:61]
	v_mfma_f32_16x16x32_bf16 v[46:49], v[152:155], v[208:211], v[46:49]
	v_mfma_f32_16x16x32_bf16 v[42:45], v[160:163], v[208:211], v[42:45]
	v_mfma_f32_16x16x32_bf16 v[30:33], v[152:155], v[216:219], v[30:33]
	v_mfma_f32_16x16x32_bf16 v[26:29], v[160:163], v[216:219], v[26:29]
	v_mfma_f32_16x16x32_bf16 v[14:17], v[152:155], v[236:239], v[14:17]
	v_mfma_f32_16x16x32_bf16 v[10:13], v[160:163], v[236:239], v[10:13]
	v_mfma_f32_16x16x32_bf16 v[54:57], v[164:167], v[180:183], v[54:57]
	v_mfma_f32_16x16x32_bf16 v[50:53], v[172:175], v[180:183], v[50:53]
	v_mfma_f32_16x16x32_bf16 v[38:41], v[164:167], v[188:191], v[38:41]
	v_mfma_f32_16x16x32_bf16 v[34:37], v[172:175], v[188:191], v[34:37]
	v_mfma_f32_16x16x32_bf16 v[22:25], v[164:167], v[212:215], v[22:25]
	v_mfma_f32_16x16x32_bf16 v[18:21], v[172:175], v[212:215], v[18:21]
	v_mfma_f32_16x16x32_bf16 v[6:9], v[164:167], v[220:223], v[6:9]
	v_mfma_f32_16x16x32_bf16 v[2:5], v[172:175], v[220:223], v[2:5]
	v_mfma_f32_16x16x32_bf16 v[54:57], v[168:171], v[184:187], v[54:57]
	v_mfma_f32_16x16x32_bf16 v[50:53], v[176:179], v[184:187], v[50:53]
	v_mfma_f32_16x16x32_bf16 v[38:41], v[168:171], v[208:211], v[38:41]
	v_mfma_f32_16x16x32_bf16 v[34:37], v[176:179], v[208:211], v[34:37]
	v_mfma_f32_16x16x32_bf16 v[22:25], v[168:171], v[216:219], v[22:25]
	v_mfma_f32_16x16x32_bf16 v[18:21], v[176:179], v[216:219], v[18:21]
	v_mfma_f32_16x16x32_bf16 v[6:9], v[168:171], v[236:239], v[6:9]
	v_mfma_f32_16x16x32_bf16 v[2:5], v[176:179], v[236:239], v[2:5]
	s_setprio 0
	s_barrier
	s_add_u32 s48, s48, 0x100
	s_addc_u32 s49, s49, 0
	s_add_u32 s85, s85, 0x100
	s_addc_u32 s86, s86, 0
	s_cmp_ge_i32 s87, s58
	s_mov_b32 s50, s87
	s_cbranch_scc0 .LBB0_36

; #define PG8_STAGE(bufoff, gbase, voff) do { _Pragma("unroll") for (int _i = 0; _i < 2; ++_i) \
;         __builtin_amdgcn_global_load_lds((const unsigned*)((const char*)(gbase) + (voff)[_i]), (PG8_LAS unsigned*)(lds + (bufoff) + ldsw + _i * 8192), 16, 0, 0); } while (0)
; #define PG8_LDA(dst, b, h) do { _Pragma("unroll") for (int m = 0; m < 4; ++m) _Pragma("unroll") for (int k = 0; k < 2; ++k) dst[m][k] = *(const PG8_LAS bf16x8*)(lds + PG8_SA(b, h) + aoff + m * 2048 + k * 1024); } while (0)
; #define PG8_LDB(dst, b, h) do { _Pragma("unroll") for (int n = 0; n < 2; ++n) _Pragma("unroll") for (int k = 0; k < 2; ++k) dst[n][k] = *(const PG8_LAS bf16x8*)(lds + PG8_SB(b, h) + boff + n * 2048 + k * 1024); } while (0)
; #define PG8_MMA(ai, bj, At, Bt) do { __builtin_amdgcn_s_setprio(1); _Pragma("unroll") for (int m = 0; m < 4; ++m) _Pragma("unroll") for (int n = 0; n < 2; ++n) _Pragma("unroll") for (int k = 0; k < 2; ++k) \
;         acc[ai][bj][m][n] = __builtin_amdgcn_mfma_f32_16x16x32_bf16(Bt[n][k], At[m][k], acc[ai][bj][m][n], 0, 0, 0); __builtin_amdgcn_s_setprio(0); } while (0)
; #define PG8_WAIT_V(n) asm volatile("s_waitcnt vmcnt(" #n ")" ::: "memory")
; #define PG8_WAIT_L(n) asm volatile("s_waitcnt lgkmcnt(" #n ")" ::: "memory")
; #define PG8_BAR __builtin_amdgcn_s_barrier()
; #define PG8_SCHED __builtin_amdgcn_sched_barrier(0)
; template <class Epi, class Sched, bool ALIGN_EPI = false, bool SP2 = false>
; __device__ __forceinline__ void gemm_phase(PG8_LAS unsigned char* lds, const Gemm g, const Sched& S, const Epi& E) {
;     ...
;             const char* a2 = last ? nA : cA + (size_t)(t + 2) * kstep; const char* b2 = last ? nB : cB + (size_t)(t + 2) * kstep;
;             const char* a3 = a2 + kstep; const char* b3 = b2 + kstep;
;             if (last && has_next) S.a_ready(nxt);
;             if constexpr (SP2) {
;             PG8_LDB(B0, 0, 0); PG8_LDB(B1, 0, 1); PG8_SCHED; PG8_LDA(At, 0, 0); PG8_STAGE(PG8_SA(1, 1), a1 + hstep, voffA);
;             PG8_WAIT_V(8); PG8_WAIT_L(0); PG8_BAR; PG8_MMA(0, 0, At, B0); PG8_MMA(0, 1, At, B1); PG8_BAR; PG8_SCHED;
;             PG8_LDA(At, 0, 1); PG8_STAGE(PG8_SB(0, 0), b2, voffB); PG8_STAGE(PG8_SB(0, 1), b2 + hstep, voffB); PG8_STAGE(PG8_SA(0, 0), a2, voffA);
.LBB0_65:
	s_add_i32 s95, s58, 2
	s_add_u32 s64, s14, 0x80
	s_addc_u32 s59, s15, 0
	s_add_i32 s66, 0, 0x10000
	s_cmp_eq_u32 s89, s58
	s_cselect_b32 s59, s45, s59
	s_cselect_b32 s58, s44, s64
	s_cselect_b32 s65, s57, s94
	s_cselect_b32 s64, s56, s93
	s_add_i32 s67, 0, 0x14000
	v_add_u32_e32 v146, s66, v179
	v_add_u32_e32 v172, s67, v179
	ds_read_b128 v[134:137], v146
	ds_read_b128 v[138:141], v146 offset:1024
	ds_read_b128 v[142:145], v146 offset:2048
	ds_read_b128 v[146:149], v146 offset:3072
	ds_read_b128 v[160:163], v172
	ds_read_b128 v[164:167], v172 offset:1024
	ds_read_b128 v[168:171], v172 offset:2048
	ds_read_b128 v[172:175], v172 offset:3072
	v_lshl_add_u64 v[176:177], s[14:15], 0, v[156:157]
	s_add_i32 m0, s82, 0xc000
	ds_read_b128 v[182:185], v181
	ds_read_b128 v[186:189], v181 offset:1024
	ds_read_b128 v[190:193], v181 offset:2048
	ds_read_b128 v[208:211], v181 offset:3072
	ds_read_b128 v[212:215], v181 offset:4096
	ds_read_b128 v[216:219], v181 offset:5120
	ds_read_b128 v[220:223], v181 offset:6144
	ds_read_b128 v[236:239], v181 offset:7168
	global_load_lds_dwordx4 v[176:177], off
	v_lshl_add_u64 v[176:177], s[14:15], 0, v[158:159]
	s_add_i32 m0, s82, 0xe000
	s_nop 0
	global_load_lds_dwordx4 v[176:177], off
	s_waitcnt vmcnt(8)
	s_waitcnt lgkmcnt(0)
	s_barrier
	s_setprio 1
	s_waitcnt lgkmcnt(0)
	v_mfma_f32_16x16x32_bf16 v[126:129], v[134:137], v[182:185], v[126:129]
	v_mfma_f32_16x16x32_bf16 v[122:125], v[142:145], v[182:185], v[122:125]
	v_mfma_f32_16x16x32_bf16 v[110:113], v[134:137], v[190:193], v[110:113]
	v_mfma_f32_16x16x32_bf16 v[106:109], v[142:145], v[190:193], v[106:109]
	v_mfma_f32_16x16x32_bf16 v[94:97], v[134:137], v[212:215], v[94:97]
	v_mfma_f32_16x16x32_bf16 v[90:93], v[142:145], v[212:215], v[90:93]
	v_mfma_f32_16x16x32_bf16 v[78:81], v[134:137], v[220:223], v[78:81]
	v_mfma_f32_16x16x32_bf16 v[74:77], v[142:145], v[220:223], v[74:77]
	v_mfma_f32_16x16x32_bf16 v[126:129], v[138:141], v[186:189], v[126:129]
	v_mfma_f32_16x16x32_bf16 v[122:125], v[146:149], v[186:189], v[122:125]
	v_mfma_f32_16x16x32_bf16 v[110:113], v[138:141], v[208:211], v[110:113]
	v_mfma_f32_16x16x32_bf16 v[106:109], v[146:149], v[208:211], v[106:109]
	v_mfma_f32_16x16x32_bf16 v[94:97], v[138:141], v[216:219], v[94:97]
	v_mfma_f32_16x16x32_bf16 v[90:93], v[146:149], v[216:219], v[90:93]
	v_mfma_f32_16x16x32_bf16 v[78:81], v[138:141], v[236:239], v[78:81]
	v_mfma_f32_16x16x32_bf16 v[74:77], v[146:149], v[236:239], v[74:77]
	v_mfma_f32_16x16x32_bf16 v[118:121], v[160:163], v[182:185], v[118:121]
	v_mfma_f32_16x16x32_bf16 v[114:117], v[168:171], v[182:185], v[114:117]
	v_mfma_f32_16x16x32_bf16 v[102:105], v[160:163], v[190:193], v[102:105]
	v_mfma_f32_16x16x32_bf16 v[98:101], v[168:171], v[190:193], v[98:101]
	v_mfma_f32_16x16x32_bf16 v[86:89], v[160:163], v[212:215], v[86:89]
	v_mfma_f32_16x16x32_bf16 v[82:85], v[168:171], v[212:215], v[82:85]
	v_mfma_f32_16x16x32_bf16 v[70:73], v[160:163], v[220:223], v[70:73]
	v_mfma_f32_16x16x32_bf16 v[66:69], v[168:171], v[220:223], v[66:69]
	v_mfma_f32_16x16x32_bf16 v[118:121], v[164:167], v[186:189], v[118:121]
	v_mfma_f32_16x16x32_bf16 v[114:117], v[172:175], v[186:189], v[114:117]
	v_mfma_f32_16x16x32_bf16 v[102:105], v[164:167], v[208:211], v[102:105]
	v_mfma_f32_16x16x32_bf16 v[98:101], v[172:175], v[208:211], v[98:101]
	v_mfma_f32_16x16x32_bf16 v[86:89], v[164:167], v[216:219], v[86:89]
	v_mfma_f32_16x16x32_bf16 v[82:85], v[172:175], v[216:219], v[82:85]
	v_mfma_f32_16x16x32_bf16 v[70:73], v[164:167], v[236:239], v[70:73]
	v_mfma_f32_16x16x32_bf16 v[66:69], v[172:175], v[236:239], v[66:69]
	s_setprio 0
	s_barrier
	s_add_i32 s66, s66, s81
	v_lshl_add_u64 v[176:177], s[64:65], 0, v[0:1]
	s_mov_b32 m0, s66
	ds_read_b128 v[182:185], v181 offset:16384
	ds_read_b128 v[186:189], v181 offset:17408
	ds_read_b128 v[190:193], v181 offset:18432
	ds_read_b128 v[208:211], v181 offset:19456
	ds_read_b128 v[212:215], v181 offset:20480
	ds_read_b128 v[216:219], v181 offset:21504
	ds_read_b128 v[220:223], v181 offset:22528
	ds_read_b128 v[236:239], v181 offset:23552
	global_load_lds_dwordx4 v[176:177], off
	s_add_i32 m0, s66, 0x2000
	v_lshl_add_u64 v[198:199], s[64:65], 0, v[150:151]
	s_add_u32 s64, s64, s4
	s_addc_u32 s65, s65, s5
	s_add_i32 s66, s67, s81
	global_load_lds_dwordx4 v[198:199], off
	v_lshl_add_u64 v[200:201], s[64:65], 0, v[0:1]
	s_mov_b32 m0, s66
	v_lshl_add_u64 v[202:203], s[64:65], 0, v[150:151]
	global_load_lds_dwordx4 v[200:201], off
	s_add_i32 m0, s66, 0x2000
	v_lshl_add_u64 v[204:205], s[58:59], 0, v[154:155]
	global_load_lds_dwordx4 v[202:203], off
	s_mov_b32 m0, s82
	v_lshl_add_u64 v[224:225], s[58:59], 0, v[152:153]
	global_load_lds_dwordx4 v[204:205], off
	s_mov_b32 m0, s83
	s_nop 0
	global_load_lds_dwordx4 v[224:225], off
	s_waitcnt vmcnt(8)
	s_waitcnt lgkmcnt(0)
	s_barrier
; #define PG8_STAGE(bufoff, gbase, voff) do { _Pragma("unroll") for (int _i = 0; _i < 2; ++_i) \
;         __builtin_amdgcn_global_load_lds((const unsigned*)((const char*)(gbase) + (voff)[_i]), (PG8_LAS unsigned*)(lds + (bufoff) + ldsw + _i * 8192), 16, 0, 0); } while (0)
; #define PG8_LDA(dst, b, h) do { _Pragma("unroll") for (int m = 0; m < 4; ++m) _Pragma("unroll") for (int k = 0; k < 2; ++k) dst[m][k] = *(const PG8_LAS bf16x8*)(lds + PG8_SA(b, h) + aoff + m * 2048 + k * 1024); } while (0)
; #define PG8_LDB(dst, b, h) do { _Pragma("unroll") for (int n = 0; n < 2; ++n) _Pragma("unroll") for (int k = 0; k < 2; ++k) dst[n][k] = *(const PG8_LAS bf16x8*)(lds + PG8_SB(b, h) + boff + n * 2048 + k * 1024); } while (0)
; #define PG8_MMA(ai, bj, At, Bt) do { __builtin_amdgcn_s_setprio(1); _Pragma("unroll") for (int m = 0; m < 4; ++m) _Pragma("unroll") for (int n = 0; n < 2; ++n) _Pragma("unroll") for (int k = 0; k < 2; ++k) \
;         acc[ai][bj][m][n] = __builtin_amdgcn_mfma_f32_16x16x32_bf16(Bt[n][k], At[m][k], acc[ai][bj][m][n], 0, 0, 0); __builtin_amdgcn_s_setprio(0); } while (0)
; #define PG8_WAIT_V(n) asm volatile("s_waitcnt vmcnt(" #n ")" ::: "memory")
; #define PG8_WAIT_L(n) asm volatile("s_waitcnt lgkmcnt(" #n ")" ::: "memory")
; #define PG8_BAR __builtin_amdgcn_s_barrier()
; #define PG8_SCHED __builtin_amdgcn_sched_barrier(0)
; template <class Epi, class Sched, bool ALIGN_EPI = false, bool SP2 = false>
; __device__ __forceinline__ void gemm_phase(PG8_LAS unsigned char* lds, const Gemm g, const Sched& S, const Epi& E) {
;     ...
;             PG8_WAIT_V(8); PG8_WAIT_L(0); PG8_BAR; PG8_MMA(1, 0, At, B0); PG8_MMA(1, 1, At, B1); PG8_BAR; PG8_SCHED;
;             PG8_LDB(B0, 1, 0); PG8_LDB(B1, 1, 1); PG8_SCHED; PG8_LDA(At, 1, 0); PG8_STAGE(PG8_SA(0, 1), a2 + hstep, voffA);
;             PG8_WAIT_V(8); PG8_WAIT_L(0); PG8_BAR; PG8_MMA(0, 0, At, B0); PG8_MMA(0, 1, At, B1); PG8_BAR; PG8_SCHED;
	s_setprio 1
	s_waitcnt lgkmcnt(0)
	v_mfma_f32_16x16x32_bf16 v[62:65], v[134:137], v[182:185], v[62:65]
	v_mfma_f32_16x16x32_bf16 v[58:61], v[142:145], v[182:185], v[58:61]
	v_mfma_f32_16x16x32_bf16 v[46:49], v[134:137], v[190:193], v[46:49]
	v_mfma_f32_16x16x32_bf16 v[42:45], v[142:145], v[190:193], v[42:45]
	v_mfma_f32_16x16x32_bf16 v[30:33], v[134:137], v[212:215], v[30:33]
	v_mfma_f32_16x16x32_bf16 v[26:29], v[142:145], v[212:215], v[26:29]
	v_mfma_f32_16x16x32_bf16 v[14:17], v[134:137], v[220:223], v[14:17]
	v_mfma_f32_16x16x32_bf16 v[10:13], v[142:145], v[220:223], v[10:13]
	v_mfma_f32_16x16x32_bf16 v[62:65], v[138:141], v[186:189], v[62:65]
	v_mfma_f32_16x16x32_bf16 v[58:61], v[146:149], v[186:189], v[58:61]
	v_mfma_f32_16x16x32_bf16 v[46:49], v[138:141], v[208:211], v[46:49]
	v_mfma_f32_16x16x32_bf16 v[42:45], v[146:149], v[208:211], v[42:45]
	v_mfma_f32_16x16x32_bf16 v[30:33], v[138:141], v[216:219], v[30:33]
	v_mfma_f32_16x16x32_bf16 v[26:29], v[146:149], v[216:219], v[26:29]
	v_mfma_f32_16x16x32_bf16 v[14:17], v[138:141], v[236:239], v[14:17]
	v_mfma_f32_16x16x32_bf16 v[10:13], v[146:149], v[236:239], v[10:13]
	v_mfma_f32_16x16x32_bf16 v[54:57], v[160:163], v[182:185], v[54:57]
	v_mfma_f32_16x16x32_bf16 v[50:53], v[168:171], v[182:185], v[50:53]
	v_mfma_f32_16x16x32_bf16 v[38:41], v[160:163], v[190:193], v[38:41]
	v_mfma_f32_16x16x32_bf16 v[34:37], v[168:171], v[190:193], v[34:37]
	v_mfma_f32_16x16x32_bf16 v[22:25], v[160:163], v[212:215], v[22:25]
	v_mfma_f32_16x16x32_bf16 v[18:21], v[168:171], v[212:215], v[18:21]
	v_mfma_f32_16x16x32_bf16 v[6:9], v[160:163], v[220:223], v[6:9]
	v_mfma_f32_16x16x32_bf16 v[2:5], v[168:171], v[220:223], v[2:5]
	v_mfma_f32_16x16x32_bf16 v[54:57], v[164:167], v[186:189], v[54:57]
	v_mfma_f32_16x16x32_bf16 v[50:53], v[172:175], v[186:189], v[50:53]
	v_mfma_f32_16x16x32_bf16 v[38:41], v[164:167], v[208:211], v[38:41]
	v_mfma_f32_16x16x32_bf16 v[34:37], v[172:175], v[208:211], v[34:37]
	v_mfma_f32_16x16x32_bf16 v[22:25], v[164:167], v[216:219], v[22:25]
	v_mfma_f32_16x16x32_bf16 v[18:21], v[172:175], v[216:219], v[18:21]
	v_mfma_f32_16x16x32_bf16 v[6:9], v[164:167], v[236:239], v[6:9]
	v_mfma_f32_16x16x32_bf16 v[2:5], v[172:175], v[236:239], v[2:5]
	s_setprio 0
	s_barrier
	s_add_i32 s64, 0, 0x18000
	s_add_i32 s65, 0, 0x1c000
	v_add_u32_e32 v146, s64, v179
	v_add_u32_e32 v172, s65, v179
	ds_read_b128 v[134:137], v146
	ds_read_b128 v[138:141], v146 offset:1024
	ds_read_b128 v[142:145], v146 offset:2048
	ds_read_b128 v[146:149], v146 offset:3072
	ds_read_b128 v[160:163], v172
	ds_read_b128 v[164:167], v172 offset:1024
	ds_read_b128 v[168:171], v172 offset:2048
	ds_read_b128 v[172:175], v172 offset:3072
	s_add_u32 s58, s58, s4
	s_addc_u32 s59, s59, s5
	s_mov_b32 m0, s84
	v_lshl_add_u64 v[228:229], s[58:59], 0, v[154:155]
	ds_read_b128 v[182:185], v181 offset:32768
	ds_read_b128 v[186:189], v181 offset:33792
	ds_read_b128 v[190:193], v181 offset:34816
	ds_read_b128 v[208:211], v181 offset:35840
	ds_read_b128 v[212:215], v181 offset:36864
	ds_read_b128 v[216:219], v181 offset:37888
	ds_read_b128 v[220:223], v181 offset:38912
	ds_read_b128 v[236:239], v181 offset:39936
	global_load_lds_dwordx4 v[228:229], off
	v_lshl_add_u64 v[228:229], s[58:59], 0, v[152:153]
	s_mov_b32 m0, s85
	s_nop 0
	global_load_lds_dwordx4 v[228:229], off
	s_waitcnt vmcnt(8)
	s_waitcnt lgkmcnt(0)
	s_barrier
	s_setprio 1
	s_waitcnt lgkmcnt(0)
	v_mfma_f32_16x16x32_bf16 v[126:129], v[134:137], v[182:185], v[126:129]
	v_mfma_f32_16x16x32_bf16 v[122:125], v[142:145], v[182:185], v[122:125]
	v_mfma_f32_16x16x32_bf16 v[110:113], v[134:137], v[190:193], v[110:113]
	v_mfma_f32_16x16x32_bf16 v[106:109], v[142:145], v[190:193], v[106:109]
	v_mfma_f32_16x16x32_bf16 v[94:97], v[134:137], v[212:215], v[94:97]
	v_mfma_f32_16x16x32_bf16 v[90:93], v[142:145], v[212:215], v[90:93]
	v_mfma_f32_16x16x32_bf16 v[78:81], v[134:137], v[220:223], v[78:81]
	v_mfma_f32_16x16x32_bf16 v[74:77], v[142:145], v[220:223], v[74:77]
	v_mfma_f32_16x16x32_bf16 v[126:129], v[138:141], v[186:189], v[126:129]
	v_mfma_f32_16x16x32_bf16 v[122:125], v[146:149], v[186:189], v[122:125]
	v_mfma_f32_16x16x32_bf16 v[110:113], v[138:141], v[208:211], v[110:113]
	v_mfma_f32_16x16x32_bf16 v[106:109], v[146:149], v[208:211], v[106:109]
	v_mfma_f32_16x16x32_bf16 v[94:97], v[138:141], v[216:219], v[94:97]
	v_mfma_f32_16x16x32_bf16 v[90:93], v[146:149], v[216:219], v[90:93]
	v_mfma_f32_16x16x32_bf16 v[78:81], v[138:141], v[236:239], v[78:81]
	v_mfma_f32_16x16x32_bf16 v[74:77], v[146:149], v[236:239], v[74:77]
	v_mfma_f32_16x16x32_bf16 v[118:121], v[160:163], v[182:185], v[118:121]
	v_mfma_f32_16x16x32_bf16 v[114:117], v[168:171], v[182:185], v[114:117]
	v_mfma_f32_16x16x32_bf16 v[102:105], v[160:163], v[190:193], v[102:105]
	v_mfma_f32_16x16x32_bf16 v[98:101], v[168:171], v[190:193], v[98:101]
	v_mfma_f32_16x16x32_bf16 v[86:89], v[160:163], v[212:215], v[86:89]
	v_mfma_f32_16x16x32_bf16 v[82:85], v[168:171], v[212:215], v[82:85]
	v_mfma_f32_16x16x32_bf16 v[70:73], v[160:163], v[220:223], v[70:73]
	v_mfma_f32_16x16x32_bf16 v[66:69], v[168:171], v[220:223], v[66:69]
	v_mfma_f32_16x16x32_bf16 v[118:121], v[164:167], v[186:189], v[118:121]
	v_mfma_f32_16x16x32_bf16 v[114:117], v[172:175], v[186:189], v[114:117]
	v_mfma_f32_16x16x32_bf16 v[102:105], v[164:167], v[208:211], v[102:105]
	v_mfma_f32_16x16x32_bf16 v[98:101], v[172:175], v[208:211], v[98:101]
	v_mfma_f32_16x16x32_bf16 v[86:89], v[164:167], v[216:219], v[86:89]
	v_mfma_f32_16x16x32_bf16 v[82:85], v[172:175], v[216:219], v[82:85]
	v_mfma_f32_16x16x32_bf16 v[70:73], v[164:167], v[236:239], v[70:73]
	v_mfma_f32_16x16x32_bf16 v[66:69], v[172:175], v[236:239], v[66:69]
	s_setprio 0
	s_barrier
; #define PG8_STAGE(bufoff, gbase, voff) do { _Pragma("unroll") for (int _i = 0; _i < 2; ++_i) \
;         __builtin_amdgcn_global_load_lds((const unsigned*)((const char*)(gbase) + (voff)[_i]), (PG8_LAS unsigned*)(lds + (bufoff) + ldsw + _i * 8192), 16, 0, 0); } while (0)
; #define PG8_LDA(dst, b, h) do { _Pragma("unroll") for (int m = 0; m < 4; ++m) _Pragma("unroll") for (int k = 0; k < 2; ++k) dst[m][k] = *(const PG8_LAS bf16x8*)(lds + PG8_SA(b, h) + aoff + m * 2048 + k * 1024); } while (0)
; #define PG8_MMA(ai, bj, At, Bt) do { __builtin_amdgcn_s_setprio(1); _Pragma("unroll") for (int m = 0; m < 4; ++m) _Pragma("unroll") for (int n = 0; n < 2; ++n) _Pragma("unroll") for (int k = 0; k < 2; ++k) \
;         acc[ai][bj][m][n] = __builtin_amdgcn_mfma_f32_16x16x32_bf16(Bt[n][k], At[m][k], acc[ai][bj][m][n], 0, 0, 0); __builtin_amdgcn_s_setprio(0); } while (0)
; #define PG8_WAIT_V(n) asm volatile("s_waitcnt vmcnt(" #n ")" ::: "memory")
; #define PG8_WAIT_L(n) asm volatile("s_waitcnt lgkmcnt(" #n ")" ::: "memory")
; #define PG8_BAR __builtin_amdgcn_s_barrier()
; #define PG8_SCHED __builtin_amdgcn_sched_barrier(0)
; template <class Epi, class Sched, bool ALIGN_EPI = false, bool SP2 = false>
; __device__ __forceinline__ void gemm_phase(PG8_LAS unsigned char* lds, const Gemm g, const Sched& S, const Epi& E) {
;     ...
;             PG8_LDA(At, 1, 1); PG8_STAGE(PG8_SB(1, 0), b3, voffB); PG8_STAGE(PG8_SB(1, 1), b3 + hstep, voffB); PG8_STAGE(PG8_SA(1, 0), a3, voffA);
;             PG8_WAIT_V(8); PG8_WAIT_L(0); PG8_BAR; PG8_MMA(1, 0, At, B0); PG8_MMA(1, 1, At, B1); PG8_BAR; PG8_SCHED;
	s_add_i32 s58, s64, s81
	v_lshl_add_u64 v[176:177], v[176:177], 0, s[26:27]
	s_mov_b32 m0, s58
	ds_read_b128 v[182:185], v181 offset:49152
	ds_read_b128 v[186:189], v181 offset:50176
	ds_read_b128 v[190:193], v181 offset:51200
	ds_read_b128 v[208:211], v181 offset:52224
	ds_read_b128 v[212:215], v181 offset:53248
	ds_read_b128 v[216:219], v181 offset:54272
	ds_read_b128 v[220:223], v181 offset:55296
	ds_read_b128 v[236:239], v181 offset:56320
	global_load_lds_dwordx4 v[176:177], off
	v_lshl_add_u64 v[176:177], v[198:199], 0, s[26:27]
	s_add_i32 m0, s58, 0x2000
	s_add_i32 s58, s65, s81
	global_load_lds_dwordx4 v[176:177], off
	v_lshl_add_u64 v[176:177], v[200:201], 0, s[26:27]
	s_mov_b32 m0, s58
	s_nop 0
	global_load_lds_dwordx4 v[176:177], off
	v_lshl_add_u64 v[176:177], v[202:203], 0, s[26:27]
	s_add_i32 m0, s58, 0x2000
	s_nop 0
	global_load_lds_dwordx4 v[176:177], off
	v_lshl_add_u64 v[176:177], v[204:205], 0, s[26:27]
	s_mov_b32 m0, s87
	s_nop 0
	global_load_lds_dwordx4 v[176:177], off
	v_lshl_add_u64 v[176:177], v[224:225], 0, s[26:27]
	s_mov_b32 m0, s88
	s_nop 0
	global_load_lds_dwordx4 v[176:177], off
	s_waitcnt vmcnt(8)
	s_waitcnt lgkmcnt(0)
	s_barrier
	s_setprio 1
	s_waitcnt lgkmcnt(0)
	v_mfma_f32_16x16x32_bf16 v[62:65], v[134:137], v[182:185], v[62:65]
	v_mfma_f32_16x16x32_bf16 v[58:61], v[142:145], v[182:185], v[58:61]
	v_mfma_f32_16x16x32_bf16 v[46:49], v[134:137], v[190:193], v[46:49]
	v_mfma_f32_16x16x32_bf16 v[42:45], v[142:145], v[190:193], v[42:45]
	v_mfma_f32_16x16x32_bf16 v[30:33], v[134:137], v[212:215], v[30:33]
	v_mfma_f32_16x16x32_bf16 v[26:29], v[142:145], v[212:215], v[26:29]
	v_mfma_f32_16x16x32_bf16 v[14:17], v[134:137], v[220:223], v[14:17]
	v_mfma_f32_16x16x32_bf16 v[10:13], v[142:145], v[220:223], v[10:13]
	v_mfma_f32_16x16x32_bf16 v[62:65], v[138:141], v[186:189], v[62:65]
	v_mfma_f32_16x16x32_bf16 v[58:61], v[146:149], v[186:189], v[58:61]
	v_mfma_f32_16x16x32_bf16 v[46:49], v[138:141], v[208:211], v[46:49]
	v_mfma_f32_16x16x32_bf16 v[42:45], v[146:149], v[208:211], v[42:45]
	v_mfma_f32_16x16x32_bf16 v[30:33], v[138:141], v[216:219], v[30:33]
	v_mfma_f32_16x16x32_bf16 v[26:29], v[146:149], v[216:219], v[26:29]
	v_mfma_f32_16x16x32_bf16 v[14:17], v[138:141], v[236:239], v[14:17]
	v_mfma_f32_16x16x32_bf16 v[10:13], v[146:149], v[236:239], v[10:13]
	v_mfma_f32_16x16x32_bf16 v[54:57], v[160:163], v[182:185], v[54:57]
	v_mfma_f32_16x16x32_bf16 v[50:53], v[168:171], v[182:185], v[50:53]
	v_mfma_f32_16x16x32_bf16 v[38:41], v[160:163], v[190:193], v[38:41]
	v_mfma_f32_16x16x32_bf16 v[34:37], v[168:171], v[190:193], v[34:37]
	v_mfma_f32_16x16x32_bf16 v[22:25], v[160:163], v[212:215], v[22:25]
	v_mfma_f32_16x16x32_bf16 v[18:21], v[168:171], v[212:215], v[18:21]
	v_mfma_f32_16x16x32_bf16 v[6:9], v[160:163], v[220:223], v[6:9]
	v_mfma_f32_16x16x32_bf16 v[2:5], v[168:171], v[220:223], v[2:5]
	v_mfma_f32_16x16x32_bf16 v[54:57], v[164:167], v[186:189], v[54:57]
	v_mfma_f32_16x16x32_bf16 v[50:53], v[172:175], v[186:189], v[50:53]
	v_mfma_f32_16x16x32_bf16 v[38:41], v[164:167], v[208:211], v[38:41]
	v_mfma_f32_16x16x32_bf16 v[34:37], v[172:175], v[208:211], v[34:37]
	v_mfma_f32_16x16x32_bf16 v[22:25], v[164:167], v[216:219], v[22:25]
	v_mfma_f32_16x16x32_bf16 v[18:21], v[172:175], v[216:219], v[18:21]
	v_mfma_f32_16x16x32_bf16 v[6:9], v[164:167], v[236:239], v[6:9]
	v_mfma_f32_16x16x32_bf16 v[2:5], v[172:175], v[236:239], v[2:5]
	s_setprio 0
	s_barrier
	s_add_u32 s14, s14, 0x100
	s_addc_u32 s15, s15, 0
	s_add_u32 s93, s93, 0x100
	s_addc_u32 s94, s94, 0
	s_cmp_ge_i32 s95, s86
	s_mov_b32 s58, s95
	s_cbranch_scc0 .LBB0_65

; #define PG8_STAGE(bufoff, gbase, voff) do { _Pragma("unroll") for (int _i = 0; _i < 2; ++_i) \
;         __builtin_amdgcn_global_load_lds((const unsigned*)((const char*)(gbase) + (voff)[_i]), (PG8_LAS unsigned*)(lds + (bufoff) + ldsw + _i * 8192), 16, 0, 0); } while (0)
; #define PG8_LDA(dst, b, h) do { _Pragma("unroll") for (int m = 0; m < 4; ++m) _Pragma("unroll") for (int k = 0; k < 2; ++k) dst[m][k] = *(const PG8_LAS bf16x8*)(lds + PG8_SA(b, h) + aoff + m * 2048 + k * 1024); } while (0)
; #define PG8_LDB(dst, b, h) do { _Pragma("unroll") for (int n = 0; n < 2; ++n) _Pragma("unroll") for (int k = 0; k < 2; ++k) dst[n][k] = *(const PG8_LAS bf16x8*)(lds + PG8_SB(b, h) + boff + n * 2048 + k * 1024); } while (0)
; #define PG8_MMA(ai, bj, At, Bt) do { __builtin_amdgcn_s_setprio(1); _Pragma("unroll") for (int m = 0; m < 4; ++m) _Pragma("unroll") for (int n = 0; n < 2; ++n) _Pragma("unroll") for (int k = 0; k < 2; ++k) \
;         acc[ai][bj][m][n] = __builtin_amdgcn_mfma_f32_16x16x32_bf16(Bt[n][k], At[m][k], acc[ai][bj][m][n], 0, 0, 0); __builtin_amdgcn_s_setprio(0); } while (0)
; #define PG8_WAIT_V(n) asm volatile("s_waitcnt vmcnt(" #n ")" ::: "memory")
; #define PG8_WAIT_L(n) asm volatile("s_waitcnt lgkmcnt(" #n ")" ::: "memory")
; #define PG8_BAR __builtin_amdgcn_s_barrier()
; #define PG8_SCHED __builtin_amdgcn_sched_barrier(0)
; template <class Epi, class Sched, bool ALIGN_EPI = false, bool SP2 = false>
; __device__ __forceinline__ void gemm_phase(PG8_LAS unsigned char* lds, const Gemm g, const Sched& S, const Epi& E) {
;     ...
;             const char* a2 = last ? nA : cA + (size_t)(t + 2) * kstep; const char* b2 = last ? nB : cB + (size_t)(t + 2) * kstep;
;             const char* a3 = a2 + kstep; const char* b3 = b2 + kstep;
;             if (last && has_next) S.a_ready(nxt);
;             if constexpr (SP2) {
;             PG8_LDB(B0, 0, 0); PG8_LDB(B1, 0, 1); PG8_SCHED; PG8_LDA(At, 0, 0); PG8_STAGE(PG8_SA(1, 1), a1 + hstep, voffA);
;             PG8_WAIT_V(8); PG8_WAIT_L(0); PG8_BAR; PG8_MMA(0, 0, At, B0); PG8_MMA(0, 1, At, B1); PG8_BAR; PG8_SCHED;
;             PG8_LDA(At, 0, 1); PG8_STAGE(PG8_SB(0, 0), b2, voffB); PG8_STAGE(PG8_SB(0, 1), b2 + hstep, voffB); PG8_STAGE(PG8_SA(0, 0), a2, voffA);
.LBB0_104:
	s_add_i32 s91, s54, 2
	s_add_u32 s64, s14, 0x80
	s_addc_u32 s55, s15, 0
	s_add_i32 s66, 0, 0x10000
	s_cmp_eq_u32 s83, s54
	s_cselect_b32 s55, s43, s55
	s_cselect_b32 s54, s42, s64
	s_cselect_b32 s65, s53, s90
	s_cselect_b32 s64, s52, s89
	s_add_i32 s67, 0, 0x14000
	v_add_u32_e32 v86, s66, v226
	v_add_u32_e32 v110, s67, v226
	ds_read_b128 v[74:77], v86
	ds_read_b128 v[78:81], v86 offset:1024
	ds_read_b128 v[82:85], v86 offset:2048
	ds_read_b128 v[86:89], v86 offset:3072
	ds_read_b128 v[98:101], v110
	ds_read_b128 v[102:105], v110 offset:1024
	ds_read_b128 v[106:109], v110 offset:2048
	ds_read_b128 v[110:113], v110 offset:3072
	v_lshl_add_u64 v[192:193], s[14:15], 0, v[172:173]
	s_add_i32 m0, s58, 0xc000
	ds_read_b128 v[176:179], v229
	ds_read_b128 v[180:183], v229 offset:1024
	ds_read_b128 v[184:187], v229 offset:2048
	ds_read_b128 v[188:191], v229 offset:3072
	ds_read_b128 v[208:211], v229 offset:4096
	ds_read_b128 v[212:215], v229 offset:5120
	ds_read_b128 v[216:219], v229 offset:6144
	ds_read_b128 v[220:223], v229 offset:7168
	global_load_lds_dwordx4 v[192:193], off
	v_lshl_add_u64 v[192:193], s[14:15], 0, v[174:175]
	s_add_i32 m0, s58, 0xe000
	s_nop 0
	global_load_lds_dwordx4 v[192:193], off
	s_waitcnt vmcnt(8)
	s_waitcnt lgkmcnt(0)
	s_barrier
	s_setprio 1
	s_waitcnt lgkmcnt(0)
	v_mfma_f32_16x16x32_bf16 v[162:165], v[74:77], v[176:179], v[162:165]
	v_mfma_f32_16x16x32_bf16 v[154:157], v[82:85], v[176:179], v[154:157]
	v_mfma_f32_16x16x32_bf16 v[146:149], v[74:77], v[184:187], v[146:149]
	v_mfma_f32_16x16x32_bf16 v[138:141], v[82:85], v[184:187], v[138:141]
	v_mfma_f32_16x16x32_bf16 v[126:129], v[74:77], v[208:211], v[126:129]
	v_mfma_f32_16x16x32_bf16 v[118:121], v[82:85], v[208:211], v[118:121]
	v_mfma_f32_16x16x32_bf16 v[94:97], v[74:77], v[216:219], v[94:97]
	v_mfma_f32_16x16x32_bf16 v[70:73], v[82:85], v[216:219], v[70:73]
	v_mfma_f32_16x16x32_bf16 v[162:165], v[78:81], v[180:183], v[162:165]
	v_mfma_f32_16x16x32_bf16 v[154:157], v[86:89], v[180:183], v[154:157]
	v_mfma_f32_16x16x32_bf16 v[146:149], v[78:81], v[188:191], v[146:149]
	v_mfma_f32_16x16x32_bf16 v[138:141], v[86:89], v[188:191], v[138:141]
	v_mfma_f32_16x16x32_bf16 v[126:129], v[78:81], v[212:215], v[126:129]
	v_mfma_f32_16x16x32_bf16 v[118:121], v[86:89], v[212:215], v[118:121]
	v_mfma_f32_16x16x32_bf16 v[94:97], v[78:81], v[220:223], v[94:97]
	v_mfma_f32_16x16x32_bf16 v[70:73], v[86:89], v[220:223], v[70:73]
	v_mfma_f32_16x16x32_bf16 v[158:161], v[98:101], v[176:179], v[158:161]
	v_mfma_f32_16x16x32_bf16 v[150:153], v[106:109], v[176:179], v[150:153]
	v_mfma_f32_16x16x32_bf16 v[142:145], v[98:101], v[184:187], v[142:145]
	v_mfma_f32_16x16x32_bf16 v[134:137], v[106:109], v[184:187], v[134:137]
	v_mfma_f32_16x16x32_bf16 v[122:125], v[98:101], v[208:211], v[122:125]
	v_mfma_f32_16x16x32_bf16 v[114:117], v[106:109], v[208:211], v[114:117]
	v_mfma_f32_16x16x32_bf16 v[90:93], v[98:101], v[216:219], v[90:93]
	v_mfma_f32_16x16x32_bf16 v[66:69], v[106:109], v[216:219], v[66:69]
	v_mfma_f32_16x16x32_bf16 v[158:161], v[102:105], v[180:183], v[158:161]
	v_mfma_f32_16x16x32_bf16 v[150:153], v[110:113], v[180:183], v[150:153]
	v_mfma_f32_16x16x32_bf16 v[142:145], v[102:105], v[188:191], v[142:145]
	v_mfma_f32_16x16x32_bf16 v[134:137], v[110:113], v[188:191], v[134:137]
	v_mfma_f32_16x16x32_bf16 v[122:125], v[102:105], v[212:215], v[122:125]
	v_mfma_f32_16x16x32_bf16 v[114:117], v[110:113], v[212:215], v[114:117]
	v_mfma_f32_16x16x32_bf16 v[90:93], v[102:105], v[220:223], v[90:93]
	v_mfma_f32_16x16x32_bf16 v[66:69], v[110:113], v[220:223], v[66:69]
	s_setprio 0
	s_barrier
	s_add_i32 s66, s66, s57
	v_lshl_add_u64 v[192:193], s[64:65], 0, v[0:1]
	s_mov_b32 m0, s66
	ds_read_b128 v[176:179], v229 offset:16384
	ds_read_b128 v[180:183], v229 offset:17408
	ds_read_b128 v[184:187], v229 offset:18432
	ds_read_b128 v[188:191], v229 offset:19456
	ds_read_b128 v[208:211], v229 offset:20480
	ds_read_b128 v[212:215], v229 offset:21504
	ds_read_b128 v[216:219], v229 offset:22528
	ds_read_b128 v[220:223], v229 offset:23552
	global_load_lds_dwordx4 v[192:193], off
	s_add_i32 m0, s66, 0x2000
	v_lshl_add_u64 v[198:199], s[64:65], 0, v[166:167]
	s_add_u32 s64, s64, s4
	s_addc_u32 s65, s65, s5
	s_add_i32 s66, s67, s57
	global_load_lds_dwordx4 v[198:199], off
	v_lshl_add_u64 v[200:201], s[64:65], 0, v[0:1]
	s_mov_b32 m0, s66
	v_lshl_add_u64 v[202:203], s[64:65], 0, v[166:167]
	global_load_lds_dwordx4 v[200:201], off
	s_add_i32 m0, s66, 0x2000
	v_lshl_add_u64 v[204:205], s[54:55], 0, v[170:171]
	global_load_lds_dwordx4 v[202:203], off
	s_mov_b32 m0, s58
	v_lshl_add_u64 v[236:237], s[54:55], 0, v[168:169]
	global_load_lds_dwordx4 v[204:205], off
	s_mov_b32 m0, s59
	s_nop 0
	global_load_lds_dwordx4 v[236:237], off
	s_waitcnt vmcnt(8)
	s_waitcnt lgkmcnt(0)
	s_barrier
; #define PG8_STAGE(bufoff, gbase, voff) do { _Pragma("unroll") for (int _i = 0; _i < 2; ++_i) \
;         __builtin_amdgcn_global_load_lds((const unsigned*)((const char*)(gbase) + (voff)[_i]), (PG8_LAS unsigned*)(lds + (bufoff) + ldsw + _i * 8192), 16, 0, 0); } while (0)
; #define PG8_LDA(dst, b, h) do { _Pragma("unroll") for (int m = 0; m < 4; ++m) _Pragma("unroll") for (int k = 0; k < 2; ++k) dst[m][k] = *(const PG8_LAS bf16x8*)(lds + PG8_SA(b, h) + aoff + m * 2048 + k * 1024); } while (0)
; #define PG8_LDB(dst, b, h) do { _Pragma("unroll") for (int n = 0; n < 2; ++n) _Pragma("unroll") for (int k = 0; k < 2; ++k) dst[n][k] = *(const PG8_LAS bf16x8*)(lds + PG8_SB(b, h) + boff + n * 2048 + k * 1024); } while (0)
; #define PG8_MMA(ai, bj, At, Bt) do { __builtin_amdgcn_s_setprio(1); _Pragma("unroll") for (int m = 0; m < 4; ++m) _Pragma("unroll") for (int n = 0; n < 2; ++n) _Pragma("unroll") for (int k = 0; k < 2; ++k) \
;         acc[ai][bj][m][n] = __builtin_amdgcn_mfma_f32_16x16x32_bf16(Bt[n][k], At[m][k], acc[ai][bj][m][n], 0, 0, 0); __builtin_amdgcn_s_setprio(0); } while (0)
; #define PG8_WAIT_V(n) asm volatile("s_waitcnt vmcnt(" #n ")" ::: "memory")
; #define PG8_WAIT_L(n) asm volatile("s_waitcnt lgkmcnt(" #n ")" ::: "memory")
; #define PG8_BAR __builtin_amdgcn_s_barrier()
; #define PG8_SCHED __builtin_amdgcn_sched_barrier(0)
; template <class Epi, class Sched, bool ALIGN_EPI = false, bool SP2 = false>
; __device__ __forceinline__ void gemm_phase(PG8_LAS unsigned char* lds, const Gemm g, const Sched& S, const Epi& E) {
;     ...
;             PG8_WAIT_V(8); PG8_WAIT_L(0); PG8_BAR; PG8_MMA(1, 0, At, B0); PG8_MMA(1, 1, At, B1); PG8_BAR; PG8_SCHED;
;             PG8_LDB(B0, 1, 0); PG8_LDB(B1, 1, 1); PG8_SCHED; PG8_LDA(At, 1, 0); PG8_STAGE(PG8_SA(0, 1), a2 + hstep, voffA);
;             PG8_WAIT_V(8); PG8_WAIT_L(0); PG8_BAR; PG8_MMA(0, 0, At, B0); PG8_MMA(0, 1, At, B1); PG8_BAR; PG8_SCHED;
	s_setprio 1
	s_waitcnt lgkmcnt(0)
	v_mfma_f32_16x16x32_bf16 v[62:65], v[74:77], v[176:179], v[62:65]
	v_mfma_f32_16x16x32_bf16 v[54:57], v[82:85], v[176:179], v[54:57]
	v_mfma_f32_16x16x32_bf16 v[46:49], v[74:77], v[184:187], v[46:49]
	v_mfma_f32_16x16x32_bf16 v[38:41], v[82:85], v[184:187], v[38:41]
	v_mfma_f32_16x16x32_bf16 v[30:33], v[74:77], v[208:211], v[30:33]
	v_mfma_f32_16x16x32_bf16 v[22:25], v[82:85], v[208:211], v[22:25]
	v_mfma_f32_16x16x32_bf16 v[14:17], v[74:77], v[216:219], v[14:17]
	v_mfma_f32_16x16x32_bf16 v[6:9], v[82:85], v[216:219], v[6:9]
	v_mfma_f32_16x16x32_bf16 v[62:65], v[78:81], v[180:183], v[62:65]
	v_mfma_f32_16x16x32_bf16 v[54:57], v[86:89], v[180:183], v[54:57]
	v_mfma_f32_16x16x32_bf16 v[46:49], v[78:81], v[188:191], v[46:49]
	v_mfma_f32_16x16x32_bf16 v[38:41], v[86:89], v[188:191], v[38:41]
	v_mfma_f32_16x16x32_bf16 v[30:33], v[78:81], v[212:215], v[30:33]
	v_mfma_f32_16x16x32_bf16 v[22:25], v[86:89], v[212:215], v[22:25]
	v_mfma_f32_16x16x32_bf16 v[14:17], v[78:81], v[220:223], v[14:17]
	v_mfma_f32_16x16x32_bf16 v[6:9], v[86:89], v[220:223], v[6:9]
	v_mfma_f32_16x16x32_bf16 v[58:61], v[98:101], v[176:179], v[58:61]
	v_mfma_f32_16x16x32_bf16 v[50:53], v[106:109], v[176:179], v[50:53]
	v_mfma_f32_16x16x32_bf16 v[42:45], v[98:101], v[184:187], v[42:45]
	v_mfma_f32_16x16x32_bf16 v[34:37], v[106:109], v[184:187], v[34:37]
	v_mfma_f32_16x16x32_bf16 v[26:29], v[98:101], v[208:211], v[26:29]
	v_mfma_f32_16x16x32_bf16 v[18:21], v[106:109], v[208:211], v[18:21]
	v_mfma_f32_16x16x32_bf16 v[10:13], v[98:101], v[216:219], v[10:13]
	v_mfma_f32_16x16x32_bf16 v[2:5], v[106:109], v[216:219], v[2:5]
	v_mfma_f32_16x16x32_bf16 v[58:61], v[102:105], v[180:183], v[58:61]
	v_mfma_f32_16x16x32_bf16 v[50:53], v[110:113], v[180:183], v[50:53]
	v_mfma_f32_16x16x32_bf16 v[42:45], v[102:105], v[188:191], v[42:45]
	v_mfma_f32_16x16x32_bf16 v[34:37], v[110:113], v[188:191], v[34:37]
	v_mfma_f32_16x16x32_bf16 v[26:29], v[102:105], v[212:215], v[26:29]
	v_mfma_f32_16x16x32_bf16 v[18:21], v[110:113], v[212:215], v[18:21]
	v_mfma_f32_16x16x32_bf16 v[10:13], v[102:105], v[220:223], v[10:13]
	v_mfma_f32_16x16x32_bf16 v[2:5], v[110:113], v[220:223], v[2:5]
	s_setprio 0
	s_barrier
	s_add_i32 s64, 0, 0x18000
	s_add_i32 s65, 0, 0x1c000
	v_add_u32_e32 v86, s64, v226
	v_add_u32_e32 v110, s65, v226
	ds_read_b128 v[74:77], v86
	ds_read_b128 v[78:81], v86 offset:1024
	ds_read_b128 v[82:85], v86 offset:2048
	ds_read_b128 v[86:89], v86 offset:3072
	ds_read_b128 v[98:101], v110
	ds_read_b128 v[102:105], v110 offset:1024
	ds_read_b128 v[106:109], v110 offset:2048
	ds_read_b128 v[110:113], v110 offset:3072
	s_add_u32 s54, s54, s4
	s_addc_u32 s55, s55, s5
	s_mov_b32 m0, s60
	v_lshl_add_u64 v[238:239], s[54:55], 0, v[170:171]
	ds_read_b128 v[176:179], v229 offset:32768
	ds_read_b128 v[180:183], v229 offset:33792
	ds_read_b128 v[184:187], v229 offset:34816
	ds_read_b128 v[188:191], v229 offset:35840
	ds_read_b128 v[208:211], v229 offset:36864
	ds_read_b128 v[212:215], v229 offset:37888
	ds_read_b128 v[216:219], v229 offset:38912
	ds_read_b128 v[220:223], v229 offset:39936
	global_load_lds_dwordx4 v[238:239], off
	v_lshl_add_u64 v[238:239], s[54:55], 0, v[168:169]
	s_mov_b32 m0, s61
	s_nop 0
	global_load_lds_dwordx4 v[238:239], off
	s_waitcnt vmcnt(8)
	s_waitcnt lgkmcnt(0)
	s_barrier
	s_setprio 1
	s_waitcnt lgkmcnt(0)
	v_mfma_f32_16x16x32_bf16 v[162:165], v[74:77], v[176:179], v[162:165]
	v_mfma_f32_16x16x32_bf16 v[154:157], v[82:85], v[176:179], v[154:157]
	v_mfma_f32_16x16x32_bf16 v[146:149], v[74:77], v[184:187], v[146:149]
	v_mfma_f32_16x16x32_bf16 v[138:141], v[82:85], v[184:187], v[138:141]
	v_mfma_f32_16x16x32_bf16 v[126:129], v[74:77], v[208:211], v[126:129]
	v_mfma_f32_16x16x32_bf16 v[118:121], v[82:85], v[208:211], v[118:121]
	v_mfma_f32_16x16x32_bf16 v[94:97], v[74:77], v[216:219], v[94:97]
	v_mfma_f32_16x16x32_bf16 v[70:73], v[82:85], v[216:219], v[70:73]
	v_mfma_f32_16x16x32_bf16 v[162:165], v[78:81], v[180:183], v[162:165]
	v_mfma_f32_16x16x32_bf16 v[154:157], v[86:89], v[180:183], v[154:157]
	v_mfma_f32_16x16x32_bf16 v[146:149], v[78:81], v[188:191], v[146:149]
	v_mfma_f32_16x16x32_bf16 v[138:141], v[86:89], v[188:191], v[138:141]
	v_mfma_f32_16x16x32_bf16 v[126:129], v[78:81], v[212:215], v[126:129]
	v_mfma_f32_16x16x32_bf16 v[118:121], v[86:89], v[212:215], v[118:121]
	v_mfma_f32_16x16x32_bf16 v[94:97], v[78:81], v[220:223], v[94:97]
	v_mfma_f32_16x16x32_bf16 v[70:73], v[86:89], v[220:223], v[70:73]
	v_mfma_f32_16x16x32_bf16 v[158:161], v[98:101], v[176:179], v[158:161]
	v_mfma_f32_16x16x32_bf16 v[150:153], v[106:109], v[176:179], v[150:153]
	v_mfma_f32_16x16x32_bf16 v[142:145], v[98:101], v[184:187], v[142:145]
	v_mfma_f32_16x16x32_bf16 v[134:137], v[106:109], v[184:187], v[134:137]
	v_mfma_f32_16x16x32_bf16 v[122:125], v[98:101], v[208:211], v[122:125]
	v_mfma_f32_16x16x32_bf16 v[114:117], v[106:109], v[208:211], v[114:117]
	v_mfma_f32_16x16x32_bf16 v[90:93], v[98:101], v[216:219], v[90:93]
	v_mfma_f32_16x16x32_bf16 v[66:69], v[106:109], v[216:219], v[66:69]
	v_mfma_f32_16x16x32_bf16 v[158:161], v[102:105], v[180:183], v[158:161]
	v_mfma_f32_16x16x32_bf16 v[150:153], v[110:113], v[180:183], v[150:153]
	v_mfma_f32_16x16x32_bf16 v[142:145], v[102:105], v[188:191], v[142:145]
	v_mfma_f32_16x16x32_bf16 v[134:137], v[110:113], v[188:191], v[134:137]
	v_mfma_f32_16x16x32_bf16 v[122:125], v[102:105], v[212:215], v[122:125]
	v_mfma_f32_16x16x32_bf16 v[114:117], v[110:113], v[212:215], v[114:117]
	v_mfma_f32_16x16x32_bf16 v[90:93], v[102:105], v[220:223], v[90:93]
	v_mfma_f32_16x16x32_bf16 v[66:69], v[110:113], v[220:223], v[66:69]
	s_setprio 0
	s_barrier
; #define PG8_STAGE(bufoff, gbase, voff) do { _Pragma("unroll") for (int _i = 0; _i < 2; ++_i) \
;         __builtin_amdgcn_global_load_lds((const unsigned*)((const char*)(gbase) + (voff)[_i]), (PG8_LAS unsigned*)(lds + (bufoff) + ldsw + _i * 8192), 16, 0, 0); } while (0)
; #define PG8_LDA(dst, b, h) do { _Pragma("unroll") for (int m = 0; m < 4; ++m) _Pragma("unroll") for (int k = 0; k < 2; ++k) dst[m][k] = *(const PG8_LAS bf16x8*)(lds + PG8_SA(b, h) + aoff + m * 2048 + k * 1024); } while (0)
; #define PG8_MMA(ai, bj, At, Bt) do { __builtin_amdgcn_s_setprio(1); _Pragma("unroll") for (int m = 0; m < 4; ++m) _Pragma("unroll") for (int n = 0; n < 2; ++n) _Pragma("unroll") for (int k = 0; k < 2; ++k) \
;         acc[ai][bj][m][n] = __builtin_amdgcn_mfma_f32_16x16x32_bf16(Bt[n][k], At[m][k], acc[ai][bj][m][n], 0, 0, 0); __builtin_amdgcn_s_setprio(0); } while (0)
; #define PG8_WAIT_V(n) asm volatile("s_waitcnt vmcnt(" #n ")" ::: "memory")
; #define PG8_WAIT_L(n) asm volatile("s_waitcnt lgkmcnt(" #n ")" ::: "memory")
; #define PG8_BAR __builtin_amdgcn_s_barrier()
; #define PG8_SCHED __builtin_amdgcn_sched_barrier(0)
; template <class Epi, class Sched, bool ALIGN_EPI = false, bool SP2 = false>
; __device__ __forceinline__ void gemm_phase(PG8_LAS unsigned char* lds, const Gemm g, const Sched& S, const Epi& E) {
;     ...
;             PG8_LDA(At, 1, 1); PG8_STAGE(PG8_SB(1, 0), b3, voffB); PG8_STAGE(PG8_SB(1, 1), b3 + hstep, voffB); PG8_STAGE(PG8_SA(1, 0), a3, voffA);
;             PG8_WAIT_V(8); PG8_WAIT_L(0); PG8_BAR; PG8_MMA(1, 0, At, B0); PG8_MMA(1, 1, At, B1); PG8_BAR; PG8_SCHED;
	s_add_i32 s54, s64, s57
	v_lshl_add_u64 v[192:193], v[192:193], 0, s[26:27]
	s_mov_b32 m0, s54
	ds_read_b128 v[176:179], v229 offset:49152
	ds_read_b128 v[180:183], v229 offset:50176
	ds_read_b128 v[184:187], v229 offset:51200
	ds_read_b128 v[188:191], v229 offset:52224
	ds_read_b128 v[208:211], v229 offset:53248
	ds_read_b128 v[212:215], v229 offset:54272
	ds_read_b128 v[216:219], v229 offset:55296
	ds_read_b128 v[220:223], v229 offset:56320
	global_load_lds_dwordx4 v[192:193], off
	v_lshl_add_u64 v[192:193], v[198:199], 0, s[26:27]
	s_add_i32 m0, s54, 0x2000
	s_add_i32 s54, s65, s57
	global_load_lds_dwordx4 v[192:193], off
	v_lshl_add_u64 v[192:193], v[200:201], 0, s[26:27]
	s_mov_b32 m0, s54
	s_nop 0
	global_load_lds_dwordx4 v[192:193], off
	v_lshl_add_u64 v[192:193], v[202:203], 0, s[26:27]
	s_add_i32 m0, s54, 0x2000
	s_nop 0
	global_load_lds_dwordx4 v[192:193], off
	v_lshl_add_u64 v[192:193], v[204:205], 0, s[26:27]
	s_mov_b32 m0, s81
	s_nop 0
	global_load_lds_dwordx4 v[192:193], off
	v_lshl_add_u64 v[192:193], v[236:237], 0, s[26:27]
	s_mov_b32 m0, s82
	s_nop 0
	global_load_lds_dwordx4 v[192:193], off
	s_waitcnt vmcnt(8)
	s_waitcnt lgkmcnt(0)
	s_barrier
	s_setprio 1
	s_waitcnt lgkmcnt(0)
	v_mfma_f32_16x16x32_bf16 v[62:65], v[74:77], v[176:179], v[62:65]
	v_mfma_f32_16x16x32_bf16 v[54:57], v[82:85], v[176:179], v[54:57]
	v_mfma_f32_16x16x32_bf16 v[46:49], v[74:77], v[184:187], v[46:49]
	v_mfma_f32_16x16x32_bf16 v[38:41], v[82:85], v[184:187], v[38:41]
	v_mfma_f32_16x16x32_bf16 v[30:33], v[74:77], v[208:211], v[30:33]
	v_mfma_f32_16x16x32_bf16 v[22:25], v[82:85], v[208:211], v[22:25]
	v_mfma_f32_16x16x32_bf16 v[14:17], v[74:77], v[216:219], v[14:17]
	v_mfma_f32_16x16x32_bf16 v[6:9], v[82:85], v[216:219], v[6:9]
	v_mfma_f32_16x16x32_bf16 v[62:65], v[78:81], v[180:183], v[62:65]
	v_mfma_f32_16x16x32_bf16 v[54:57], v[86:89], v[180:183], v[54:57]
	v_mfma_f32_16x16x32_bf16 v[46:49], v[78:81], v[188:191], v[46:49]
	v_mfma_f32_16x16x32_bf16 v[38:41], v[86:89], v[188:191], v[38:41]
	v_mfma_f32_16x16x32_bf16 v[30:33], v[78:81], v[212:215], v[30:33]
	v_mfma_f32_16x16x32_bf16 v[22:25], v[86:89], v[212:215], v[22:25]
	v_mfma_f32_16x16x32_bf16 v[14:17], v[78:81], v[220:223], v[14:17]
	v_mfma_f32_16x16x32_bf16 v[6:9], v[86:89], v[220:223], v[6:9]
	v_mfma_f32_16x16x32_bf16 v[58:61], v[98:101], v[176:179], v[58:61]
	v_mfma_f32_16x16x32_bf16 v[50:53], v[106:109], v[176:179], v[50:53]
	v_mfma_f32_16x16x32_bf16 v[42:45], v[98:101], v[184:187], v[42:45]
	v_mfma_f32_16x16x32_bf16 v[34:37], v[106:109], v[184:187], v[34:37]
	v_mfma_f32_16x16x32_bf16 v[26:29], v[98:101], v[208:211], v[26:29]
	v_mfma_f32_16x16x32_bf16 v[18:21], v[106:109], v[208:211], v[18:21]
	v_mfma_f32_16x16x32_bf16 v[10:13], v[98:101], v[216:219], v[10:13]
	v_mfma_f32_16x16x32_bf16 v[2:5], v[106:109], v[216:219], v[2:5]
	v_mfma_f32_16x16x32_bf16 v[58:61], v[102:105], v[180:183], v[58:61]
	v_mfma_f32_16x16x32_bf16 v[50:53], v[110:113], v[180:183], v[50:53]
	v_mfma_f32_16x16x32_bf16 v[42:45], v[102:105], v[188:191], v[42:45]
	v_mfma_f32_16x16x32_bf16 v[34:37], v[110:113], v[188:191], v[34:37]
	v_mfma_f32_16x16x32_bf16 v[26:29], v[102:105], v[212:215], v[26:29]
	v_mfma_f32_16x16x32_bf16 v[18:21], v[110:113], v[212:215], v[18:21]
	v_mfma_f32_16x16x32_bf16 v[10:13], v[102:105], v[220:223], v[10:13]
	v_mfma_f32_16x16x32_bf16 v[2:5], v[110:113], v[220:223], v[2:5]
	s_setprio 0
	s_barrier
	s_add_u32 s14, s14, 0x100
	s_addc_u32 s15, s15, 0
	s_add_u32 s89, s89, 0x100
	s_addc_u32 s90, s90, 0
	s_cmp_ge_i32 s91, s80
	s_mov_b32 s54, s91
	s_cbranch_scc0 .LBB0_104

; #define PG8_STAGE(bufoff, gbase, voff) do { _Pragma("unroll") for (int _i = 0; _i < 2; ++_i) \
;         __builtin_amdgcn_global_load_lds((const unsigned*)((const char*)(gbase) + (voff)[_i]), (PG8_LAS unsigned*)(lds + (bufoff) + ldsw + _i * 8192), 16, 0, 0); } while (0)
; #define PG8_LDA(dst, b, h) do { _Pragma("unroll") for (int m = 0; m < 4; ++m) _Pragma("unroll") for (int k = 0; k < 2; ++k) dst[m][k] = *(const PG8_LAS bf16x8*)(lds + PG8_SA(b, h) + aoff + m * 2048 + k * 1024); } while (0)
; #define PG8_LDB(dst, b, h) do { _Pragma("unroll") for (int n = 0; n < 2; ++n) _Pragma("unroll") for (int k = 0; k < 2; ++k) dst[n][k] = *(const PG8_LAS bf16x8*)(lds + PG8_SB(b, h) + boff + n * 2048 + k * 1024); } while (0)
; #define PG8_MMA(ai, bj, At, Bt) do { __builtin_amdgcn_s_setprio(1); _Pragma("unroll") for (int m = 0; m < 4; ++m) _Pragma("unroll") for (int n = 0; n < 2; ++n) _Pragma("unroll") for (int k = 0; k < 2; ++k) \
;         acc[ai][bj][m][n] = __builtin_amdgcn_mfma_f32_16x16x32_bf16(Bt[n][k], At[m][k], acc[ai][bj][m][n], 0, 0, 0); __builtin_amdgcn_s_setprio(0); } while (0)
; #define PG8_WAIT_V(n) asm volatile("s_waitcnt vmcnt(" #n ")" ::: "memory")
; #define PG8_WAIT_L(n) asm volatile("s_waitcnt lgkmcnt(" #n ")" ::: "memory")
; #define PG8_BAR __builtin_amdgcn_s_barrier()
; #define PG8_SCHED __builtin_amdgcn_sched_barrier(0)
; template <class Epi, class Sched, bool ALIGN_EPI = false, bool SP2 = false>
; __device__ __forceinline__ void gemm_phase(PG8_LAS unsigned char* lds, const Gemm g, const Sched& S, const Epi& E) {
;     ...
;             const char* a2 = last ? nA : cA + (size_t)(t + 2) * kstep; const char* b2 = last ? nB : cB + (size_t)(t + 2) * kstep;
;             const char* a3 = a2 + kstep; const char* b3 = b2 + kstep;
;             if (last && has_next) S.a_ready(nxt);
;             if constexpr (SP2) {
;             PG8_LDB(B0, 0, 0); PG8_LDB(B1, 0, 1); PG8_SCHED; PG8_LDA(At, 0, 0); PG8_STAGE(PG8_SA(1, 1), a1 + hstep, voffA);
;             PG8_WAIT_V(8); PG8_WAIT_L(0); PG8_BAR; PG8_MMA(0, 0, At, B0); PG8_MMA(0, 1, At, B1); PG8_BAR; PG8_SCHED;
;             PG8_LDA(At, 0, 1); PG8_STAGE(PG8_SB(0, 0), b2, voffB); PG8_STAGE(PG8_SB(0, 1), b2 + hstep, voffB); PG8_STAGE(PG8_SA(0, 0), a2, voffA);
.LBB0_132:
	s_add_i32 s93, s56, 2
	s_add_u32 s64, s14, 0x80
	s_addc_u32 s57, s15, 0
	s_add_i32 s66, 0, 0x10000
	s_cmp_eq_u32 s89, s56
	s_cselect_b32 s57, s45, s57
	s_cselect_b32 s56, s44, s64
	s_cselect_b32 s65, s55, s59
	s_cselect_b32 s64, s54, s58
	s_add_i32 s67, 0, 0x14000
	v_add_u32_e32 v146, s66, v181
	v_add_u32_e32 v172, s67, v181
	ds_read_b128 v[134:137], v146
	ds_read_b128 v[138:141], v146 offset:1024
	ds_read_b128 v[142:145], v146 offset:2048
	ds_read_b128 v[146:149], v146 offset:3072
	ds_read_b128 v[150:153], v172
	ds_read_b128 v[154:157], v172 offset:1024
	ds_read_b128 v[168:171], v172 offset:2048
	ds_read_b128 v[172:175], v172 offset:3072
	v_lshl_add_u64 v[192:193], s[14:15], 0, v[164:165]
	s_add_i32 m0, s82, 0xc000
	ds_read_b128 v[176:179], v183
	ds_read_b128 v[184:187], v183 offset:1024
	ds_read_b128 v[188:191], v183 offset:2048
	ds_read_b128 v[208:211], v183 offset:3072
	ds_read_b128 v[212:215], v183 offset:4096
	ds_read_b128 v[216:219], v183 offset:5120
	ds_read_b128 v[220:223], v183 offset:6144
	ds_read_b128 v[236:239], v183 offset:7168
	global_load_lds_dwordx4 v[192:193], off
	v_lshl_add_u64 v[192:193], s[14:15], 0, v[166:167]
	s_add_i32 m0, s82, 0xe000
	s_nop 0
	global_load_lds_dwordx4 v[192:193], off
	s_waitcnt vmcnt(8)
	s_waitcnt lgkmcnt(0)
	s_barrier
	s_setprio 1
	s_waitcnt lgkmcnt(0)
	v_mfma_f32_16x16x32_bf16 v[126:129], v[134:137], v[176:179], v[126:129]
	v_mfma_f32_16x16x32_bf16 v[122:125], v[142:145], v[176:179], v[122:125]
	v_mfma_f32_16x16x32_bf16 v[110:113], v[134:137], v[188:191], v[110:113]
	v_mfma_f32_16x16x32_bf16 v[106:109], v[142:145], v[188:191], v[106:109]
	v_mfma_f32_16x16x32_bf16 v[94:97], v[134:137], v[212:215], v[94:97]
	v_mfma_f32_16x16x32_bf16 v[90:93], v[142:145], v[212:215], v[90:93]
	v_mfma_f32_16x16x32_bf16 v[78:81], v[134:137], v[220:223], v[78:81]
	v_mfma_f32_16x16x32_bf16 v[74:77], v[142:145], v[220:223], v[74:77]
	v_mfma_f32_16x16x32_bf16 v[126:129], v[138:141], v[184:187], v[126:129]
	v_mfma_f32_16x16x32_bf16 v[122:125], v[146:149], v[184:187], v[122:125]
	v_mfma_f32_16x16x32_bf16 v[110:113], v[138:141], v[208:211], v[110:113]
	v_mfma_f32_16x16x32_bf16 v[106:109], v[146:149], v[208:211], v[106:109]
	v_mfma_f32_16x16x32_bf16 v[94:97], v[138:141], v[216:219], v[94:97]
	v_mfma_f32_16x16x32_bf16 v[90:93], v[146:149], v[216:219], v[90:93]
	v_mfma_f32_16x16x32_bf16 v[78:81], v[138:141], v[236:239], v[78:81]
	v_mfma_f32_16x16x32_bf16 v[74:77], v[146:149], v[236:239], v[74:77]
	v_mfma_f32_16x16x32_bf16 v[118:121], v[150:153], v[176:179], v[118:121]
	v_mfma_f32_16x16x32_bf16 v[114:117], v[168:171], v[176:179], v[114:117]
	v_mfma_f32_16x16x32_bf16 v[102:105], v[150:153], v[188:191], v[102:105]
	v_mfma_f32_16x16x32_bf16 v[98:101], v[168:171], v[188:191], v[98:101]
	v_mfma_f32_16x16x32_bf16 v[86:89], v[150:153], v[212:215], v[86:89]
	v_mfma_f32_16x16x32_bf16 v[82:85], v[168:171], v[212:215], v[82:85]
	v_mfma_f32_16x16x32_bf16 v[70:73], v[150:153], v[220:223], v[70:73]
	v_mfma_f32_16x16x32_bf16 v[66:69], v[168:171], v[220:223], v[66:69]
	v_mfma_f32_16x16x32_bf16 v[118:121], v[154:157], v[184:187], v[118:121]
	v_mfma_f32_16x16x32_bf16 v[114:117], v[172:175], v[184:187], v[114:117]
	v_mfma_f32_16x16x32_bf16 v[102:105], v[154:157], v[208:211], v[102:105]
	v_mfma_f32_16x16x32_bf16 v[98:101], v[172:175], v[208:211], v[98:101]
	v_mfma_f32_16x16x32_bf16 v[86:89], v[154:157], v[216:219], v[86:89]
	v_mfma_f32_16x16x32_bf16 v[82:85], v[172:175], v[216:219], v[82:85]
	v_mfma_f32_16x16x32_bf16 v[70:73], v[154:157], v[236:239], v[70:73]
	v_mfma_f32_16x16x32_bf16 v[66:69], v[172:175], v[236:239], v[66:69]
	s_setprio 0
	s_barrier
	s_add_i32 s66, s66, s81
	v_lshl_add_u64 v[192:193], s[64:65], 0, v[0:1]
	s_mov_b32 m0, s66
	ds_read_b128 v[176:179], v183 offset:16384
	ds_read_b128 v[184:187], v183 offset:17408
	ds_read_b128 v[188:191], v183 offset:18432
	ds_read_b128 v[208:211], v183 offset:19456
	ds_read_b128 v[212:215], v183 offset:20480
	ds_read_b128 v[216:219], v183 offset:21504
	ds_read_b128 v[220:223], v183 offset:22528
	ds_read_b128 v[236:239], v183 offset:23552
	global_load_lds_dwordx4 v[192:193], off
	s_add_i32 m0, s66, 0x2000
	v_lshl_add_u64 v[198:199], s[64:65], 0, v[158:159]
	s_add_u32 s64, s64, s4
	s_addc_u32 s65, s65, s5
	s_add_i32 s66, s67, s81
	global_load_lds_dwordx4 v[198:199], off
	v_lshl_add_u64 v[200:201], s[64:65], 0, v[0:1]
	s_mov_b32 m0, s66
	v_lshl_add_u64 v[202:203], s[64:65], 0, v[158:159]
	global_load_lds_dwordx4 v[200:201], off
	s_add_i32 m0, s66, 0x2000
	v_lshl_add_u64 v[204:205], s[56:57], 0, v[162:163]
	global_load_lds_dwordx4 v[202:203], off
	s_mov_b32 m0, s82
	v_lshl_add_u64 v[224:225], s[56:57], 0, v[160:161]
	global_load_lds_dwordx4 v[204:205], off
	s_mov_b32 m0, s83
	s_nop 0
	global_load_lds_dwordx4 v[224:225], off
	s_waitcnt vmcnt(8)
	s_waitcnt lgkmcnt(0)
	s_barrier
; #define PG8_STAGE(bufoff, gbase, voff) do { _Pragma("unroll") for (int _i = 0; _i < 2; ++_i) \
;         __builtin_amdgcn_global_load_lds((const unsigned*)((const char*)(gbase) + (voff)[_i]), (PG8_LAS unsigned*)(lds + (bufoff) + ldsw + _i * 8192), 16, 0, 0); } while (0)
; #define PG8_LDA(dst, b, h) do { _Pragma("unroll") for (int m = 0; m < 4; ++m) _Pragma("unroll") for (int k = 0; k < 2; ++k) dst[m][k] = *(const PG8_LAS bf16x8*)(lds + PG8_SA(b, h) + aoff + m * 2048 + k * 1024); } while (0)
; #define PG8_LDB(dst, b, h) do { _Pragma("unroll") for (int n = 0; n < 2; ++n) _Pragma("unroll") for (int k = 0; k < 2; ++k) dst[n][k] = *(const PG8_LAS bf16x8*)(lds + PG8_SB(b, h) + boff + n * 2048 + k * 1024); } while (0)
; #define PG8_MMA(ai, bj, At, Bt) do { __builtin_amdgcn_s_setprio(1); _Pragma("unroll") for (int m = 0; m < 4; ++m) _Pragma("unroll") for (int n = 0; n < 2; ++n) _Pragma("unroll") for (int k = 0; k < 2; ++k) \
;         acc[ai][bj][m][n] = __builtin_amdgcn_mfma_f32_16x16x32_bf16(Bt[n][k], At[m][k], acc[ai][bj][m][n], 0, 0, 0); __builtin_amdgcn_s_setprio(0); } while (0)
; #define PG8_WAIT_V(n) asm volatile("s_waitcnt vmcnt(" #n ")" ::: "memory")
; #define PG8_WAIT_L(n) asm volatile("s_waitcnt lgkmcnt(" #n ")" ::: "memory")
; #define PG8_BAR __builtin_amdgcn_s_barrier()
; #define PG8_SCHED __builtin_amdgcn_sched_barrier(0)
; template <class Epi, class Sched, bool ALIGN_EPI = false, bool SP2 = false>
; __device__ __forceinline__ void gemm_phase(PG8_LAS unsigned char* lds, const Gemm g, const Sched& S, const Epi& E) {
;     ...
;             PG8_WAIT_V(8); PG8_WAIT_L(0); PG8_BAR; PG8_MMA(1, 0, At, B0); PG8_MMA(1, 1, At, B1); PG8_BAR; PG8_SCHED;
;             PG8_LDB(B0, 1, 0); PG8_LDB(B1, 1, 1); PG8_SCHED; PG8_LDA(At, 1, 0); PG8_STAGE(PG8_SA(0, 1), a2 + hstep, voffA);
;             PG8_WAIT_V(8); PG8_WAIT_L(0); PG8_BAR; PG8_MMA(0, 0, At, B0); PG8_MMA(0, 1, At, B1); PG8_BAR; PG8_SCHED;
	s_setprio 1
	s_waitcnt lgkmcnt(0)
	v_mfma_f32_16x16x32_bf16 v[62:65], v[134:137], v[176:179], v[62:65]
	v_mfma_f32_16x16x32_bf16 v[58:61], v[142:145], v[176:179], v[58:61]
	v_mfma_f32_16x16x32_bf16 v[46:49], v[134:137], v[188:191], v[46:49]
	v_mfma_f32_16x16x32_bf16 v[42:45], v[142:145], v[188:191], v[42:45]
	v_mfma_f32_16x16x32_bf16 v[30:33], v[134:137], v[212:215], v[30:33]
	v_mfma_f32_16x16x32_bf16 v[26:29], v[142:145], v[212:215], v[26:29]
	v_mfma_f32_16x16x32_bf16 v[14:17], v[134:137], v[220:223], v[14:17]
	v_mfma_f32_16x16x32_bf16 v[10:13], v[142:145], v[220:223], v[10:13]
	v_mfma_f32_16x16x32_bf16 v[62:65], v[138:141], v[184:187], v[62:65]
	v_mfma_f32_16x16x32_bf16 v[58:61], v[146:149], v[184:187], v[58:61]
	v_mfma_f32_16x16x32_bf16 v[46:49], v[138:141], v[208:211], v[46:49]
	v_mfma_f32_16x16x32_bf16 v[42:45], v[146:149], v[208:211], v[42:45]
	v_mfma_f32_16x16x32_bf16 v[30:33], v[138:141], v[216:219], v[30:33]
	v_mfma_f32_16x16x32_bf16 v[26:29], v[146:149], v[216:219], v[26:29]
	v_mfma_f32_16x16x32_bf16 v[14:17], v[138:141], v[236:239], v[14:17]
	v_mfma_f32_16x16x32_bf16 v[10:13], v[146:149], v[236:239], v[10:13]
	v_mfma_f32_16x16x32_bf16 v[54:57], v[150:153], v[176:179], v[54:57]
	v_mfma_f32_16x16x32_bf16 v[50:53], v[168:171], v[176:179], v[50:53]
	v_mfma_f32_16x16x32_bf16 v[38:41], v[150:153], v[188:191], v[38:41]
	v_mfma_f32_16x16x32_bf16 v[34:37], v[168:171], v[188:191], v[34:37]
	v_mfma_f32_16x16x32_bf16 v[22:25], v[150:153], v[212:215], v[22:25]
	v_mfma_f32_16x16x32_bf16 v[18:21], v[168:171], v[212:215], v[18:21]
	v_mfma_f32_16x16x32_bf16 v[6:9], v[150:153], v[220:223], v[6:9]
	v_mfma_f32_16x16x32_bf16 v[2:5], v[168:171], v[220:223], v[2:5]
	v_mfma_f32_16x16x32_bf16 v[54:57], v[154:157], v[184:187], v[54:57]
	v_mfma_f32_16x16x32_bf16 v[50:53], v[172:175], v[184:187], v[50:53]
	v_mfma_f32_16x16x32_bf16 v[38:41], v[154:157], v[208:211], v[38:41]
	v_mfma_f32_16x16x32_bf16 v[34:37], v[172:175], v[208:211], v[34:37]
	v_mfma_f32_16x16x32_bf16 v[22:25], v[154:157], v[216:219], v[22:25]
	v_mfma_f32_16x16x32_bf16 v[18:21], v[172:175], v[216:219], v[18:21]
	v_mfma_f32_16x16x32_bf16 v[6:9], v[154:157], v[236:239], v[6:9]
	v_mfma_f32_16x16x32_bf16 v[2:5], v[172:175], v[236:239], v[2:5]
	s_setprio 0
	s_barrier
	s_add_i32 s64, 0, 0x18000
	s_add_i32 s65, 0, 0x1c000
	v_add_u32_e32 v146, s64, v181
	v_add_u32_e32 v172, s65, v181
	ds_read_b128 v[134:137], v146
	ds_read_b128 v[138:141], v146 offset:1024
	ds_read_b128 v[142:145], v146 offset:2048
	ds_read_b128 v[146:149], v146 offset:3072
	ds_read_b128 v[150:153], v172
	ds_read_b128 v[154:157], v172 offset:1024
	ds_read_b128 v[168:171], v172 offset:2048
	ds_read_b128 v[172:175], v172 offset:3072
	s_add_u32 s56, s56, s4
	s_addc_u32 s57, s57, s5
	s_mov_b32 m0, s84
	v_lshl_add_u64 v[228:229], s[56:57], 0, v[162:163]
	ds_read_b128 v[176:179], v183 offset:32768
	ds_read_b128 v[184:187], v183 offset:33792
	ds_read_b128 v[188:191], v183 offset:34816
	ds_read_b128 v[208:211], v183 offset:35840
	ds_read_b128 v[212:215], v183 offset:36864
	ds_read_b128 v[216:219], v183 offset:37888
	ds_read_b128 v[220:223], v183 offset:38912
	ds_read_b128 v[236:239], v183 offset:39936
	global_load_lds_dwordx4 v[228:229], off
	v_lshl_add_u64 v[228:229], s[56:57], 0, v[160:161]
	s_mov_b32 m0, s85
	s_nop 0
	global_load_lds_dwordx4 v[228:229], off
	s_waitcnt vmcnt(8)
	s_waitcnt lgkmcnt(0)
	s_barrier
	s_setprio 1
	s_waitcnt lgkmcnt(0)
	v_mfma_f32_16x16x32_bf16 v[126:129], v[134:137], v[176:179], v[126:129]
	v_mfma_f32_16x16x32_bf16 v[122:125], v[142:145], v[176:179], v[122:125]
	v_mfma_f32_16x16x32_bf16 v[110:113], v[134:137], v[188:191], v[110:113]
	v_mfma_f32_16x16x32_bf16 v[106:109], v[142:145], v[188:191], v[106:109]
	v_mfma_f32_16x16x32_bf16 v[94:97], v[134:137], v[212:215], v[94:97]
	v_mfma_f32_16x16x32_bf16 v[90:93], v[142:145], v[212:215], v[90:93]
	v_mfma_f32_16x16x32_bf16 v[78:81], v[134:137], v[220:223], v[78:81]
	v_mfma_f32_16x16x32_bf16 v[74:77], v[142:145], v[220:223], v[74:77]
	v_mfma_f32_16x16x32_bf16 v[126:129], v[138:141], v[184:187], v[126:129]
	v_mfma_f32_16x16x32_bf16 v[122:125], v[146:149], v[184:187], v[122:125]
	v_mfma_f32_16x16x32_bf16 v[110:113], v[138:141], v[208:211], v[110:113]
	v_mfma_f32_16x16x32_bf16 v[106:109], v[146:149], v[208:211], v[106:109]
	v_mfma_f32_16x16x32_bf16 v[94:97], v[138:141], v[216:219], v[94:97]
	v_mfma_f32_16x16x32_bf16 v[90:93], v[146:149], v[216:219], v[90:93]
	v_mfma_f32_16x16x32_bf16 v[78:81], v[138:141], v[236:239], v[78:81]
	v_mfma_f32_16x16x32_bf16 v[74:77], v[146:149], v[236:239], v[74:77]
	v_mfma_f32_16x16x32_bf16 v[118:121], v[150:153], v[176:179], v[118:121]
	v_mfma_f32_16x16x32_bf16 v[114:117], v[168:171], v[176:179], v[114:117]
	v_mfma_f32_16x16x32_bf16 v[102:105], v[150:153], v[188:191], v[102:105]
	v_mfma_f32_16x16x32_bf16 v[98:101], v[168:171], v[188:191], v[98:101]
	v_mfma_f32_16x16x32_bf16 v[86:89], v[150:153], v[212:215], v[86:89]
	v_mfma_f32_16x16x32_bf16 v[82:85], v[168:171], v[212:215], v[82:85]
	v_mfma_f32_16x16x32_bf16 v[70:73], v[150:153], v[220:223], v[70:73]
	v_mfma_f32_16x16x32_bf16 v[66:69], v[168:171], v[220:223], v[66:69]
	v_mfma_f32_16x16x32_bf16 v[118:121], v[154:157], v[184:187], v[118:121]
	v_mfma_f32_16x16x32_bf16 v[114:117], v[172:175], v[184:187], v[114:117]
	v_mfma_f32_16x16x32_bf16 v[102:105], v[154:157], v[208:211], v[102:105]
	v_mfma_f32_16x16x32_bf16 v[98:101], v[172:175], v[208:211], v[98:101]
	v_mfma_f32_16x16x32_bf16 v[86:89], v[154:157], v[216:219], v[86:89]
	v_mfma_f32_16x16x32_bf16 v[82:85], v[172:175], v[216:219], v[82:85]
	v_mfma_f32_16x16x32_bf16 v[70:73], v[154:157], v[236:239], v[70:73]
	v_mfma_f32_16x16x32_bf16 v[66:69], v[172:175], v[236:239], v[66:69]
	s_setprio 0
	s_barrier
; #define PG8_STAGE(bufoff, gbase, voff) do { _Pragma("unroll") for (int _i = 0; _i < 2; ++_i) \
;         __builtin_amdgcn_global_load_lds((const unsigned*)((const char*)(gbase) + (voff)[_i]), (PG8_LAS unsigned*)(lds + (bufoff) + ldsw + _i * 8192), 16, 0, 0); } while (0)
; #define PG8_LDA(dst, b, h) do { _Pragma("unroll") for (int m = 0; m < 4; ++m) _Pragma("unroll") for (int k = 0; k < 2; ++k) dst[m][k] = *(const PG8_LAS bf16x8*)(lds + PG8_SA(b, h) + aoff + m * 2048 + k * 1024); } while (0)
; #define PG8_MMA(ai, bj, At, Bt) do { __builtin_amdgcn_s_setprio(1); _Pragma("unroll") for (int m = 0; m < 4; ++m) _Pragma("unroll") for (int n = 0; n < 2; ++n) _Pragma("unroll") for (int k = 0; k < 2; ++k) \
;         acc[ai][bj][m][n] = __builtin_amdgcn_mfma_f32_16x16x32_bf16(Bt[n][k], At[m][k], acc[ai][bj][m][n], 0, 0, 0); __builtin_amdgcn_s_setprio(0); } while (0)
; #define PG8_WAIT_V(n) asm volatile("s_waitcnt vmcnt(" #n ")" ::: "memory")
; #define PG8_WAIT_L(n) asm volatile("s_waitcnt lgkmcnt(" #n ")" ::: "memory")
; #define PG8_BAR __builtin_amdgcn_s_barrier()
; #define PG8_SCHED __builtin_amdgcn_sched_barrier(0)
; template <class Epi, class Sched, bool ALIGN_EPI = false, bool SP2 = false>
; __device__ __forceinline__ void gemm_phase(PG8_LAS unsigned char* lds, const Gemm g, const Sched& S, const Epi& E) {
;     ...
;             PG8_LDA(At, 1, 1); PG8_STAGE(PG8_SB(1, 0), b3, voffB); PG8_STAGE(PG8_SB(1, 1), b3 + hstep, voffB); PG8_STAGE(PG8_SA(1, 0), a3, voffA);
;             PG8_WAIT_V(8); PG8_WAIT_L(0); PG8_BAR; PG8_MMA(1, 0, At, B0); PG8_MMA(1, 1, At, B1); PG8_BAR; PG8_SCHED;
	s_add_i32 s56, s64, s81
	v_lshl_add_u64 v[192:193], v[192:193], 0, s[26:27]
	s_mov_b32 m0, s56
	ds_read_b128 v[176:179], v183 offset:49152
	ds_read_b128 v[184:187], v183 offset:50176
	ds_read_b128 v[188:191], v183 offset:51200
	ds_read_b128 v[208:211], v183 offset:52224
	ds_read_b128 v[212:215], v183 offset:53248
	ds_read_b128 v[216:219], v183 offset:54272
	ds_read_b128 v[220:223], v183 offset:55296
	ds_read_b128 v[236:239], v183 offset:56320
	global_load_lds_dwordx4 v[192:193], off
	v_lshl_add_u64 v[192:193], v[198:199], 0, s[26:27]
	s_add_i32 m0, s56, 0x2000
	s_add_i32 s56, s65, s81
	global_load_lds_dwordx4 v[192:193], off
	v_lshl_add_u64 v[192:193], v[200:201], 0, s[26:27]
	s_mov_b32 m0, s56
	s_nop 0
	global_load_lds_dwordx4 v[192:193], off
	v_lshl_add_u64 v[192:193], v[202:203], 0, s[26:27]
	s_add_i32 m0, s56, 0x2000
	s_nop 0
	global_load_lds_dwordx4 v[192:193], off
	v_lshl_add_u64 v[192:193], v[204:205], 0, s[26:27]
	s_mov_b32 m0, s87
	s_nop 0
	global_load_lds_dwordx4 v[192:193], off
	v_lshl_add_u64 v[192:193], v[224:225], 0, s[26:27]
	s_mov_b32 m0, s88
	s_nop 0
	global_load_lds_dwordx4 v[192:193], off
	s_waitcnt vmcnt(8)
	s_waitcnt lgkmcnt(0)
	s_barrier
	s_setprio 1
	s_waitcnt lgkmcnt(0)
	v_mfma_f32_16x16x32_bf16 v[62:65], v[134:137], v[176:179], v[62:65]
	v_mfma_f32_16x16x32_bf16 v[58:61], v[142:145], v[176:179], v[58:61]
	v_mfma_f32_16x16x32_bf16 v[46:49], v[134:137], v[188:191], v[46:49]
	v_mfma_f32_16x16x32_bf16 v[42:45], v[142:145], v[188:191], v[42:45]
	v_mfma_f32_16x16x32_bf16 v[30:33], v[134:137], v[212:215], v[30:33]
	v_mfma_f32_16x16x32_bf16 v[26:29], v[142:145], v[212:215], v[26:29]
	v_mfma_f32_16x16x32_bf16 v[14:17], v[134:137], v[220:223], v[14:17]
	v_mfma_f32_16x16x32_bf16 v[10:13], v[142:145], v[220:223], v[10:13]
	v_mfma_f32_16x16x32_bf16 v[62:65], v[138:141], v[184:187], v[62:65]
	v_mfma_f32_16x16x32_bf16 v[58:61], v[146:149], v[184:187], v[58:61]
	v_mfma_f32_16x16x32_bf16 v[46:49], v[138:141], v[208:211], v[46:49]
	v_mfma_f32_16x16x32_bf16 v[42:45], v[146:149], v[208:211], v[42:45]
	v_mfma_f32_16x16x32_bf16 v[30:33], v[138:141], v[216:219], v[30:33]
	v_mfma_f32_16x16x32_bf16 v[26:29], v[146:149], v[216:219], v[26:29]
	v_mfma_f32_16x16x32_bf16 v[14:17], v[138:141], v[236:239], v[14:17]
	v_mfma_f32_16x16x32_bf16 v[10:13], v[146:149], v[236:239], v[10:13]
	v_mfma_f32_16x16x32_bf16 v[54:57], v[150:153], v[176:179], v[54:57]
	v_mfma_f32_16x16x32_bf16 v[50:53], v[168:171], v[176:179], v[50:53]
	v_mfma_f32_16x16x32_bf16 v[38:41], v[150:153], v[188:191], v[38:41]
	v_mfma_f32_16x16x32_bf16 v[34:37], v[168:171], v[188:191], v[34:37]
	v_mfma_f32_16x16x32_bf16 v[22:25], v[150:153], v[212:215], v[22:25]
	v_mfma_f32_16x16x32_bf16 v[18:21], v[168:171], v[212:215], v[18:21]
	v_mfma_f32_16x16x32_bf16 v[6:9], v[150:153], v[220:223], v[6:9]
	v_mfma_f32_16x16x32_bf16 v[2:5], v[168:171], v[220:223], v[2:5]
	v_mfma_f32_16x16x32_bf16 v[54:57], v[154:157], v[184:187], v[54:57]
	v_mfma_f32_16x16x32_bf16 v[50:53], v[172:175], v[184:187], v[50:53]
	v_mfma_f32_16x16x32_bf16 v[38:41], v[154:157], v[208:211], v[38:41]
	v_mfma_f32_16x16x32_bf16 v[34:37], v[172:175], v[208:211], v[34:37]
	v_mfma_f32_16x16x32_bf16 v[22:25], v[154:157], v[216:219], v[22:25]
	v_mfma_f32_16x16x32_bf16 v[18:21], v[172:175], v[216:219], v[18:21]
	v_mfma_f32_16x16x32_bf16 v[6:9], v[154:157], v[236:239], v[6:9]
	v_mfma_f32_16x16x32_bf16 v[2:5], v[172:175], v[236:239], v[2:5]
	s_setprio 0
	s_barrier
	s_add_u32 s14, s14, 0x100
	s_addc_u32 s15, s15, 0
	s_add_u32 s58, s58, 0x100
	s_addc_u32 s59, s59, 0
	s_cmp_ge_i32 s93, s86
	s_mov_b32 s56, s93
	s_cbranch_scc0 .LBB0_132

; #define PG8_STAGE(bufoff, gbase, voff) do { _Pragma("unroll") for (int _i = 0; _i < 2; ++_i) \
;         __builtin_amdgcn_global_load_lds((const unsigned*)((const char*)(gbase) + (voff)[_i]), (PG8_LAS unsigned*)(lds + (bufoff) + ldsw + _i * 8192), 16, 0, 0); } while (0)
; #define PG8_LDA(dst, b, h) do { _Pragma("unroll") for (int m = 0; m < 4; ++m) _Pragma("unroll") for (int k = 0; k < 2; ++k) dst[m][k] = *(const PG8_LAS bf16x8*)(lds + PG8_SA(b, h) + aoff + m * 2048 + k * 1024); } while (0)
; #define PG8_LDB(dst, b, h) do { _Pragma("unroll") for (int n = 0; n < 2; ++n) _Pragma("unroll") for (int k = 0; k < 2; ++k) dst[n][k] = *(const PG8_LAS bf16x8*)(lds + PG8_SB(b, h) + boff + n * 2048 + k * 1024); } while (0)
; #define PG8_MMA(ai, bj, At, Bt) do { __builtin_amdgcn_s_setprio(1); _Pragma("unroll") for (int m = 0; m < 4; ++m) _Pragma("unroll") for (int n = 0; n < 2; ++n) _Pragma("unroll") for (int k = 0; k < 2; ++k) \
;         acc[ai][bj][m][n] = __builtin_amdgcn_mfma_f32_16x16x32_bf16(Bt[n][k], At[m][k], acc[ai][bj][m][n], 0, 0, 0); __builtin_amdgcn_s_setprio(0); } while (0)
; #define PG8_WAIT_V(n) asm volatile("s_waitcnt vmcnt(" #n ")" ::: "memory")
; #define PG8_WAIT_L(n) asm volatile("s_waitcnt lgkmcnt(" #n ")" ::: "memory")
; #define PG8_BAR __builtin_amdgcn_s_barrier()
; #define PG8_SCHED __builtin_amdgcn_sched_barrier(0)
; template <class Epi, class Sched, bool ALIGN_EPI = false, bool SP2 = false>
; __device__ __forceinline__ void gemm_phase(PG8_LAS unsigned char* lds, const Gemm g, const Sched& S, const Epi& E) {
;     ...
;             const char* a2 = last ? nA : cA + (size_t)(t + 2) * kstep; const char* b2 = last ? nB : cB + (size_t)(t + 2) * kstep;
;             const char* a3 = a2 + kstep; const char* b3 = b2 + kstep;
;             if (last && has_next) S.a_ready(nxt);
;             if constexpr (SP2) {
;             PG8_LDB(B0, 0, 0); PG8_LDB(B1, 0, 1); PG8_SCHED; PG8_LDA(At, 0, 0); PG8_STAGE(PG8_SA(1, 1), a1 + hstep, voffA);
;             PG8_WAIT_V(8); PG8_WAIT_L(0); PG8_BAR; PG8_MMA(0, 0, At, B0); PG8_MMA(0, 1, At, B1); PG8_BAR; PG8_SCHED;
;             PG8_LDA(At, 0, 1); PG8_STAGE(PG8_SB(0, 0), b2, voffB); PG8_STAGE(PG8_SB(0, 1), b2 + hstep, voffB); PG8_STAGE(PG8_SA(0, 0), a2, voffA);
.LBB0_344:
	s_add_i32 s77, s48, 2
	s_add_u32 s64, s14, 0x80
	s_addc_u32 s49, s15, 0
	s_add_i32 s66, 0, 0x10000
	s_cmp_eq_u32 s61, s48
	s_cselect_b32 s49, s43, s49
	s_cselect_b32 s48, s42, s64
	v_add_u32_e32 v0, s66, v153
	s_cselect_b32 s65, s47, s76
	s_cselect_b32 s64, s46, s51
	s_add_i32 s67, 0, 0x14000
	ds_read_b128 v[156:159], v0
	ds_read_b128 v[160:163], v0 offset:1024
	ds_read_b128 v[164:167], v0 offset:2048
	ds_read_b128 v[168:171], v0 offset:3072
	v_add_u32_e32 v0, s67, v153
	ds_read_b128 v[172:175], v0
	ds_read_b128 v[176:179], v0 offset:1024
	ds_read_b128 v[180:183], v0 offset:2048
	ds_read_b128 v[184:187], v0 offset:3072
	v_lshl_add_u64 v[150:151], s[14:15], 0, v[144:145]
	s_add_i32 m0, s54, 0xc000
	ds_read_b128 v[188:191], v154
	ds_read_b128 v[208:211], v154 offset:1024
	ds_read_b128 v[212:215], v154 offset:2048
	ds_read_b128 v[216:219], v154 offset:3072
	ds_read_b128 v[220:223], v154 offset:4096
	ds_read_b128 v[236:239], v154 offset:5120
	ds_read_b128 v[240:243], v154 offset:6144
	ds_read_b128 v[244:247], v154 offset:7168
	global_load_lds_dwordx4 v[150:151], off
	v_lshl_add_u64 v[150:151], s[14:15], 0, v[146:147]
	s_add_i32 m0, s54, 0xe000
	s_nop 0
	global_load_lds_dwordx4 v[150:151], off
	s_waitcnt vmcnt(8)
	s_waitcnt lgkmcnt(0)
	s_barrier
	s_setprio 1
	s_waitcnt lgkmcnt(0)
	v_mfma_f32_16x16x32_bf16 v[122:125], v[156:159], v[188:191], v[122:125]
	v_mfma_f32_16x16x32_bf16 v[126:129], v[164:167], v[188:191], v[126:129]
	v_mfma_f32_16x16x32_bf16 v[110:113], v[156:159], v[212:215], v[110:113]
	v_mfma_f32_16x16x32_bf16 v[106:109], v[164:167], v[212:215], v[106:109]
	v_mfma_f32_16x16x32_bf16 v[94:97], v[156:159], v[220:223], v[94:97]
	v_mfma_f32_16x16x32_bf16 v[90:93], v[164:167], v[220:223], v[90:93]
	v_mfma_f32_16x16x32_bf16 v[78:81], v[156:159], v[240:243], v[78:81]
	v_mfma_f32_16x16x32_bf16 v[74:77], v[164:167], v[240:243], v[74:77]
	v_mfma_f32_16x16x32_bf16 v[122:125], v[160:163], v[208:211], v[122:125]
	v_mfma_f32_16x16x32_bf16 v[126:129], v[168:171], v[208:211], v[126:129]
	v_mfma_f32_16x16x32_bf16 v[110:113], v[160:163], v[216:219], v[110:113]
	v_mfma_f32_16x16x32_bf16 v[106:109], v[168:171], v[216:219], v[106:109]
	v_mfma_f32_16x16x32_bf16 v[94:97], v[160:163], v[236:239], v[94:97]
	v_mfma_f32_16x16x32_bf16 v[90:93], v[168:171], v[236:239], v[90:93]
	v_mfma_f32_16x16x32_bf16 v[78:81], v[160:163], v[244:247], v[78:81]
	v_mfma_f32_16x16x32_bf16 v[74:77], v[168:171], v[244:247], v[74:77]
	v_mfma_f32_16x16x32_bf16 v[118:121], v[172:175], v[188:191], v[118:121]
	v_mfma_f32_16x16x32_bf16 v[114:117], v[180:183], v[188:191], v[114:117]
	v_mfma_f32_16x16x32_bf16 v[102:105], v[172:175], v[212:215], v[102:105]
	v_mfma_f32_16x16x32_bf16 v[98:101], v[180:183], v[212:215], v[98:101]
	v_mfma_f32_16x16x32_bf16 v[86:89], v[172:175], v[220:223], v[86:89]
	v_mfma_f32_16x16x32_bf16 v[82:85], v[180:183], v[220:223], v[82:85]
	v_mfma_f32_16x16x32_bf16 v[70:73], v[172:175], v[240:243], v[70:73]
	v_mfma_f32_16x16x32_bf16 v[66:69], v[180:183], v[240:243], v[66:69]
	v_mfma_f32_16x16x32_bf16 v[118:121], v[176:179], v[208:211], v[118:121]
	v_mfma_f32_16x16x32_bf16 v[114:117], v[184:187], v[208:211], v[114:117]
	v_mfma_f32_16x16x32_bf16 v[102:105], v[176:179], v[216:219], v[102:105]
	v_mfma_f32_16x16x32_bf16 v[98:101], v[184:187], v[216:219], v[98:101]
	v_mfma_f32_16x16x32_bf16 v[86:89], v[176:179], v[236:239], v[86:89]
	v_mfma_f32_16x16x32_bf16 v[82:85], v[184:187], v[236:239], v[82:85]
	v_mfma_f32_16x16x32_bf16 v[70:73], v[176:179], v[244:247], v[70:73]
	v_mfma_f32_16x16x32_bf16 v[66:69], v[184:187], v[244:247], v[66:69]
	s_setprio 0
	s_barrier
	s_add_i32 s66, s66, s53
	v_lshl_add_u64 v[150:151], s[64:65], 0, v[138:139]
	s_mov_b32 m0, s66
	ds_read_b128 v[188:191], v154 offset:16384
	ds_read_b128 v[208:211], v154 offset:17408
	ds_read_b128 v[212:215], v154 offset:18432
	ds_read_b128 v[216:219], v154 offset:19456
	ds_read_b128 v[220:223], v154 offset:20480
	ds_read_b128 v[236:239], v154 offset:21504
	ds_read_b128 v[240:243], v154 offset:22528
	ds_read_b128 v[244:247], v154 offset:23552
	global_load_lds_dwordx4 v[150:151], off
	s_add_i32 m0, s66, 0x2000
	v_lshl_add_u64 v[192:193], s[64:65], 0, v[134:135]
	s_add_u32 s64, s64, s4
	s_addc_u32 s65, s65, s5
	s_add_i32 s66, s67, s53
	global_load_lds_dwordx4 v[192:193], off
	v_lshl_add_u64 v[198:199], s[64:65], 0, v[138:139]
	s_mov_b32 m0, s66
	v_lshl_add_u64 v[200:201], s[64:65], 0, v[134:135]
	global_load_lds_dwordx4 v[198:199], off
	s_add_i32 m0, s66, 0x2000
	v_lshl_add_u64 v[202:203], s[48:49], 0, v[140:141]
	global_load_lds_dwordx4 v[200:201], off
	s_mov_b32 m0, s54
	v_lshl_add_u64 v[204:205], s[48:49], 0, v[136:137]
	global_load_lds_dwordx4 v[202:203], off
	s_mov_b32 m0, s55
	s_nop 0
	global_load_lds_dwordx4 v[204:205], off
	s_waitcnt vmcnt(8)
	s_waitcnt lgkmcnt(0)
	s_barrier
; #define PG8_STAGE(bufoff, gbase, voff) do { _Pragma("unroll") for (int _i = 0; _i < 2; ++_i) \
;         __builtin_amdgcn_global_load_lds((const unsigned*)((const char*)(gbase) + (voff)[_i]), (PG8_LAS unsigned*)(lds + (bufoff) + ldsw + _i * 8192), 16, 0, 0); } while (0)
; #define PG8_LDA(dst, b, h) do { _Pragma("unroll") for (int m = 0; m < 4; ++m) _Pragma("unroll") for (int k = 0; k < 2; ++k) dst[m][k] = *(const PG8_LAS bf16x8*)(lds + PG8_SA(b, h) + aoff + m * 2048 + k * 1024); } while (0)
; #define PG8_LDB(dst, b, h) do { _Pragma("unroll") for (int n = 0; n < 2; ++n) _Pragma("unroll") for (int k = 0; k < 2; ++k) dst[n][k] = *(const PG8_LAS bf16x8*)(lds + PG8_SB(b, h) + boff + n * 2048 + k * 1024); } while (0)
; #define PG8_MMA(ai, bj, At, Bt) do { __builtin_amdgcn_s_setprio(1); _Pragma("unroll") for (int m = 0; m < 4; ++m) _Pragma("unroll") for (int n = 0; n < 2; ++n) _Pragma("unroll") for (int k = 0; k < 2; ++k) \
;         acc[ai][bj][m][n] = __builtin_amdgcn_mfma_f32_16x16x32_bf16(Bt[n][k], At[m][k], acc[ai][bj][m][n], 0, 0, 0); __builtin_amdgcn_s_setprio(0); } while (0)
; #define PG8_WAIT_V(n) asm volatile("s_waitcnt vmcnt(" #n ")" ::: "memory")
; #define PG8_WAIT_L(n) asm volatile("s_waitcnt lgkmcnt(" #n ")" ::: "memory")
; #define PG8_BAR __builtin_amdgcn_s_barrier()
; #define PG8_SCHED __builtin_amdgcn_sched_barrier(0)
; template <class Epi, class Sched, bool ALIGN_EPI = false, bool SP2 = false>
; __device__ __forceinline__ void gemm_phase(PG8_LAS unsigned char* lds, const Gemm g, const Sched& S, const Epi& E) {
;     ...
;             PG8_WAIT_V(8); PG8_WAIT_L(0); PG8_BAR; PG8_MMA(1, 0, At, B0); PG8_MMA(1, 1, At, B1); PG8_BAR; PG8_SCHED;
;             PG8_LDB(B0, 1, 0); PG8_LDB(B1, 1, 1); PG8_SCHED; PG8_LDA(At, 1, 0); PG8_STAGE(PG8_SA(0, 1), a2 + hstep, voffA);
;             PG8_WAIT_V(8); PG8_WAIT_L(0); PG8_BAR; PG8_MMA(0, 0, At, B0); PG8_MMA(0, 1, At, B1); PG8_BAR; PG8_SCHED;
	s_setprio 1
	s_waitcnt lgkmcnt(0)
	v_mfma_f32_16x16x32_bf16 v[62:65], v[156:159], v[188:191], v[62:65]
	v_mfma_f32_16x16x32_bf16 v[58:61], v[164:167], v[188:191], v[58:61]
	v_mfma_f32_16x16x32_bf16 v[46:49], v[156:159], v[212:215], v[46:49]
	v_mfma_f32_16x16x32_bf16 v[42:45], v[164:167], v[212:215], v[42:45]
	v_mfma_f32_16x16x32_bf16 v[30:33], v[156:159], v[220:223], v[30:33]
	v_mfma_f32_16x16x32_bf16 v[26:29], v[164:167], v[220:223], v[26:29]
	v_mfma_f32_16x16x32_bf16 v[14:17], v[156:159], v[240:243], v[14:17]
	v_mfma_f32_16x16x32_bf16 v[10:13], v[164:167], v[240:243], v[10:13]
	v_mfma_f32_16x16x32_bf16 v[62:65], v[160:163], v[208:211], v[62:65]
	v_mfma_f32_16x16x32_bf16 v[58:61], v[168:171], v[208:211], v[58:61]
	v_mfma_f32_16x16x32_bf16 v[46:49], v[160:163], v[216:219], v[46:49]
	v_mfma_f32_16x16x32_bf16 v[42:45], v[168:171], v[216:219], v[42:45]
	v_mfma_f32_16x16x32_bf16 v[30:33], v[160:163], v[236:239], v[30:33]
	v_mfma_f32_16x16x32_bf16 v[26:29], v[168:171], v[236:239], v[26:29]
	v_mfma_f32_16x16x32_bf16 v[14:17], v[160:163], v[244:247], v[14:17]
	v_mfma_f32_16x16x32_bf16 v[10:13], v[168:171], v[244:247], v[10:13]
	v_mfma_f32_16x16x32_bf16 v[54:57], v[172:175], v[188:191], v[54:57]
	v_mfma_f32_16x16x32_bf16 v[50:53], v[180:183], v[188:191], v[50:53]
	v_mfma_f32_16x16x32_bf16 v[38:41], v[172:175], v[212:215], v[38:41]
	v_mfma_f32_16x16x32_bf16 v[34:37], v[180:183], v[212:215], v[34:37]
	v_mfma_f32_16x16x32_bf16 v[22:25], v[172:175], v[220:223], v[22:25]
	v_mfma_f32_16x16x32_bf16 v[18:21], v[180:183], v[220:223], v[18:21]
	v_mfma_f32_16x16x32_bf16 v[6:9], v[172:175], v[240:243], v[6:9]
	v_mfma_f32_16x16x32_bf16 v[2:5], v[180:183], v[240:243], v[2:5]
	v_mfma_f32_16x16x32_bf16 v[54:57], v[176:179], v[208:211], v[54:57]
	v_mfma_f32_16x16x32_bf16 v[50:53], v[184:187], v[208:211], v[50:53]
	v_mfma_f32_16x16x32_bf16 v[38:41], v[176:179], v[216:219], v[38:41]
	v_mfma_f32_16x16x32_bf16 v[34:37], v[184:187], v[216:219], v[34:37]
	v_mfma_f32_16x16x32_bf16 v[22:25], v[176:179], v[236:239], v[22:25]
	v_mfma_f32_16x16x32_bf16 v[18:21], v[184:187], v[236:239], v[18:21]
	v_mfma_f32_16x16x32_bf16 v[6:9], v[176:179], v[244:247], v[6:9]
	v_mfma_f32_16x16x32_bf16 v[2:5], v[184:187], v[244:247], v[2:5]
	s_setprio 0
	s_barrier
	s_add_i32 s64, 0, 0x18000
	v_add_u32_e32 v0, s64, v153
	s_add_i32 s65, 0, 0x1c000
	ds_read_b128 v[156:159], v0
	ds_read_b128 v[160:163], v0 offset:1024
	ds_read_b128 v[164:167], v0 offset:2048
	ds_read_b128 v[168:171], v0 offset:3072
	v_add_u32_e32 v0, s65, v153
	ds_read_b128 v[172:175], v0
	ds_read_b128 v[176:179], v0 offset:1024
	ds_read_b128 v[180:183], v0 offset:2048
	ds_read_b128 v[184:187], v0 offset:3072
	s_add_u32 s48, s48, s4
	s_addc_u32 s49, s49, s5
	s_mov_b32 m0, s56
	v_lshl_add_u64 v[224:225], s[48:49], 0, v[140:141]
	ds_read_b128 v[188:191], v154 offset:32768
	ds_read_b128 v[208:211], v154 offset:33792
	ds_read_b128 v[212:215], v154 offset:34816
	ds_read_b128 v[216:219], v154 offset:35840
	ds_read_b128 v[220:223], v154 offset:36864
	ds_read_b128 v[236:239], v154 offset:37888
	ds_read_b128 v[240:243], v154 offset:38912
	ds_read_b128 v[244:247], v154 offset:39936
	global_load_lds_dwordx4 v[224:225], off
	v_lshl_add_u64 v[224:225], s[48:49], 0, v[136:137]
	s_mov_b32 m0, s57
	s_nop 0
	global_load_lds_dwordx4 v[224:225], off
	s_waitcnt vmcnt(8)
	s_waitcnt lgkmcnt(0)
	s_barrier
	s_setprio 1
	s_waitcnt lgkmcnt(0)
	v_mfma_f32_16x16x32_bf16 v[122:125], v[156:159], v[188:191], v[122:125]
	v_mfma_f32_16x16x32_bf16 v[126:129], v[164:167], v[188:191], v[126:129]
	v_mfma_f32_16x16x32_bf16 v[110:113], v[156:159], v[212:215], v[110:113]
	v_mfma_f32_16x16x32_bf16 v[106:109], v[164:167], v[212:215], v[106:109]
	v_mfma_f32_16x16x32_bf16 v[94:97], v[156:159], v[220:223], v[94:97]
	v_mfma_f32_16x16x32_bf16 v[90:93], v[164:167], v[220:223], v[90:93]
	v_mfma_f32_16x16x32_bf16 v[78:81], v[156:159], v[240:243], v[78:81]
	v_mfma_f32_16x16x32_bf16 v[74:77], v[164:167], v[240:243], v[74:77]
	v_mfma_f32_16x16x32_bf16 v[122:125], v[160:163], v[208:211], v[122:125]
	v_mfma_f32_16x16x32_bf16 v[126:129], v[168:171], v[208:211], v[126:129]
	v_mfma_f32_16x16x32_bf16 v[110:113], v[160:163], v[216:219], v[110:113]
	v_mfma_f32_16x16x32_bf16 v[106:109], v[168:171], v[216:219], v[106:109]
	v_mfma_f32_16x16x32_bf16 v[94:97], v[160:163], v[236:239], v[94:97]
	v_mfma_f32_16x16x32_bf16 v[90:93], v[168:171], v[236:239], v[90:93]
	v_mfma_f32_16x16x32_bf16 v[78:81], v[160:163], v[244:247], v[78:81]
	v_mfma_f32_16x16x32_bf16 v[74:77], v[168:171], v[244:247], v[74:77]
	v_mfma_f32_16x16x32_bf16 v[118:121], v[172:175], v[188:191], v[118:121]
	v_mfma_f32_16x16x32_bf16 v[114:117], v[180:183], v[188:191], v[114:117]
	v_mfma_f32_16x16x32_bf16 v[102:105], v[172:175], v[212:215], v[102:105]
	v_mfma_f32_16x16x32_bf16 v[98:101], v[180:183], v[212:215], v[98:101]
	v_mfma_f32_16x16x32_bf16 v[86:89], v[172:175], v[220:223], v[86:89]
	v_mfma_f32_16x16x32_bf16 v[82:85], v[180:183], v[220:223], v[82:85]
	v_mfma_f32_16x16x32_bf16 v[70:73], v[172:175], v[240:243], v[70:73]
	v_mfma_f32_16x16x32_bf16 v[66:69], v[180:183], v[240:243], v[66:69]
	v_mfma_f32_16x16x32_bf16 v[118:121], v[176:179], v[208:211], v[118:121]
	v_mfma_f32_16x16x32_bf16 v[114:117], v[184:187], v[208:211], v[114:117]
	v_mfma_f32_16x16x32_bf16 v[102:105], v[176:179], v[216:219], v[102:105]
	v_mfma_f32_16x16x32_bf16 v[98:101], v[184:187], v[216:219], v[98:101]
	v_mfma_f32_16x16x32_bf16 v[86:89], v[176:179], v[236:239], v[86:89]
	v_mfma_f32_16x16x32_bf16 v[82:85], v[184:187], v[236:239], v[82:85]
	v_mfma_f32_16x16x32_bf16 v[70:73], v[176:179], v[244:247], v[70:73]
	v_mfma_f32_16x16x32_bf16 v[66:69], v[184:187], v[244:247], v[66:69]
	s_setprio 0
	s_barrier
; #define PG8_STAGE(bufoff, gbase, voff) do { _Pragma("unroll") for (int _i = 0; _i < 2; ++_i) \
;         __builtin_amdgcn_global_load_lds((const unsigned*)((const char*)(gbase) + (voff)[_i]), (PG8_LAS unsigned*)(lds + (bufoff) + ldsw + _i * 8192), 16, 0, 0); } while (0)
; #define PG8_LDA(dst, b, h) do { _Pragma("unroll") for (int m = 0; m < 4; ++m) _Pragma("unroll") for (int k = 0; k < 2; ++k) dst[m][k] = *(const PG8_LAS bf16x8*)(lds + PG8_SA(b, h) + aoff + m * 2048 + k * 1024); } while (0)
; #define PG8_MMA(ai, bj, At, Bt) do { __builtin_amdgcn_s_setprio(1); _Pragma("unroll") for (int m = 0; m < 4; ++m) _Pragma("unroll") for (int n = 0; n < 2; ++n) _Pragma("unroll") for (int k = 0; k < 2; ++k) \
;         acc[ai][bj][m][n] = __builtin_amdgcn_mfma_f32_16x16x32_bf16(Bt[n][k], At[m][k], acc[ai][bj][m][n], 0, 0, 0); __builtin_amdgcn_s_setprio(0); } while (0)
; #define PG8_WAIT_V(n) asm volatile("s_waitcnt vmcnt(" #n ")" ::: "memory")
; #define PG8_WAIT_L(n) asm volatile("s_waitcnt lgkmcnt(" #n ")" ::: "memory")
; #define PG8_BAR __builtin_amdgcn_s_barrier()
; #define PG8_SCHED __builtin_amdgcn_sched_barrier(0)
; template <class Epi, class Sched, bool ALIGN_EPI = false, bool SP2 = false>
; __device__ __forceinline__ void gemm_phase(PG8_LAS unsigned char* lds, const Gemm g, const Sched& S, const Epi& E) {
;     ...
;             PG8_LDA(At, 1, 1); PG8_STAGE(PG8_SB(1, 0), b3, voffB); PG8_STAGE(PG8_SB(1, 1), b3 + hstep, voffB); PG8_STAGE(PG8_SA(1, 0), a3, voffA);
;             PG8_WAIT_V(8); PG8_WAIT_L(0); PG8_BAR; PG8_MMA(1, 0, At, B0); PG8_MMA(1, 1, At, B1); PG8_BAR; PG8_SCHED;
	s_add_i32 s48, s64, s53
	v_lshl_add_u64 v[150:151], v[150:151], 0, s[26:27]
	s_mov_b32 m0, s48
	ds_read_b128 v[188:191], v154 offset:49152
	ds_read_b128 v[208:211], v154 offset:50176
	ds_read_b128 v[212:215], v154 offset:51200
	ds_read_b128 v[216:219], v154 offset:52224
	ds_read_b128 v[220:223], v154 offset:53248
	ds_read_b128 v[236:239], v154 offset:54272
	ds_read_b128 v[240:243], v154 offset:55296
	ds_read_b128 v[244:247], v154 offset:56320
	global_load_lds_dwordx4 v[150:151], off
	v_lshl_add_u64 v[150:151], v[192:193], 0, s[26:27]
	s_add_i32 m0, s48, 0x2000
	s_add_i32 s48, s65, s53
	global_load_lds_dwordx4 v[150:151], off
	v_lshl_add_u64 v[150:151], v[198:199], 0, s[26:27]
	s_mov_b32 m0, s48
	s_nop 0
	global_load_lds_dwordx4 v[150:151], off
	v_lshl_add_u64 v[150:151], v[200:201], 0, s[26:27]
	s_add_i32 m0, s48, 0x2000
	s_nop 0
	global_load_lds_dwordx4 v[150:151], off
	v_lshl_add_u64 v[150:151], v[202:203], 0, s[26:27]
	s_mov_b32 m0, s59
	s_nop 0
	global_load_lds_dwordx4 v[150:151], off
	v_lshl_add_u64 v[150:151], v[204:205], 0, s[26:27]
	s_mov_b32 m0, s60
	s_nop 0
	global_load_lds_dwordx4 v[150:151], off
	s_waitcnt vmcnt(8)
	s_waitcnt lgkmcnt(0)
	s_barrier
	s_setprio 1
	s_waitcnt lgkmcnt(0)
	v_mfma_f32_16x16x32_bf16 v[62:65], v[156:159], v[188:191], v[62:65]
	v_mfma_f32_16x16x32_bf16 v[58:61], v[164:167], v[188:191], v[58:61]
	v_mfma_f32_16x16x32_bf16 v[46:49], v[156:159], v[212:215], v[46:49]
	v_mfma_f32_16x16x32_bf16 v[42:45], v[164:167], v[212:215], v[42:45]
	v_mfma_f32_16x16x32_bf16 v[30:33], v[156:159], v[220:223], v[30:33]
	v_mfma_f32_16x16x32_bf16 v[26:29], v[164:167], v[220:223], v[26:29]
	v_mfma_f32_16x16x32_bf16 v[14:17], v[156:159], v[240:243], v[14:17]
	v_mfma_f32_16x16x32_bf16 v[10:13], v[164:167], v[240:243], v[10:13]
	v_mfma_f32_16x16x32_bf16 v[62:65], v[160:163], v[208:211], v[62:65]
	v_mfma_f32_16x16x32_bf16 v[58:61], v[168:171], v[208:211], v[58:61]
	v_mfma_f32_16x16x32_bf16 v[46:49], v[160:163], v[216:219], v[46:49]
	v_mfma_f32_16x16x32_bf16 v[42:45], v[168:171], v[216:219], v[42:45]
	v_mfma_f32_16x16x32_bf16 v[30:33], v[160:163], v[236:239], v[30:33]
	v_mfma_f32_16x16x32_bf16 v[26:29], v[168:171], v[236:239], v[26:29]
	v_mfma_f32_16x16x32_bf16 v[14:17], v[160:163], v[244:247], v[14:17]
	v_mfma_f32_16x16x32_bf16 v[10:13], v[168:171], v[244:247], v[10:13]
	v_mfma_f32_16x16x32_bf16 v[54:57], v[172:175], v[188:191], v[54:57]
	v_mfma_f32_16x16x32_bf16 v[50:53], v[180:183], v[188:191], v[50:53]
	v_mfma_f32_16x16x32_bf16 v[38:41], v[172:175], v[212:215], v[38:41]
	v_mfma_f32_16x16x32_bf16 v[34:37], v[180:183], v[212:215], v[34:37]
	v_mfma_f32_16x16x32_bf16 v[22:25], v[172:175], v[220:223], v[22:25]
	v_mfma_f32_16x16x32_bf16 v[18:21], v[180:183], v[220:223], v[18:21]
	v_mfma_f32_16x16x32_bf16 v[6:9], v[172:175], v[240:243], v[6:9]
	v_mfma_f32_16x16x32_bf16 v[2:5], v[180:183], v[240:243], v[2:5]
	v_mfma_f32_16x16x32_bf16 v[54:57], v[176:179], v[208:211], v[54:57]
	v_mfma_f32_16x16x32_bf16 v[50:53], v[184:187], v[208:211], v[50:53]
	v_mfma_f32_16x16x32_bf16 v[38:41], v[176:179], v[216:219], v[38:41]
	v_mfma_f32_16x16x32_bf16 v[34:37], v[184:187], v[216:219], v[34:37]
	v_mfma_f32_16x16x32_bf16 v[22:25], v[176:179], v[236:239], v[22:25]
	v_mfma_f32_16x16x32_bf16 v[18:21], v[184:187], v[236:239], v[18:21]
	v_mfma_f32_16x16x32_bf16 v[6:9], v[176:179], v[244:247], v[6:9]
	v_mfma_f32_16x16x32_bf16 v[2:5], v[184:187], v[244:247], v[2:5]
	s_setprio 0
	s_barrier
	s_add_u32 s14, s14, 0x100
	s_addc_u32 s15, s15, 0
	s_add_u32 s51, s51, 0x100
	s_addc_u32 s76, s76, 0
	s_cmp_ge_i32 s77, s58
	s_mov_b32 s48, s77
	s_cbranch_scc0 .LBB0_344

; #define PG8_STAGE(bufoff, gbase, voff) do { _Pragma("unroll") for (int _i = 0; _i < 2; ++_i) \
;         __builtin_amdgcn_global_load_lds((const unsigned*)((const char*)(gbase) + (voff)[_i]), (PG8_LAS unsigned*)(lds + (bufoff) + ldsw + _i * 8192), 16, 0, 0); } while (0)
; #define PG8_LDA(dst, b, h) do { _Pragma("unroll") for (int m = 0; m < 4; ++m) _Pragma("unroll") for (int k = 0; k < 2; ++k) dst[m][k] = *(const PG8_LAS bf16x8*)(lds + PG8_SA(b, h) + aoff + m * 2048 + k * 1024); } while (0)
; #define PG8_LDB(dst, b, h) do { _Pragma("unroll") for (int n = 0; n < 2; ++n) _Pragma("unroll") for (int k = 0; k < 2; ++k) dst[n][k] = *(const PG8_LAS bf16x8*)(lds + PG8_SB(b, h) + boff + n * 2048 + k * 1024); } while (0)
; #define PG8_MMA(ai, bj, At, Bt) do { __builtin_amdgcn_s_setprio(1); _Pragma("unroll") for (int m = 0; m < 4; ++m) _Pragma("unroll") for (int n = 0; n < 2; ++n) _Pragma("unroll") for (int k = 0; k < 2; ++k) \
;         acc[ai][bj][m][n] = __builtin_amdgcn_mfma_f32_16x16x32_bf16(Bt[n][k], At[m][k], acc[ai][bj][m][n], 0, 0, 0); __builtin_amdgcn_s_setprio(0); } while (0)
; #define PG8_WAIT_V(n) asm volatile("s_waitcnt vmcnt(" #n ")" ::: "memory")
; #define PG8_WAIT_L(n) asm volatile("s_waitcnt lgkmcnt(" #n ")" ::: "memory")
; #define PG8_BAR __builtin_amdgcn_s_barrier()
; #define PG8_SCHED __builtin_amdgcn_sched_barrier(0)
; template <class Epi, class Sched, bool ALIGN_EPI = false, bool SP2 = false>
; __device__ __forceinline__ void gemm_phase(PG8_LAS unsigned char* lds, const Gemm g, const Sched& S, const Epi& E) {
;     ...
;             const char* a2 = last ? nA : cA + (size_t)(t + 2) * kstep; const char* b2 = last ? nB : cB + (size_t)(t + 2) * kstep;
;             const char* a3 = a2 + kstep; const char* b3 = b2 + kstep;
;             if (last && has_next) S.a_ready(nxt);
;             if constexpr (SP2) {
;             PG8_LDB(B0, 0, 0); PG8_LDB(B1, 0, 1); PG8_SCHED; PG8_LDA(At, 0, 0); PG8_STAGE(PG8_SA(1, 1), a1 + hstep, voffA);
;             PG8_WAIT_V(8); PG8_WAIT_L(0); PG8_BAR; PG8_MMA(0, 0, At, B0); PG8_MMA(0, 1, At, B1); PG8_BAR; PG8_SCHED;
;             PG8_LDA(At, 0, 1); PG8_STAGE(PG8_SB(0, 0), b2, voffB); PG8_STAGE(PG8_SB(0, 1), b2 + hstep, voffB); PG8_STAGE(PG8_SA(0, 0), a2, voffA);
.LBB0_368:
	s_add_i32 s52, s42, 2
	s_add_u32 s53, s14, 0x80
	s_addc_u32 s43, s15, 0
	s_add_i32 s56, 0, 0x10000
	s_cmp_eq_u32 s77, s42
	s_cselect_b32 s43, s47, s43
	s_cselect_b32 s42, s46, s53
	v_add_u32_e32 v0, s56, v159
	s_cselect_b32 s55, s49, s51
	s_cselect_b32 s54, s48, s50
	s_add_i32 s53, 0, 0x14000
	ds_read_b128 v[146:149], v0
	ds_read_b128 v[150:153], v0 offset:1024
	ds_read_b128 v[154:157], v0 offset:2048
	ds_read_b128 v[162:165], v0 offset:3072
	v_add_u32_e32 v0, s53, v159
	ds_read_b128 v[166:169], v0
	ds_read_b128 v[170:173], v0 offset:1024
	ds_read_b128 v[174:177], v0 offset:2048
	ds_read_b128 v[178:181], v0 offset:3072
	v_lshl_add_u64 v[198:199], s[14:15], 0, v[142:143]
	s_add_i32 m0, s60, 0xc000
	ds_read_b128 v[182:185], v161
	ds_read_b128 v[186:189], v161 offset:1024
	ds_read_b128 v[190:193], v161 offset:2048
	ds_read_b128 v[208:211], v161 offset:3072
	ds_read_b128 v[212:215], v161 offset:4096
	ds_read_b128 v[216:219], v161 offset:5120
	ds_read_b128 v[220:223], v161 offset:6144
	ds_read_b128 v[236:239], v161 offset:7168
	global_load_lds_dwordx4 v[198:199], off
	v_lshl_add_u64 v[198:199], s[14:15], 0, v[144:145]
	s_add_i32 m0, s60, 0xe000
	s_nop 0
	global_load_lds_dwordx4 v[198:199], off
	s_waitcnt vmcnt(8)
	s_waitcnt lgkmcnt(0)
	s_barrier
	s_setprio 1
	s_waitcnt lgkmcnt(0)
	v_mfma_f32_16x16x32_bf16 v[122:125], v[146:149], v[182:185], v[122:125]
	v_mfma_f32_16x16x32_bf16 v[126:129], v[154:157], v[182:185], v[126:129]
	v_mfma_f32_16x16x32_bf16 v[110:113], v[146:149], v[190:193], v[110:113]
	v_mfma_f32_16x16x32_bf16 v[106:109], v[154:157], v[190:193], v[106:109]
	v_mfma_f32_16x16x32_bf16 v[94:97], v[146:149], v[212:215], v[94:97]
	v_mfma_f32_16x16x32_bf16 v[90:93], v[154:157], v[212:215], v[90:93]
	v_mfma_f32_16x16x32_bf16 v[78:81], v[146:149], v[220:223], v[78:81]
	v_mfma_f32_16x16x32_bf16 v[74:77], v[154:157], v[220:223], v[74:77]
	v_mfma_f32_16x16x32_bf16 v[122:125], v[150:153], v[186:189], v[122:125]
	v_mfma_f32_16x16x32_bf16 v[126:129], v[162:165], v[186:189], v[126:129]
	v_mfma_f32_16x16x32_bf16 v[110:113], v[150:153], v[208:211], v[110:113]
	v_mfma_f32_16x16x32_bf16 v[106:109], v[162:165], v[208:211], v[106:109]
	v_mfma_f32_16x16x32_bf16 v[94:97], v[150:153], v[216:219], v[94:97]
	v_mfma_f32_16x16x32_bf16 v[90:93], v[162:165], v[216:219], v[90:93]
	v_mfma_f32_16x16x32_bf16 v[78:81], v[150:153], v[236:239], v[78:81]
	v_mfma_f32_16x16x32_bf16 v[74:77], v[162:165], v[236:239], v[74:77]
	v_mfma_f32_16x16x32_bf16 v[118:121], v[166:169], v[182:185], v[118:121]
	v_mfma_f32_16x16x32_bf16 v[114:117], v[174:177], v[182:185], v[114:117]
	v_mfma_f32_16x16x32_bf16 v[102:105], v[166:169], v[190:193], v[102:105]
	v_mfma_f32_16x16x32_bf16 v[98:101], v[174:177], v[190:193], v[98:101]
	v_mfma_f32_16x16x32_bf16 v[86:89], v[166:169], v[212:215], v[86:89]
	v_mfma_f32_16x16x32_bf16 v[82:85], v[174:177], v[212:215], v[82:85]
	v_mfma_f32_16x16x32_bf16 v[70:73], v[166:169], v[220:223], v[70:73]
	v_mfma_f32_16x16x32_bf16 v[66:69], v[174:177], v[220:223], v[66:69]
	v_mfma_f32_16x16x32_bf16 v[118:121], v[170:173], v[186:189], v[118:121]
	v_mfma_f32_16x16x32_bf16 v[114:117], v[178:181], v[186:189], v[114:117]
	v_mfma_f32_16x16x32_bf16 v[102:105], v[170:173], v[208:211], v[102:105]
	v_mfma_f32_16x16x32_bf16 v[98:101], v[178:181], v[208:211], v[98:101]
	v_mfma_f32_16x16x32_bf16 v[86:89], v[170:173], v[216:219], v[86:89]
	v_mfma_f32_16x16x32_bf16 v[82:85], v[178:181], v[216:219], v[82:85]
	v_mfma_f32_16x16x32_bf16 v[70:73], v[170:173], v[236:239], v[70:73]
	v_mfma_f32_16x16x32_bf16 v[66:69], v[178:181], v[236:239], v[66:69]
	s_setprio 0
	s_barrier
	s_add_i32 s56, s56, s59
	v_lshl_add_u64 v[198:199], s[54:55], 0, v[138:139]
	s_mov_b32 m0, s56
	ds_read_b128 v[182:185], v161 offset:16384
	ds_read_b128 v[186:189], v161 offset:17408
	ds_read_b128 v[190:193], v161 offset:18432
	ds_read_b128 v[208:211], v161 offset:19456
	ds_read_b128 v[212:215], v161 offset:20480
	ds_read_b128 v[216:219], v161 offset:21504
	ds_read_b128 v[220:223], v161 offset:22528
	ds_read_b128 v[236:239], v161 offset:23552
	global_load_lds_dwordx4 v[198:199], off
	s_add_i32 m0, s56, 0x2000
	v_lshl_add_u64 v[200:201], s[54:55], 0, v[134:135]
	s_add_u32 s54, s54, s4
	s_addc_u32 s55, s55, s5
	s_add_i32 s53, s53, s59
	global_load_lds_dwordx4 v[200:201], off
	v_lshl_add_u64 v[202:203], s[54:55], 0, v[138:139]
	s_mov_b32 m0, s53
	v_lshl_add_u64 v[204:205], s[54:55], 0, v[134:135]
	global_load_lds_dwordx4 v[202:203], off
	s_add_i32 m0, s53, 0x2000
	v_lshl_add_u64 v[224:225], s[42:43], 0, v[140:141]
	global_load_lds_dwordx4 v[204:205], off
	s_mov_b32 m0, s60
	v_lshl_add_u64 v[228:229], s[42:43], 0, v[136:137]
	global_load_lds_dwordx4 v[224:225], off
	s_mov_b32 m0, s61
	s_nop 0
	global_load_lds_dwordx4 v[228:229], off
	s_waitcnt vmcnt(8)
	s_waitcnt lgkmcnt(0)
	s_barrier
; #define PG8_STAGE(bufoff, gbase, voff) do { _Pragma("unroll") for (int _i = 0; _i < 2; ++_i) \
;         __builtin_amdgcn_global_load_lds((const unsigned*)((const char*)(gbase) + (voff)[_i]), (PG8_LAS unsigned*)(lds + (bufoff) + ldsw + _i * 8192), 16, 0, 0); } while (0)
; #define PG8_LDA(dst, b, h) do { _Pragma("unroll") for (int m = 0; m < 4; ++m) _Pragma("unroll") for (int k = 0; k < 2; ++k) dst[m][k] = *(const PG8_LAS bf16x8*)(lds + PG8_SA(b, h) + aoff + m * 2048 + k * 1024); } while (0)
; #define PG8_LDB(dst, b, h) do { _Pragma("unroll") for (int n = 0; n < 2; ++n) _Pragma("unroll") for (int k = 0; k < 2; ++k) dst[n][k] = *(const PG8_LAS bf16x8*)(lds + PG8_SB(b, h) + boff + n * 2048 + k * 1024); } while (0)
; #define PG8_MMA(ai, bj, At, Bt) do { __builtin_amdgcn_s_setprio(1); _Pragma("unroll") for (int m = 0; m < 4; ++m) _Pragma("unroll") for (int n = 0; n < 2; ++n) _Pragma("unroll") for (int k = 0; k < 2; ++k) \
;         acc[ai][bj][m][n] = __builtin_amdgcn_mfma_f32_16x16x32_bf16(Bt[n][k], At[m][k], acc[ai][bj][m][n], 0, 0, 0); __builtin_amdgcn_s_setprio(0); } while (0)
; #define PG8_WAIT_V(n) asm volatile("s_waitcnt vmcnt(" #n ")" ::: "memory")
; #define PG8_WAIT_L(n) asm volatile("s_waitcnt lgkmcnt(" #n ")" ::: "memory")
; #define PG8_BAR __builtin_amdgcn_s_barrier()
; #define PG8_SCHED __builtin_amdgcn_sched_barrier(0)
; template <class Epi, class Sched, bool ALIGN_EPI = false, bool SP2 = false>
; __device__ __forceinline__ void gemm_phase(PG8_LAS unsigned char* lds, const Gemm g, const Sched& S, const Epi& E) {
;     ...
;             PG8_WAIT_V(8); PG8_WAIT_L(0); PG8_BAR; PG8_MMA(1, 0, At, B0); PG8_MMA(1, 1, At, B1); PG8_BAR; PG8_SCHED;
;             PG8_LDB(B0, 1, 0); PG8_LDB(B1, 1, 1); PG8_SCHED; PG8_LDA(At, 1, 0); PG8_STAGE(PG8_SA(0, 1), a2 + hstep, voffA);
;             PG8_WAIT_V(8); PG8_WAIT_L(0); PG8_BAR; PG8_MMA(0, 0, At, B0); PG8_MMA(0, 1, At, B1); PG8_BAR; PG8_SCHED;
	s_setprio 1
	s_waitcnt lgkmcnt(0)
	v_mfma_f32_16x16x32_bf16 v[62:65], v[146:149], v[182:185], v[62:65]
	v_mfma_f32_16x16x32_bf16 v[58:61], v[154:157], v[182:185], v[58:61]
	v_mfma_f32_16x16x32_bf16 v[46:49], v[146:149], v[190:193], v[46:49]
	v_mfma_f32_16x16x32_bf16 v[42:45], v[154:157], v[190:193], v[42:45]
	v_mfma_f32_16x16x32_bf16 v[30:33], v[146:149], v[212:215], v[30:33]
	v_mfma_f32_16x16x32_bf16 v[26:29], v[154:157], v[212:215], v[26:29]
	v_mfma_f32_16x16x32_bf16 v[14:17], v[146:149], v[220:223], v[14:17]
	v_mfma_f32_16x16x32_bf16 v[10:13], v[154:157], v[220:223], v[10:13]
	v_mfma_f32_16x16x32_bf16 v[62:65], v[150:153], v[186:189], v[62:65]
	v_mfma_f32_16x16x32_bf16 v[58:61], v[162:165], v[186:189], v[58:61]
	v_mfma_f32_16x16x32_bf16 v[46:49], v[150:153], v[208:211], v[46:49]
	v_mfma_f32_16x16x32_bf16 v[42:45], v[162:165], v[208:211], v[42:45]
	v_mfma_f32_16x16x32_bf16 v[30:33], v[150:153], v[216:219], v[30:33]
	v_mfma_f32_16x16x32_bf16 v[26:29], v[162:165], v[216:219], v[26:29]
	v_mfma_f32_16x16x32_bf16 v[14:17], v[150:153], v[236:239], v[14:17]
	v_mfma_f32_16x16x32_bf16 v[10:13], v[162:165], v[236:239], v[10:13]
	v_mfma_f32_16x16x32_bf16 v[54:57], v[166:169], v[182:185], v[54:57]
	v_mfma_f32_16x16x32_bf16 v[50:53], v[174:177], v[182:185], v[50:53]
	v_mfma_f32_16x16x32_bf16 v[38:41], v[166:169], v[190:193], v[38:41]
	v_mfma_f32_16x16x32_bf16 v[34:37], v[174:177], v[190:193], v[34:37]
	v_mfma_f32_16x16x32_bf16 v[22:25], v[166:169], v[212:215], v[22:25]
	v_mfma_f32_16x16x32_bf16 v[18:21], v[174:177], v[212:215], v[18:21]
	v_mfma_f32_16x16x32_bf16 v[6:9], v[166:169], v[220:223], v[6:9]
	v_mfma_f32_16x16x32_bf16 v[2:5], v[174:177], v[220:223], v[2:5]
	v_mfma_f32_16x16x32_bf16 v[54:57], v[170:173], v[186:189], v[54:57]
	v_mfma_f32_16x16x32_bf16 v[50:53], v[178:181], v[186:189], v[50:53]
	v_mfma_f32_16x16x32_bf16 v[38:41], v[170:173], v[208:211], v[38:41]
	v_mfma_f32_16x16x32_bf16 v[34:37], v[178:181], v[208:211], v[34:37]
	v_mfma_f32_16x16x32_bf16 v[22:25], v[170:173], v[216:219], v[22:25]
	v_mfma_f32_16x16x32_bf16 v[18:21], v[178:181], v[216:219], v[18:21]
	v_mfma_f32_16x16x32_bf16 v[6:9], v[170:173], v[236:239], v[6:9]
	v_mfma_f32_16x16x32_bf16 v[2:5], v[178:181], v[236:239], v[2:5]
	s_setprio 0
	s_barrier
	s_add_i32 s53, 0, 0x18000
	v_add_u32_e32 v0, s53, v159
	s_add_i32 s54, 0, 0x1c000
	ds_read_b128 v[146:149], v0
	ds_read_b128 v[150:153], v0 offset:1024
	ds_read_b128 v[154:157], v0 offset:2048
	ds_read_b128 v[162:165], v0 offset:3072
	v_add_u32_e32 v0, s54, v159
	ds_read_b128 v[166:169], v0
	ds_read_b128 v[170:173], v0 offset:1024
	ds_read_b128 v[174:177], v0 offset:2048
	ds_read_b128 v[178:181], v0 offset:3072
	s_add_u32 s42, s42, s4
	s_addc_u32 s43, s43, s5
	s_mov_b32 m0, s72
	v_lshl_add_u64 v[240:241], s[42:43], 0, v[140:141]
	ds_read_b128 v[182:185], v161 offset:32768
	ds_read_b128 v[186:189], v161 offset:33792
	ds_read_b128 v[190:193], v161 offset:34816
	ds_read_b128 v[208:211], v161 offset:35840
	ds_read_b128 v[212:215], v161 offset:36864
	ds_read_b128 v[216:219], v161 offset:37888
	ds_read_b128 v[220:223], v161 offset:38912
	ds_read_b128 v[236:239], v161 offset:39936
	global_load_lds_dwordx4 v[240:241], off
	v_lshl_add_u64 v[240:241], s[42:43], 0, v[136:137]
	s_mov_b32 m0, s73
	s_nop 0
	global_load_lds_dwordx4 v[240:241], off
	s_waitcnt vmcnt(8)
	s_waitcnt lgkmcnt(0)
	s_barrier
	s_setprio 1
	s_waitcnt lgkmcnt(0)
	v_mfma_f32_16x16x32_bf16 v[122:125], v[146:149], v[182:185], v[122:125]
	v_mfma_f32_16x16x32_bf16 v[126:129], v[154:157], v[182:185], v[126:129]
	v_mfma_f32_16x16x32_bf16 v[110:113], v[146:149], v[190:193], v[110:113]
	v_mfma_f32_16x16x32_bf16 v[106:109], v[154:157], v[190:193], v[106:109]
	v_mfma_f32_16x16x32_bf16 v[94:97], v[146:149], v[212:215], v[94:97]
	v_mfma_f32_16x16x32_bf16 v[90:93], v[154:157], v[212:215], v[90:93]
	v_mfma_f32_16x16x32_bf16 v[78:81], v[146:149], v[220:223], v[78:81]
	v_mfma_f32_16x16x32_bf16 v[74:77], v[154:157], v[220:223], v[74:77]
	v_mfma_f32_16x16x32_bf16 v[122:125], v[150:153], v[186:189], v[122:125]
	v_mfma_f32_16x16x32_bf16 v[126:129], v[162:165], v[186:189], v[126:129]
	v_mfma_f32_16x16x32_bf16 v[110:113], v[150:153], v[208:211], v[110:113]
	v_mfma_f32_16x16x32_bf16 v[106:109], v[162:165], v[208:211], v[106:109]
	v_mfma_f32_16x16x32_bf16 v[94:97], v[150:153], v[216:219], v[94:97]
	v_mfma_f32_16x16x32_bf16 v[90:93], v[162:165], v[216:219], v[90:93]
	v_mfma_f32_16x16x32_bf16 v[78:81], v[150:153], v[236:239], v[78:81]
	v_mfma_f32_16x16x32_bf16 v[74:77], v[162:165], v[236:239], v[74:77]
	v_mfma_f32_16x16x32_bf16 v[118:121], v[166:169], v[182:185], v[118:121]
	v_mfma_f32_16x16x32_bf16 v[114:117], v[174:177], v[182:185], v[114:117]
	v_mfma_f32_16x16x32_bf16 v[102:105], v[166:169], v[190:193], v[102:105]
	v_mfma_f32_16x16x32_bf16 v[98:101], v[174:177], v[190:193], v[98:101]
	v_mfma_f32_16x16x32_bf16 v[86:89], v[166:169], v[212:215], v[86:89]
	v_mfma_f32_16x16x32_bf16 v[82:85], v[174:177], v[212:215], v[82:85]
	v_mfma_f32_16x16x32_bf16 v[70:73], v[166:169], v[220:223], v[70:73]
	v_mfma_f32_16x16x32_bf16 v[66:69], v[174:177], v[220:223], v[66:69]
	v_mfma_f32_16x16x32_bf16 v[118:121], v[170:173], v[186:189], v[118:121]
	v_mfma_f32_16x16x32_bf16 v[114:117], v[178:181], v[186:189], v[114:117]
	v_mfma_f32_16x16x32_bf16 v[102:105], v[170:173], v[208:211], v[102:105]
	v_mfma_f32_16x16x32_bf16 v[98:101], v[178:181], v[208:211], v[98:101]
	v_mfma_f32_16x16x32_bf16 v[86:89], v[170:173], v[216:219], v[86:89]
	v_mfma_f32_16x16x32_bf16 v[82:85], v[178:181], v[216:219], v[82:85]
	v_mfma_f32_16x16x32_bf16 v[70:73], v[170:173], v[236:239], v[70:73]
	v_mfma_f32_16x16x32_bf16 v[66:69], v[178:181], v[236:239], v[66:69]
	s_setprio 0
	s_barrier
; #define PG8_STAGE(bufoff, gbase, voff) do { _Pragma("unroll") for (int _i = 0; _i < 2; ++_i) \
;         __builtin_amdgcn_global_load_lds((const unsigned*)((const char*)(gbase) + (voff)[_i]), (PG8_LAS unsigned*)(lds + (bufoff) + ldsw + _i * 8192), 16, 0, 0); } while (0)
; #define PG8_LDA(dst, b, h) do { _Pragma("unroll") for (int m = 0; m < 4; ++m) _Pragma("unroll") for (int k = 0; k < 2; ++k) dst[m][k] = *(const PG8_LAS bf16x8*)(lds + PG8_SA(b, h) + aoff + m * 2048 + k * 1024); } while (0)
; #define PG8_MMA(ai, bj, At, Bt) do { __builtin_amdgcn_s_setprio(1); _Pragma("unroll") for (int m = 0; m < 4; ++m) _Pragma("unroll") for (int n = 0; n < 2; ++n) _Pragma("unroll") for (int k = 0; k < 2; ++k) \
;         acc[ai][bj][m][n] = __builtin_amdgcn_mfma_f32_16x16x32_bf16(Bt[n][k], At[m][k], acc[ai][bj][m][n], 0, 0, 0); __builtin_amdgcn_s_setprio(0); } while (0)
; #define PG8_WAIT_V(n) asm volatile("s_waitcnt vmcnt(" #n ")" ::: "memory")
; #define PG8_WAIT_L(n) asm volatile("s_waitcnt lgkmcnt(" #n ")" ::: "memory")
; #define PG8_BAR __builtin_amdgcn_s_barrier()
; #define PG8_SCHED __builtin_amdgcn_sched_barrier(0)
; template <class Epi, class Sched, bool ALIGN_EPI = false, bool SP2 = false>
; __device__ __forceinline__ void gemm_phase(PG8_LAS unsigned char* lds, const Gemm g, const Sched& S, const Epi& E) {
;     ...
;             PG8_LDA(At, 1, 1); PG8_STAGE(PG8_SB(1, 0), b3, voffB); PG8_STAGE(PG8_SB(1, 1), b3 + hstep, voffB); PG8_STAGE(PG8_SA(1, 0), a3, voffA);
;             PG8_WAIT_V(8); PG8_WAIT_L(0); PG8_BAR; PG8_MMA(1, 0, At, B0); PG8_MMA(1, 1, At, B1); PG8_BAR; PG8_SCHED;
	s_add_i32 s42, s53, s59
	v_lshl_add_u64 v[198:199], v[198:199], 0, s[26:27]
	s_mov_b32 m0, s42
	ds_read_b128 v[182:185], v161 offset:49152
	ds_read_b128 v[186:189], v161 offset:50176
	ds_read_b128 v[190:193], v161 offset:51200
	ds_read_b128 v[208:211], v161 offset:52224
	ds_read_b128 v[212:215], v161 offset:53248
	ds_read_b128 v[216:219], v161 offset:54272
	ds_read_b128 v[220:223], v161 offset:55296
	ds_read_b128 v[236:239], v161 offset:56320
	global_load_lds_dwordx4 v[198:199], off
	v_lshl_add_u64 v[198:199], v[200:201], 0, s[26:27]
	s_add_i32 m0, s42, 0x2000
	s_add_i32 s42, s54, s59
	global_load_lds_dwordx4 v[198:199], off
	v_lshl_add_u64 v[198:199], v[202:203], 0, s[26:27]
	s_mov_b32 m0, s42
	s_nop 0
	global_load_lds_dwordx4 v[198:199], off
	v_lshl_add_u64 v[198:199], v[204:205], 0, s[26:27]
	s_add_i32 m0, s42, 0x2000
	s_nop 0
	global_load_lds_dwordx4 v[198:199], off
	v_lshl_add_u64 v[198:199], v[224:225], 0, s[26:27]
	s_mov_b32 m0, s75
	s_nop 0
	global_load_lds_dwordx4 v[198:199], off
	v_lshl_add_u64 v[198:199], v[228:229], 0, s[26:27]
	s_mov_b32 m0, s76
	s_nop 0
	global_load_lds_dwordx4 v[198:199], off
	s_waitcnt vmcnt(8)
	s_waitcnt lgkmcnt(0)
	s_barrier
	s_setprio 1
	s_waitcnt lgkmcnt(0)
	v_mfma_f32_16x16x32_bf16 v[62:65], v[146:149], v[182:185], v[62:65]
	v_mfma_f32_16x16x32_bf16 v[58:61], v[154:157], v[182:185], v[58:61]
	v_mfma_f32_16x16x32_bf16 v[46:49], v[146:149], v[190:193], v[46:49]
	v_mfma_f32_16x16x32_bf16 v[42:45], v[154:157], v[190:193], v[42:45]
	v_mfma_f32_16x16x32_bf16 v[30:33], v[146:149], v[212:215], v[30:33]
	v_mfma_f32_16x16x32_bf16 v[26:29], v[154:157], v[212:215], v[26:29]
	v_mfma_f32_16x16x32_bf16 v[14:17], v[146:149], v[220:223], v[14:17]
	v_mfma_f32_16x16x32_bf16 v[10:13], v[154:157], v[220:223], v[10:13]
	v_mfma_f32_16x16x32_bf16 v[62:65], v[150:153], v[186:189], v[62:65]
	v_mfma_f32_16x16x32_bf16 v[58:61], v[162:165], v[186:189], v[58:61]
	v_mfma_f32_16x16x32_bf16 v[46:49], v[150:153], v[208:211], v[46:49]
	v_mfma_f32_16x16x32_bf16 v[42:45], v[162:165], v[208:211], v[42:45]
	v_mfma_f32_16x16x32_bf16 v[30:33], v[150:153], v[216:219], v[30:33]
	v_mfma_f32_16x16x32_bf16 v[26:29], v[162:165], v[216:219], v[26:29]
	v_mfma_f32_16x16x32_bf16 v[14:17], v[150:153], v[236:239], v[14:17]
	v_mfma_f32_16x16x32_bf16 v[10:13], v[162:165], v[236:239], v[10:13]
	v_mfma_f32_16x16x32_bf16 v[54:57], v[166:169], v[182:185], v[54:57]
	v_mfma_f32_16x16x32_bf16 v[50:53], v[174:177], v[182:185], v[50:53]
	v_mfma_f32_16x16x32_bf16 v[38:41], v[166:169], v[190:193], v[38:41]
	v_mfma_f32_16x16x32_bf16 v[34:37], v[174:177], v[190:193], v[34:37]
	v_mfma_f32_16x16x32_bf16 v[22:25], v[166:169], v[212:215], v[22:25]
	v_mfma_f32_16x16x32_bf16 v[18:21], v[174:177], v[212:215], v[18:21]
	v_mfma_f32_16x16x32_bf16 v[6:9], v[166:169], v[220:223], v[6:9]
	v_mfma_f32_16x16x32_bf16 v[2:5], v[174:177], v[220:223], v[2:5]
	v_mfma_f32_16x16x32_bf16 v[54:57], v[170:173], v[186:189], v[54:57]
	v_mfma_f32_16x16x32_bf16 v[50:53], v[178:181], v[186:189], v[50:53]
	v_mfma_f32_16x16x32_bf16 v[38:41], v[170:173], v[208:211], v[38:41]
	v_mfma_f32_16x16x32_bf16 v[34:37], v[178:181], v[208:211], v[34:37]
	v_mfma_f32_16x16x32_bf16 v[22:25], v[170:173], v[216:219], v[22:25]
	v_mfma_f32_16x16x32_bf16 v[18:21], v[178:181], v[216:219], v[18:21]
	v_mfma_f32_16x16x32_bf16 v[6:9], v[170:173], v[236:239], v[6:9]
	v_mfma_f32_16x16x32_bf16 v[2:5], v[178:181], v[236:239], v[2:5]
	s_setprio 0
	s_barrier
	s_add_u32 s14, s14, 0x100
	s_addc_u32 s15, s15, 0
	s_add_u32 s50, s50, 0x100
	s_addc_u32 s51, s51, 0
	s_cmp_ge_i32 s52, s74
	s_mov_b32 s42, s52
	s_cbranch_scc0 .LBB0_368

; #define PG8_STAGE(bufoff, gbase, voff) do { _Pragma("unroll") for (int _i = 0; _i < 2; ++_i) \
;         __builtin_amdgcn_global_load_lds((const unsigned*)((const char*)(gbase) + (voff)[_i]), (PG8_LAS unsigned*)(lds + (bufoff) + ldsw + _i * 8192), 16, 0, 0); } while (0)
; #define PG8_LDA(dst, b, h) do { _Pragma("unroll") for (int m = 0; m < 4; ++m) _Pragma("unroll") for (int k = 0; k < 2; ++k) dst[m][k] = *(const PG8_LAS bf16x8*)(lds + PG8_SA(b, h) + aoff + m * 2048 + k * 1024); } while (0)
; #define PG8_LDB(dst, b, h) do { _Pragma("unroll") for (int n = 0; n < 2; ++n) _Pragma("unroll") for (int k = 0; k < 2; ++k) dst[n][k] = *(const PG8_LAS bf16x8*)(lds + PG8_SB(b, h) + boff + n * 2048 + k * 1024); } while (0)
; #define PG8_MMA(ai, bj, At, Bt) do { __builtin_amdgcn_s_setprio(1); _Pragma("unroll") for (int m = 0; m < 4; ++m) _Pragma("unroll") for (int n = 0; n < 2; ++n) _Pragma("unroll") for (int k = 0; k < 2; ++k) \
;         acc[ai][bj][m][n] = __builtin_amdgcn_mfma_f32_16x16x32_bf16(Bt[n][k], At[m][k], acc[ai][bj][m][n], 0, 0, 0); __builtin_amdgcn_s_setprio(0); } while (0)
; #define PG8_WAIT_V(n) asm volatile("s_waitcnt vmcnt(" #n ")" ::: "memory")
; #define PG8_WAIT_L(n) asm volatile("s_waitcnt lgkmcnt(" #n ")" ::: "memory")
; #define PG8_BAR __builtin_amdgcn_s_barrier()
; #define PG8_SCHED __builtin_amdgcn_sched_barrier(0)
; template <class Epi, class Sched, bool ALIGN_EPI = false, bool SP2 = false>
; __device__ __forceinline__ void gemm_phase(PG8_LAS unsigned char* lds, const Gemm g, const Sched& S, const Epi& E) {
;     ...
;             const char* a2 = last ? nA : cA + (size_t)(t + 2) * kstep; const char* b2 = last ? nB : cB + (size_t)(t + 2) * kstep;
;             const char* a3 = a2 + kstep; const char* b3 = b2 + kstep;
;             if (last && has_next) S.a_ready(nxt);
;             if constexpr (SP2) {
;             PG8_LDB(B0, 0, 0); PG8_LDB(B1, 0, 1); PG8_SCHED; PG8_LDA(At, 0, 0); PG8_STAGE(PG8_SA(1, 1), a1 + hstep, voffA);
;             PG8_WAIT_V(8); PG8_WAIT_L(0); PG8_BAR; PG8_MMA(0, 0, At, B0); PG8_MMA(0, 1, At, B1); PG8_BAR; PG8_SCHED;
;             PG8_LDA(At, 0, 1); PG8_STAGE(PG8_SB(0, 0), b2, voffB); PG8_STAGE(PG8_SB(0, 1), b2 + hstep, voffB); PG8_STAGE(PG8_SA(0, 0), a2, voffA);
.LBB0_423:
	s_add_i32 s59, s44, 2
	s_add_u32 s60, s14, 0x80
	s_addc_u32 s45, s15, 0
	s_add_i32 s64, 0, 0x10000
	s_cmp_eq_u32 s81, s44
	s_cselect_b32 s45, s53, s45
	s_cselect_b32 s44, s52, s60
	v_add_u32_e32 v0, s64, v162
	s_cselect_b32 s61, s55, s57
	s_cselect_b32 s60, s54, s56
	s_add_i32 s65, 0, 0x14000
	ds_read_b128 v[134:137], v0
	ds_read_b128 v[154:157], v0 offset:1024
	ds_read_b128 v[158:161], v0 offset:2048
	ds_read_b128 v[164:167], v0 offset:3072
	v_add_u32_e32 v0, s65, v162
	ds_read_b128 v[168:171], v0
	ds_read_b128 v[172:175], v0 offset:1024
	ds_read_b128 v[176:179], v0 offset:2048
	ds_read_b128 v[180:183], v0 offset:3072
	v_lshl_add_u64 v[192:193], s[14:15], 0, v[148:149]
	s_add_i32 m0, s74, 0xc000
	ds_read_b128 v[184:187], v163
	ds_read_b128 v[188:191], v163 offset:1024
	ds_read_b128 v[208:211], v163 offset:2048
	ds_read_b128 v[212:215], v163 offset:3072
	ds_read_b128 v[216:219], v163 offset:4096
	ds_read_b128 v[220:223], v163 offset:5120
	ds_read_b128 v[236:239], v163 offset:6144
	ds_read_b128 v[240:243], v163 offset:7168
	global_load_lds_dwordx4 v[192:193], off
	v_lshl_add_u64 v[192:193], s[14:15], 0, v[150:151]
	s_add_i32 m0, s74, 0xe000
	s_nop 0
	global_load_lds_dwordx4 v[192:193], off
	s_waitcnt vmcnt(8)
	s_waitcnt lgkmcnt(0)
	s_barrier
	s_setprio 1
	s_waitcnt lgkmcnt(0)
	v_mfma_f32_16x16x32_bf16 v[126:129], v[134:137], v[184:187], v[126:129]
	v_mfma_f32_16x16x32_bf16 v[122:125], v[158:161], v[184:187], v[122:125]
	v_mfma_f32_16x16x32_bf16 v[110:113], v[134:137], v[208:211], v[110:113]
	v_mfma_f32_16x16x32_bf16 v[106:109], v[158:161], v[208:211], v[106:109]
	v_mfma_f32_16x16x32_bf16 v[94:97], v[134:137], v[216:219], v[94:97]
	v_mfma_f32_16x16x32_bf16 v[90:93], v[158:161], v[216:219], v[90:93]
	v_mfma_f32_16x16x32_bf16 v[78:81], v[134:137], v[236:239], v[78:81]
	v_mfma_f32_16x16x32_bf16 v[74:77], v[158:161], v[236:239], v[74:77]
	v_mfma_f32_16x16x32_bf16 v[126:129], v[154:157], v[188:191], v[126:129]
	v_mfma_f32_16x16x32_bf16 v[122:125], v[164:167], v[188:191], v[122:125]
	v_mfma_f32_16x16x32_bf16 v[110:113], v[154:157], v[212:215], v[110:113]
	v_mfma_f32_16x16x32_bf16 v[106:109], v[164:167], v[212:215], v[106:109]
	v_mfma_f32_16x16x32_bf16 v[94:97], v[154:157], v[220:223], v[94:97]
	v_mfma_f32_16x16x32_bf16 v[90:93], v[164:167], v[220:223], v[90:93]
	v_mfma_f32_16x16x32_bf16 v[78:81], v[154:157], v[240:243], v[78:81]
	v_mfma_f32_16x16x32_bf16 v[74:77], v[164:167], v[240:243], v[74:77]
	v_mfma_f32_16x16x32_bf16 v[118:121], v[168:171], v[184:187], v[118:121]
	v_mfma_f32_16x16x32_bf16 v[114:117], v[176:179], v[184:187], v[114:117]
	v_mfma_f32_16x16x32_bf16 v[102:105], v[168:171], v[208:211], v[102:105]
	v_mfma_f32_16x16x32_bf16 v[98:101], v[176:179], v[208:211], v[98:101]
	v_mfma_f32_16x16x32_bf16 v[86:89], v[168:171], v[216:219], v[86:89]
	v_mfma_f32_16x16x32_bf16 v[82:85], v[176:179], v[216:219], v[82:85]
	v_mfma_f32_16x16x32_bf16 v[70:73], v[168:171], v[236:239], v[70:73]
	v_mfma_f32_16x16x32_bf16 v[66:69], v[176:179], v[236:239], v[66:69]
	v_mfma_f32_16x16x32_bf16 v[118:121], v[172:175], v[188:191], v[118:121]
	v_mfma_f32_16x16x32_bf16 v[114:117], v[180:183], v[188:191], v[114:117]
	v_mfma_f32_16x16x32_bf16 v[102:105], v[172:175], v[212:215], v[102:105]
	v_mfma_f32_16x16x32_bf16 v[98:101], v[180:183], v[212:215], v[98:101]
	v_mfma_f32_16x16x32_bf16 v[86:89], v[172:175], v[220:223], v[86:89]
	v_mfma_f32_16x16x32_bf16 v[82:85], v[180:183], v[220:223], v[82:85]
	v_mfma_f32_16x16x32_bf16 v[70:73], v[172:175], v[240:243], v[70:73]
	v_mfma_f32_16x16x32_bf16 v[66:69], v[180:183], v[240:243], v[66:69]
	s_setprio 0
	s_barrier
	s_add_i32 s64, s64, s33
	v_lshl_add_u64 v[192:193], s[60:61], 0, v[142:143]
	s_mov_b32 m0, s64
	ds_read_b128 v[184:187], v163 offset:16384
	ds_read_b128 v[188:191], v163 offset:17408
	ds_read_b128 v[208:211], v163 offset:18432
	ds_read_b128 v[212:215], v163 offset:19456
	ds_read_b128 v[216:219], v163 offset:20480
	ds_read_b128 v[220:223], v163 offset:21504
	ds_read_b128 v[236:239], v163 offset:22528
	ds_read_b128 v[240:243], v163 offset:23552
	global_load_lds_dwordx4 v[192:193], off
	s_add_i32 m0, s64, 0x2000
	v_lshl_add_u64 v[198:199], s[60:61], 0, v[138:139]
	s_add_u32 s60, s60, s4
	s_addc_u32 s61, s61, s5
	s_add_i32 s64, s65, s33
	global_load_lds_dwordx4 v[198:199], off
	v_lshl_add_u64 v[200:201], s[60:61], 0, v[142:143]
	s_mov_b32 m0, s64
	v_lshl_add_u64 v[202:203], s[60:61], 0, v[138:139]
	global_load_lds_dwordx4 v[200:201], off
	s_add_i32 m0, s64, 0x2000
	v_lshl_add_u64 v[204:205], s[44:45], 0, v[144:145]
	global_load_lds_dwordx4 v[202:203], off
	s_mov_b32 m0, s74
	v_lshl_add_u64 v[224:225], s[44:45], 0, v[140:141]
	global_load_lds_dwordx4 v[204:205], off
	s_mov_b32 m0, s75
	s_nop 0
	global_load_lds_dwordx4 v[224:225], off
	s_waitcnt vmcnt(8)
	s_waitcnt lgkmcnt(0)
	s_barrier
; #define PG8_STAGE(bufoff, gbase, voff) do { _Pragma("unroll") for (int _i = 0; _i < 2; ++_i) \
;         __builtin_amdgcn_global_load_lds((const unsigned*)((const char*)(gbase) + (voff)[_i]), (PG8_LAS unsigned*)(lds + (bufoff) + ldsw + _i * 8192), 16, 0, 0); } while (0)
; #define PG8_LDA(dst, b, h) do { _Pragma("unroll") for (int m = 0; m < 4; ++m) _Pragma("unroll") for (int k = 0; k < 2; ++k) dst[m][k] = *(const PG8_LAS bf16x8*)(lds + PG8_SA(b, h) + aoff + m * 2048 + k * 1024); } while (0)
; #define PG8_LDB(dst, b, h) do { _Pragma("unroll") for (int n = 0; n < 2; ++n) _Pragma("unroll") for (int k = 0; k < 2; ++k) dst[n][k] = *(const PG8_LAS bf16x8*)(lds + PG8_SB(b, h) + boff + n * 2048 + k * 1024); } while (0)
; #define PG8_MMA(ai, bj, At, Bt) do { __builtin_amdgcn_s_setprio(1); _Pragma("unroll") for (int m = 0; m < 4; ++m) _Pragma("unroll") for (int n = 0; n < 2; ++n) _Pragma("unroll") for (int k = 0; k < 2; ++k) \
;         acc[ai][bj][m][n] = __builtin_amdgcn_mfma_f32_16x16x32_bf16(Bt[n][k], At[m][k], acc[ai][bj][m][n], 0, 0, 0); __builtin_amdgcn_s_setprio(0); } while (0)
; #define PG8_WAIT_V(n) asm volatile("s_waitcnt vmcnt(" #n ")" ::: "memory")
; #define PG8_WAIT_L(n) asm volatile("s_waitcnt lgkmcnt(" #n ")" ::: "memory")
; #define PG8_BAR __builtin_amdgcn_s_barrier()
; #define PG8_SCHED __builtin_amdgcn_sched_barrier(0)
; template <class Epi, class Sched, bool ALIGN_EPI = false, bool SP2 = false>
; __device__ __forceinline__ void gemm_phase(PG8_LAS unsigned char* lds, const Gemm g, const Sched& S, const Epi& E) {
;     ...
;             PG8_WAIT_V(8); PG8_WAIT_L(0); PG8_BAR; PG8_MMA(1, 0, At, B0); PG8_MMA(1, 1, At, B1); PG8_BAR; PG8_SCHED;
;             PG8_LDB(B0, 1, 0); PG8_LDB(B1, 1, 1); PG8_SCHED; PG8_LDA(At, 1, 0); PG8_STAGE(PG8_SA(0, 1), a2 + hstep, voffA);
;             PG8_WAIT_V(8); PG8_WAIT_L(0); PG8_BAR; PG8_MMA(0, 0, At, B0); PG8_MMA(0, 1, At, B1); PG8_BAR; PG8_SCHED;
	s_setprio 1
	s_waitcnt lgkmcnt(0)
	v_mfma_f32_16x16x32_bf16 v[62:65], v[134:137], v[184:187], v[62:65]
	v_mfma_f32_16x16x32_bf16 v[58:61], v[158:161], v[184:187], v[58:61]
	v_mfma_f32_16x16x32_bf16 v[46:49], v[134:137], v[208:211], v[46:49]
	v_mfma_f32_16x16x32_bf16 v[42:45], v[158:161], v[208:211], v[42:45]
	v_mfma_f32_16x16x32_bf16 v[30:33], v[134:137], v[216:219], v[30:33]
	v_mfma_f32_16x16x32_bf16 v[26:29], v[158:161], v[216:219], v[26:29]
	v_mfma_f32_16x16x32_bf16 v[14:17], v[134:137], v[236:239], v[14:17]
	v_mfma_f32_16x16x32_bf16 v[10:13], v[158:161], v[236:239], v[10:13]
	v_mfma_f32_16x16x32_bf16 v[62:65], v[154:157], v[188:191], v[62:65]
	v_mfma_f32_16x16x32_bf16 v[58:61], v[164:167], v[188:191], v[58:61]
	v_mfma_f32_16x16x32_bf16 v[46:49], v[154:157], v[212:215], v[46:49]
	v_mfma_f32_16x16x32_bf16 v[42:45], v[164:167], v[212:215], v[42:45]
	v_mfma_f32_16x16x32_bf16 v[30:33], v[154:157], v[220:223], v[30:33]
	v_mfma_f32_16x16x32_bf16 v[26:29], v[164:167], v[220:223], v[26:29]
	v_mfma_f32_16x16x32_bf16 v[14:17], v[154:157], v[240:243], v[14:17]
	v_mfma_f32_16x16x32_bf16 v[10:13], v[164:167], v[240:243], v[10:13]
	v_mfma_f32_16x16x32_bf16 v[54:57], v[168:171], v[184:187], v[54:57]
	v_mfma_f32_16x16x32_bf16 v[50:53], v[176:179], v[184:187], v[50:53]
	v_mfma_f32_16x16x32_bf16 v[38:41], v[168:171], v[208:211], v[38:41]
	v_mfma_f32_16x16x32_bf16 v[34:37], v[176:179], v[208:211], v[34:37]
	v_mfma_f32_16x16x32_bf16 v[22:25], v[168:171], v[216:219], v[22:25]
	v_mfma_f32_16x16x32_bf16 v[18:21], v[176:179], v[216:219], v[18:21]
	v_mfma_f32_16x16x32_bf16 v[6:9], v[168:171], v[236:239], v[6:9]
	v_mfma_f32_16x16x32_bf16 v[2:5], v[176:179], v[236:239], v[2:5]
	v_mfma_f32_16x16x32_bf16 v[54:57], v[172:175], v[188:191], v[54:57]
	v_mfma_f32_16x16x32_bf16 v[50:53], v[180:183], v[188:191], v[50:53]
	v_mfma_f32_16x16x32_bf16 v[38:41], v[172:175], v[212:215], v[38:41]
	v_mfma_f32_16x16x32_bf16 v[34:37], v[180:183], v[212:215], v[34:37]
	v_mfma_f32_16x16x32_bf16 v[22:25], v[172:175], v[220:223], v[22:25]
	v_mfma_f32_16x16x32_bf16 v[18:21], v[180:183], v[220:223], v[18:21]
	v_mfma_f32_16x16x32_bf16 v[6:9], v[172:175], v[240:243], v[6:9]
	v_mfma_f32_16x16x32_bf16 v[2:5], v[180:183], v[240:243], v[2:5]
	s_setprio 0
	s_barrier
	s_add_i32 s60, 0, 0x18000
	v_add_u32_e32 v0, s60, v162
	s_add_i32 s61, 0, 0x1c000
	ds_read_b128 v[134:137], v0
	ds_read_b128 v[154:157], v0 offset:1024
	ds_read_b128 v[158:161], v0 offset:2048
	ds_read_b128 v[164:167], v0 offset:3072
	v_add_u32_e32 v0, s61, v162
	ds_read_b128 v[168:171], v0
	ds_read_b128 v[172:175], v0 offset:1024
	ds_read_b128 v[176:179], v0 offset:2048
	ds_read_b128 v[180:183], v0 offset:3072
	s_add_u32 s44, s44, s4
	s_addc_u32 s45, s45, s5
	s_mov_b32 m0, s76
	v_lshl_add_u64 v[228:229], s[44:45], 0, v[144:145]
	ds_read_b128 v[184:187], v163 offset:32768
	ds_read_b128 v[188:191], v163 offset:33792
	ds_read_b128 v[208:211], v163 offset:34816
	ds_read_b128 v[212:215], v163 offset:35840
	ds_read_b128 v[216:219], v163 offset:36864
	ds_read_b128 v[220:223], v163 offset:37888
	ds_read_b128 v[236:239], v163 offset:38912
	ds_read_b128 v[240:243], v163 offset:39936
	global_load_lds_dwordx4 v[228:229], off
	v_lshl_add_u64 v[228:229], s[44:45], 0, v[140:141]
	s_mov_b32 m0, s77
	s_nop 0
	global_load_lds_dwordx4 v[228:229], off
	s_waitcnt vmcnt(8)
	s_waitcnt lgkmcnt(0)
	s_barrier
	s_setprio 1
	s_waitcnt lgkmcnt(0)
	v_mfma_f32_16x16x32_bf16 v[126:129], v[134:137], v[184:187], v[126:129]
	v_mfma_f32_16x16x32_bf16 v[122:125], v[158:161], v[184:187], v[122:125]
	v_mfma_f32_16x16x32_bf16 v[110:113], v[134:137], v[208:211], v[110:113]
	v_mfma_f32_16x16x32_bf16 v[106:109], v[158:161], v[208:211], v[106:109]
	v_mfma_f32_16x16x32_bf16 v[94:97], v[134:137], v[216:219], v[94:97]
	v_mfma_f32_16x16x32_bf16 v[90:93], v[158:161], v[216:219], v[90:93]
	v_mfma_f32_16x16x32_bf16 v[78:81], v[134:137], v[236:239], v[78:81]
	v_mfma_f32_16x16x32_bf16 v[74:77], v[158:161], v[236:239], v[74:77]
	v_mfma_f32_16x16x32_bf16 v[126:129], v[154:157], v[188:191], v[126:129]
	v_mfma_f32_16x16x32_bf16 v[122:125], v[164:167], v[188:191], v[122:125]
	v_mfma_f32_16x16x32_bf16 v[110:113], v[154:157], v[212:215], v[110:113]
	v_mfma_f32_16x16x32_bf16 v[106:109], v[164:167], v[212:215], v[106:109]
	v_mfma_f32_16x16x32_bf16 v[94:97], v[154:157], v[220:223], v[94:97]
	v_mfma_f32_16x16x32_bf16 v[90:93], v[164:167], v[220:223], v[90:93]
	v_mfma_f32_16x16x32_bf16 v[78:81], v[154:157], v[240:243], v[78:81]
	v_mfma_f32_16x16x32_bf16 v[74:77], v[164:167], v[240:243], v[74:77]
	v_mfma_f32_16x16x32_bf16 v[118:121], v[168:171], v[184:187], v[118:121]
	v_mfma_f32_16x16x32_bf16 v[114:117], v[176:179], v[184:187], v[114:117]
	v_mfma_f32_16x16x32_bf16 v[102:105], v[168:171], v[208:211], v[102:105]
	v_mfma_f32_16x16x32_bf16 v[98:101], v[176:179], v[208:211], v[98:101]
	v_mfma_f32_16x16x32_bf16 v[86:89], v[168:171], v[216:219], v[86:89]
	v_mfma_f32_16x16x32_bf16 v[82:85], v[176:179], v[216:219], v[82:85]
	v_mfma_f32_16x16x32_bf16 v[70:73], v[168:171], v[236:239], v[70:73]
	v_mfma_f32_16x16x32_bf16 v[66:69], v[176:179], v[236:239], v[66:69]
	v_mfma_f32_16x16x32_bf16 v[118:121], v[172:175], v[188:191], v[118:121]
	v_mfma_f32_16x16x32_bf16 v[114:117], v[180:183], v[188:191], v[114:117]
	v_mfma_f32_16x16x32_bf16 v[102:105], v[172:175], v[212:215], v[102:105]
	v_mfma_f32_16x16x32_bf16 v[98:101], v[180:183], v[212:215], v[98:101]
	v_mfma_f32_16x16x32_bf16 v[86:89], v[172:175], v[220:223], v[86:89]
	v_mfma_f32_16x16x32_bf16 v[82:85], v[180:183], v[220:223], v[82:85]
	v_mfma_f32_16x16x32_bf16 v[70:73], v[172:175], v[240:243], v[70:73]
	v_mfma_f32_16x16x32_bf16 v[66:69], v[180:183], v[240:243], v[66:69]
	s_setprio 0
	s_barrier
; #define PG8_STAGE(bufoff, gbase, voff) do { _Pragma("unroll") for (int _i = 0; _i < 2; ++_i) \
;         __builtin_amdgcn_global_load_lds((const unsigned*)((const char*)(gbase) + (voff)[_i]), (PG8_LAS unsigned*)(lds + (bufoff) + ldsw + _i * 8192), 16, 0, 0); } while (0)
; #define PG8_LDA(dst, b, h) do { _Pragma("unroll") for (int m = 0; m < 4; ++m) _Pragma("unroll") for (int k = 0; k < 2; ++k) dst[m][k] = *(const PG8_LAS bf16x8*)(lds + PG8_SA(b, h) + aoff + m * 2048 + k * 1024); } while (0)
; #define PG8_MMA(ai, bj, At, Bt) do { __builtin_amdgcn_s_setprio(1); _Pragma("unroll") for (int m = 0; m < 4; ++m) _Pragma("unroll") for (int n = 0; n < 2; ++n) _Pragma("unroll") for (int k = 0; k < 2; ++k) \
;         acc[ai][bj][m][n] = __builtin_amdgcn_mfma_f32_16x16x32_bf16(Bt[n][k], At[m][k], acc[ai][bj][m][n], 0, 0, 0); __builtin_amdgcn_s_setprio(0); } while (0)
; #define PG8_WAIT_V(n) asm volatile("s_waitcnt vmcnt(" #n ")" ::: "memory")
; #define PG8_WAIT_L(n) asm volatile("s_waitcnt lgkmcnt(" #n ")" ::: "memory")
; #define PG8_BAR __builtin_amdgcn_s_barrier()
; #define PG8_SCHED __builtin_amdgcn_sched_barrier(0)
; template <class Epi, class Sched, bool ALIGN_EPI = false, bool SP2 = false>
; __device__ __forceinline__ void gemm_phase(PG8_LAS unsigned char* lds, const Gemm g, const Sched& S, const Epi& E) {
;     ...
;             PG8_LDA(At, 1, 1); PG8_STAGE(PG8_SB(1, 0), b3, voffB); PG8_STAGE(PG8_SB(1, 1), b3 + hstep, voffB); PG8_STAGE(PG8_SA(1, 0), a3, voffA);
;             PG8_WAIT_V(8); PG8_WAIT_L(0); PG8_BAR; PG8_MMA(1, 0, At, B0); PG8_MMA(1, 1, At, B1); PG8_BAR; PG8_SCHED;
	s_add_i32 s44, s60, s33
	v_lshl_add_u64 v[192:193], v[192:193], 0, s[26:27]
	s_mov_b32 m0, s44
	ds_read_b128 v[184:187], v163 offset:49152
	ds_read_b128 v[188:191], v163 offset:50176
	ds_read_b128 v[208:211], v163 offset:51200
	ds_read_b128 v[212:215], v163 offset:52224
	ds_read_b128 v[216:219], v163 offset:53248
	ds_read_b128 v[220:223], v163 offset:54272
	ds_read_b128 v[236:239], v163 offset:55296
	ds_read_b128 v[240:243], v163 offset:56320
	global_load_lds_dwordx4 v[192:193], off
	v_lshl_add_u64 v[192:193], v[198:199], 0, s[26:27]
	s_add_i32 m0, s44, 0x2000
	s_add_i32 s44, s61, s33
	global_load_lds_dwordx4 v[192:193], off
	v_lshl_add_u64 v[192:193], v[200:201], 0, s[26:27]
	s_mov_b32 m0, s44
	s_nop 0
	global_load_lds_dwordx4 v[192:193], off
	v_lshl_add_u64 v[192:193], v[202:203], 0, s[26:27]
	s_add_i32 m0, s44, 0x2000
	s_nop 0
	global_load_lds_dwordx4 v[192:193], off
	v_lshl_add_u64 v[192:193], v[204:205], 0, s[26:27]
	s_mov_b32 m0, s78
	s_nop 0
	global_load_lds_dwordx4 v[192:193], off
	v_lshl_add_u64 v[192:193], v[224:225], 0, s[26:27]
	s_mov_b32 m0, s79
	s_nop 0
	global_load_lds_dwordx4 v[192:193], off
	s_waitcnt vmcnt(8)
	s_waitcnt lgkmcnt(0)
	s_barrier
	s_setprio 1
	s_waitcnt lgkmcnt(0)
	v_mfma_f32_16x16x32_bf16 v[62:65], v[134:137], v[184:187], v[62:65]
	v_mfma_f32_16x16x32_bf16 v[58:61], v[158:161], v[184:187], v[58:61]
	v_mfma_f32_16x16x32_bf16 v[46:49], v[134:137], v[208:211], v[46:49]
	v_mfma_f32_16x16x32_bf16 v[42:45], v[158:161], v[208:211], v[42:45]
	v_mfma_f32_16x16x32_bf16 v[30:33], v[134:137], v[216:219], v[30:33]
	v_mfma_f32_16x16x32_bf16 v[26:29], v[158:161], v[216:219], v[26:29]
	v_mfma_f32_16x16x32_bf16 v[14:17], v[134:137], v[236:239], v[14:17]
	v_mfma_f32_16x16x32_bf16 v[10:13], v[158:161], v[236:239], v[10:13]
	v_mfma_f32_16x16x32_bf16 v[62:65], v[154:157], v[188:191], v[62:65]
	v_mfma_f32_16x16x32_bf16 v[58:61], v[164:167], v[188:191], v[58:61]
	v_mfma_f32_16x16x32_bf16 v[46:49], v[154:157], v[212:215], v[46:49]
	v_mfma_f32_16x16x32_bf16 v[42:45], v[164:167], v[212:215], v[42:45]
	v_mfma_f32_16x16x32_bf16 v[30:33], v[154:157], v[220:223], v[30:33]
	v_mfma_f32_16x16x32_bf16 v[26:29], v[164:167], v[220:223], v[26:29]
	v_mfma_f32_16x16x32_bf16 v[14:17], v[154:157], v[240:243], v[14:17]
	v_mfma_f32_16x16x32_bf16 v[10:13], v[164:167], v[240:243], v[10:13]
	v_mfma_f32_16x16x32_bf16 v[54:57], v[168:171], v[184:187], v[54:57]
	v_mfma_f32_16x16x32_bf16 v[50:53], v[176:179], v[184:187], v[50:53]
	v_mfma_f32_16x16x32_bf16 v[38:41], v[168:171], v[208:211], v[38:41]
	v_mfma_f32_16x16x32_bf16 v[34:37], v[176:179], v[208:211], v[34:37]
	v_mfma_f32_16x16x32_bf16 v[22:25], v[168:171], v[216:219], v[22:25]
	v_mfma_f32_16x16x32_bf16 v[18:21], v[176:179], v[216:219], v[18:21]
	v_mfma_f32_16x16x32_bf16 v[6:9], v[168:171], v[236:239], v[6:9]
	v_mfma_f32_16x16x32_bf16 v[2:5], v[176:179], v[236:239], v[2:5]
	v_mfma_f32_16x16x32_bf16 v[54:57], v[172:175], v[188:191], v[54:57]
	v_mfma_f32_16x16x32_bf16 v[50:53], v[180:183], v[188:191], v[50:53]
	v_mfma_f32_16x16x32_bf16 v[38:41], v[172:175], v[212:215], v[38:41]
	v_mfma_f32_16x16x32_bf16 v[34:37], v[180:183], v[212:215], v[34:37]
	v_mfma_f32_16x16x32_bf16 v[22:25], v[172:175], v[220:223], v[22:25]
	v_mfma_f32_16x16x32_bf16 v[18:21], v[180:183], v[220:223], v[18:21]
	v_mfma_f32_16x16x32_bf16 v[6:9], v[172:175], v[240:243], v[6:9]
	v_mfma_f32_16x16x32_bf16 v[2:5], v[180:183], v[240:243], v[2:5]
	s_setprio 0
	s_barrier
	s_add_u32 s14, s14, 0x100
	s_addc_u32 s15, s15, 0
	s_add_u32 s56, s56, 0x100
	s_addc_u32 s57, s57, 0
	s_cmp_ge_i32 s59, s80
	s_mov_b32 s44, s59
	s_cbranch_scc0 .LBB0_423
	s_and_b64 vcc, exec, s[46:47]
	s_cbranch_vccz .LBB0_426

; #define PG8_STAGE(bufoff, gbase, voff) do { _Pragma("unroll") for (int _i = 0; _i < 2; ++_i) \
;         __builtin_amdgcn_global_load_lds((const unsigned*)((const char*)(gbase) + (voff)[_i]), (PG8_LAS unsigned*)(lds + (bufoff) + ldsw + _i * 8192), 16, 0, 0); } while (0)
; #define PG8_LDA(dst, b, h) do { _Pragma("unroll") for (int m = 0; m < 4; ++m) _Pragma("unroll") for (int k = 0; k < 2; ++k) dst[m][k] = *(const PG8_LAS bf16x8*)(lds + PG8_SA(b, h) + aoff + m * 2048 + k * 1024); } while (0)
; #define PG8_LDB(dst, b, h) do { _Pragma("unroll") for (int n = 0; n < 2; ++n) _Pragma("unroll") for (int k = 0; k < 2; ++k) dst[n][k] = *(const PG8_LAS bf16x8*)(lds + PG8_SB(b, h) + boff + n * 2048 + k * 1024); } while (0)
; #define PG8_MMA(ai, bj, At, Bt) do { __builtin_amdgcn_s_setprio(1); _Pragma("unroll") for (int m = 0; m < 4; ++m) _Pragma("unroll") for (int n = 0; n < 2; ++n) _Pragma("unroll") for (int k = 0; k < 2; ++k) \
;         acc[ai][bj][m][n] = __builtin_amdgcn_mfma_f32_16x16x32_bf16(Bt[n][k], At[m][k], acc[ai][bj][m][n], 0, 0, 0); __builtin_amdgcn_s_setprio(0); } while (0)
; #define PG8_WAIT_V(n) asm volatile("s_waitcnt vmcnt(" #n ")" ::: "memory")
; #define PG8_WAIT_L(n) asm volatile("s_waitcnt lgkmcnt(" #n ")" ::: "memory")
; #define PG8_BAR __builtin_amdgcn_s_barrier()
; #define PG8_SCHED __builtin_amdgcn_sched_barrier(0)
; template <class Epi, class Sched, bool ALIGN_EPI = false, bool SP2 = false>
; __device__ __forceinline__ void gemm_phase(PG8_LAS unsigned char* lds, const Gemm g, const Sched& S, const Epi& E) {
;     ...
;             const char* a2 = last ? nA : cA + (size_t)(t + 2) * kstep; const char* b2 = last ? nB : cB + (size_t)(t + 2) * kstep;
;             const char* a3 = a2 + kstep; const char* b3 = b2 + kstep;
;             if (last && has_next) S.a_ready(nxt);
;             if constexpr (SP2) {
;             PG8_LDB(B0, 0, 0); PG8_LDB(B1, 0, 1); PG8_SCHED; PG8_LDA(At, 0, 0); PG8_STAGE(PG8_SA(1, 1), a1 + hstep, voffA);
;             PG8_WAIT_V(8); PG8_WAIT_L(0); PG8_BAR; PG8_MMA(0, 0, At, B0); PG8_MMA(0, 1, At, B1); PG8_BAR; PG8_SCHED;
;             PG8_LDA(At, 0, 1); PG8_STAGE(PG8_SB(0, 0), b2, voffB); PG8_STAGE(PG8_SB(0, 1), b2 + hstep, voffB); PG8_STAGE(PG8_SA(0, 0), a2, voffA);
.LBB0_579:
	s_add_i32 s78, s6, 2
	s_add_u32 s64, s4, 0x80
	s_addc_u32 s7, s5, 0
	s_add_i32 s66, 0, 0x10000
	s_cmp_eq_u32 s82, s6
	s_cselect_b32 s7, s43, s7
	s_cselect_b32 s6, s42, s64
	s_cselect_b32 s65, s75, s9
	s_cselect_b32 s64, s74, s8
	s_add_i32 s67, 0, 0x14000
	v_add_u32_e32 v138, s66, v237
	v_add_u32_e32 v158, s67, v237
	ds_read_b128 v[114:117], v138
	ds_read_b128 v[118:121], v138 offset:1024
	ds_read_b128 v[122:125], v138 offset:2048
	ds_read_b128 v[138:141], v138 offset:3072
	ds_read_b128 v[142:145], v158
	ds_read_b128 v[150:153], v158 offset:1024
	ds_read_b128 v[154:157], v158 offset:2048
	ds_read_b128 v[158:161], v158 offset:3072
	v_lshl_add_u64 v[192:193], s[4:5], 0, v[188:189]
	s_add_i32 m0, s24, 0xc000
	ds_read_b128 v[166:169], v239
	ds_read_b128 v[170:173], v239 offset:1024
	ds_read_b128 v[174:177], v239 offset:2048
	ds_read_b128 v[178:181], v239 offset:3072
	ds_read_b128 v[208:211], v239 offset:4096
	ds_read_b128 v[212:215], v239 offset:5120
	ds_read_b128 v[216:219], v239 offset:6144
	ds_read_b128 v[220:223], v239 offset:7168
	global_load_lds_dwordx4 v[192:193], off
	v_lshl_add_u64 v[192:193], s[4:5], 0, v[190:191]
	s_add_i32 m0, s24, 0xe000
	s_nop 0
	global_load_lds_dwordx4 v[192:193], off
	s_waitcnt vmcnt(8)
	s_waitcnt lgkmcnt(0)
	s_barrier
	s_setprio 1
	s_waitcnt lgkmcnt(0)
	v_mfma_f32_16x16x32_bf16 v[162:165], v[114:117], v[166:169], v[162:165]
	v_mfma_f32_16x16x32_bf16 v[146:149], v[122:125], v[166:169], v[146:149]
	v_mfma_f32_16x16x32_bf16 v[110:113], v[114:117], v[174:177], v[110:113]
	v_mfma_f32_16x16x32_bf16 v[106:109], v[122:125], v[174:177], v[106:109]
	v_mfma_f32_16x16x32_bf16 v[94:97], v[114:117], v[208:211], v[94:97]
	v_mfma_f32_16x16x32_bf16 v[90:93], v[122:125], v[208:211], v[90:93]
	v_mfma_f32_16x16x32_bf16 v[78:81], v[114:117], v[216:219], v[78:81]
	v_mfma_f32_16x16x32_bf16 v[74:77], v[122:125], v[216:219], v[74:77]
	v_mfma_f32_16x16x32_bf16 v[162:165], v[118:121], v[170:173], v[162:165]
	v_mfma_f32_16x16x32_bf16 v[146:149], v[138:141], v[170:173], v[146:149]
	v_mfma_f32_16x16x32_bf16 v[110:113], v[118:121], v[178:181], v[110:113]
	v_mfma_f32_16x16x32_bf16 v[106:109], v[138:141], v[178:181], v[106:109]
	v_mfma_f32_16x16x32_bf16 v[94:97], v[118:121], v[212:215], v[94:97]
	v_mfma_f32_16x16x32_bf16 v[90:93], v[138:141], v[212:215], v[90:93]
	v_mfma_f32_16x16x32_bf16 v[78:81], v[118:121], v[220:223], v[78:81]
	v_mfma_f32_16x16x32_bf16 v[74:77], v[138:141], v[220:223], v[74:77]
	v_mfma_f32_16x16x32_bf16 v[134:137], v[142:145], v[166:169], v[134:137]
	v_mfma_f32_16x16x32_bf16 v[126:129], v[154:157], v[166:169], v[126:129]
	v_mfma_f32_16x16x32_bf16 v[102:105], v[142:145], v[174:177], v[102:105]
	v_mfma_f32_16x16x32_bf16 v[98:101], v[154:157], v[174:177], v[98:101]
	v_mfma_f32_16x16x32_bf16 v[86:89], v[142:145], v[208:211], v[86:89]
	v_mfma_f32_16x16x32_bf16 v[82:85], v[154:157], v[208:211], v[82:85]
	v_mfma_f32_16x16x32_bf16 v[70:73], v[142:145], v[216:219], v[70:73]
	v_mfma_f32_16x16x32_bf16 v[66:69], v[154:157], v[216:219], v[66:69]
	v_mfma_f32_16x16x32_bf16 v[134:137], v[150:153], v[170:173], v[134:137]
	v_mfma_f32_16x16x32_bf16 v[126:129], v[158:161], v[170:173], v[126:129]
	v_mfma_f32_16x16x32_bf16 v[102:105], v[150:153], v[178:181], v[102:105]
	v_mfma_f32_16x16x32_bf16 v[98:101], v[158:161], v[178:181], v[98:101]
	v_mfma_f32_16x16x32_bf16 v[86:89], v[150:153], v[212:215], v[86:89]
	v_mfma_f32_16x16x32_bf16 v[82:85], v[158:161], v[212:215], v[82:85]
	v_mfma_f32_16x16x32_bf16 v[70:73], v[150:153], v[220:223], v[70:73]
	v_mfma_f32_16x16x32_bf16 v[66:69], v[158:161], v[220:223], v[66:69]
	s_setprio 0
	s_barrier
	s_add_i32 s66, s66, s15
	v_lshl_add_u64 v[192:193], s[64:65], 0, v[0:1]
	s_mov_b32 m0, s66
	ds_read_b128 v[166:169], v239 offset:16384
	ds_read_b128 v[170:173], v239 offset:17408
	ds_read_b128 v[174:177], v239 offset:18432
	ds_read_b128 v[178:181], v239 offset:19456
	ds_read_b128 v[208:211], v239 offset:20480
	ds_read_b128 v[212:215], v239 offset:21504
	ds_read_b128 v[216:219], v239 offset:22528
	ds_read_b128 v[220:223], v239 offset:23552
	global_load_lds_dwordx4 v[192:193], off
	s_add_i32 m0, s66, 0x2000
	v_lshl_add_u64 v[198:199], s[64:65], 0, v[182:183]
	s_add_u32 s64, s64, s44
	s_addc_u32 s65, s65, s45
	s_add_i32 s66, s67, s15
	global_load_lds_dwordx4 v[198:199], off
	v_lshl_add_u64 v[200:201], s[64:65], 0, v[0:1]
	s_mov_b32 m0, s66
	v_lshl_add_u64 v[202:203], s[64:65], 0, v[182:183]
	global_load_lds_dwordx4 v[200:201], off
	s_add_i32 m0, s66, 0x2000
	v_lshl_add_u64 v[204:205], s[6:7], 0, v[186:187]
	global_load_lds_dwordx4 v[202:203], off
	s_mov_b32 m0, s24
	v_lshl_add_u64 v[224:225], s[6:7], 0, v[184:185]
	global_load_lds_dwordx4 v[204:205], off
	s_mov_b32 m0, s33
	s_nop 0
	global_load_lds_dwordx4 v[224:225], off
	s_waitcnt vmcnt(8)
	s_waitcnt lgkmcnt(0)
	s_barrier
; #define PG8_STAGE(bufoff, gbase, voff) do { _Pragma("unroll") for (int _i = 0; _i < 2; ++_i) \
;         __builtin_amdgcn_global_load_lds((const unsigned*)((const char*)(gbase) + (voff)[_i]), (PG8_LAS unsigned*)(lds + (bufoff) + ldsw + _i * 8192), 16, 0, 0); } while (0)
; #define PG8_LDA(dst, b, h) do { _Pragma("unroll") for (int m = 0; m < 4; ++m) _Pragma("unroll") for (int k = 0; k < 2; ++k) dst[m][k] = *(const PG8_LAS bf16x8*)(lds + PG8_SA(b, h) + aoff + m * 2048 + k * 1024); } while (0)
; #define PG8_LDB(dst, b, h) do { _Pragma("unroll") for (int n = 0; n < 2; ++n) _Pragma("unroll") for (int k = 0; k < 2; ++k) dst[n][k] = *(const PG8_LAS bf16x8*)(lds + PG8_SB(b, h) + boff + n * 2048 + k * 1024); } while (0)
; #define PG8_MMA(ai, bj, At, Bt) do { __builtin_amdgcn_s_setprio(1); _Pragma("unroll") for (int m = 0; m < 4; ++m) _Pragma("unroll") for (int n = 0; n < 2; ++n) _Pragma("unroll") for (int k = 0; k < 2; ++k) \
;         acc[ai][bj][m][n] = __builtin_amdgcn_mfma_f32_16x16x32_bf16(Bt[n][k], At[m][k], acc[ai][bj][m][n], 0, 0, 0); __builtin_amdgcn_s_setprio(0); } while (0)
; #define PG8_WAIT_V(n) asm volatile("s_waitcnt vmcnt(" #n ")" ::: "memory")
; #define PG8_WAIT_L(n) asm volatile("s_waitcnt lgkmcnt(" #n ")" ::: "memory")
; #define PG8_BAR __builtin_amdgcn_s_barrier()
; #define PG8_SCHED __builtin_amdgcn_sched_barrier(0)
; template <class Epi, class Sched, bool ALIGN_EPI = false, bool SP2 = false>
; __device__ __forceinline__ void gemm_phase(PG8_LAS unsigned char* lds, const Gemm g, const Sched& S, const Epi& E) {
;     ...
;             PG8_WAIT_V(8); PG8_WAIT_L(0); PG8_BAR; PG8_MMA(1, 0, At, B0); PG8_MMA(1, 1, At, B1); PG8_BAR; PG8_SCHED;
;             PG8_LDB(B0, 1, 0); PG8_LDB(B1, 1, 1); PG8_SCHED; PG8_LDA(At, 1, 0); PG8_STAGE(PG8_SA(0, 1), a2 + hstep, voffA);
;             PG8_WAIT_V(8); PG8_WAIT_L(0); PG8_BAR; PG8_MMA(0, 0, At, B0); PG8_MMA(0, 1, At, B1); PG8_BAR; PG8_SCHED;
	s_setprio 1
	s_waitcnt lgkmcnt(0)
	v_mfma_f32_16x16x32_bf16 v[62:65], v[114:117], v[166:169], v[62:65]
	v_mfma_f32_16x16x32_bf16 v[58:61], v[122:125], v[166:169], v[58:61]
	v_mfma_f32_16x16x32_bf16 v[46:49], v[114:117], v[174:177], v[46:49]
	v_mfma_f32_16x16x32_bf16 v[42:45], v[122:125], v[174:177], v[42:45]
	v_mfma_f32_16x16x32_bf16 v[30:33], v[114:117], v[208:211], v[30:33]
	v_mfma_f32_16x16x32_bf16 v[26:29], v[122:125], v[208:211], v[26:29]
	v_mfma_f32_16x16x32_bf16 v[14:17], v[114:117], v[216:219], v[14:17]
	v_mfma_f32_16x16x32_bf16 v[10:13], v[122:125], v[216:219], v[10:13]
	v_mfma_f32_16x16x32_bf16 v[62:65], v[118:121], v[170:173], v[62:65]
	v_mfma_f32_16x16x32_bf16 v[58:61], v[138:141], v[170:173], v[58:61]
	v_mfma_f32_16x16x32_bf16 v[46:49], v[118:121], v[178:181], v[46:49]
	v_mfma_f32_16x16x32_bf16 v[42:45], v[138:141], v[178:181], v[42:45]
	v_mfma_f32_16x16x32_bf16 v[30:33], v[118:121], v[212:215], v[30:33]
	v_mfma_f32_16x16x32_bf16 v[26:29], v[138:141], v[212:215], v[26:29]
	v_mfma_f32_16x16x32_bf16 v[14:17], v[118:121], v[220:223], v[14:17]
	v_mfma_f32_16x16x32_bf16 v[10:13], v[138:141], v[220:223], v[10:13]
	v_mfma_f32_16x16x32_bf16 v[54:57], v[142:145], v[166:169], v[54:57]
	v_mfma_f32_16x16x32_bf16 v[50:53], v[154:157], v[166:169], v[50:53]
	v_mfma_f32_16x16x32_bf16 v[38:41], v[142:145], v[174:177], v[38:41]
	v_mfma_f32_16x16x32_bf16 v[34:37], v[154:157], v[174:177], v[34:37]
	v_mfma_f32_16x16x32_bf16 v[22:25], v[142:145], v[208:211], v[22:25]
	v_mfma_f32_16x16x32_bf16 v[18:21], v[154:157], v[208:211], v[18:21]
	v_mfma_f32_16x16x32_bf16 v[6:9], v[142:145], v[216:219], v[6:9]
	v_mfma_f32_16x16x32_bf16 v[2:5], v[154:157], v[216:219], v[2:5]
	v_mfma_f32_16x16x32_bf16 v[54:57], v[150:153], v[170:173], v[54:57]
	v_mfma_f32_16x16x32_bf16 v[50:53], v[158:161], v[170:173], v[50:53]
	v_mfma_f32_16x16x32_bf16 v[38:41], v[150:153], v[178:181], v[38:41]
	v_mfma_f32_16x16x32_bf16 v[34:37], v[158:161], v[178:181], v[34:37]
	v_mfma_f32_16x16x32_bf16 v[22:25], v[150:153], v[212:215], v[22:25]
	v_mfma_f32_16x16x32_bf16 v[18:21], v[158:161], v[212:215], v[18:21]
	v_mfma_f32_16x16x32_bf16 v[6:9], v[150:153], v[220:223], v[6:9]
	v_mfma_f32_16x16x32_bf16 v[2:5], v[158:161], v[220:223], v[2:5]
	s_setprio 0
	s_barrier
	s_add_i32 s64, 0, 0x18000
	s_add_i32 s65, 0, 0x1c000
	v_add_u32_e32 v138, s64, v237
	v_add_u32_e32 v158, s65, v237
	ds_read_b128 v[114:117], v138
	ds_read_b128 v[118:121], v138 offset:1024
	ds_read_b128 v[122:125], v138 offset:2048
	ds_read_b128 v[138:141], v138 offset:3072
	ds_read_b128 v[142:145], v158
	ds_read_b128 v[150:153], v158 offset:1024
	ds_read_b128 v[154:157], v158 offset:2048
	ds_read_b128 v[158:161], v158 offset:3072
	s_add_u32 s6, s6, s44
	s_addc_u32 s7, s7, s45
	s_mov_b32 m0, s60
	v_lshl_add_u64 v[228:229], s[6:7], 0, v[186:187]
	ds_read_b128 v[166:169], v239 offset:32768
	ds_read_b128 v[170:173], v239 offset:33792
	ds_read_b128 v[174:177], v239 offset:34816
	ds_read_b128 v[178:181], v239 offset:35840
	ds_read_b128 v[208:211], v239 offset:36864
	ds_read_b128 v[212:215], v239 offset:37888
	ds_read_b128 v[216:219], v239 offset:38912
	ds_read_b128 v[220:223], v239 offset:39936
	global_load_lds_dwordx4 v[228:229], off
	v_lshl_add_u64 v[228:229], s[6:7], 0, v[184:185]
	s_mov_b32 m0, s61
	s_nop 0
	global_load_lds_dwordx4 v[228:229], off
	s_waitcnt vmcnt(8)
	s_waitcnt lgkmcnt(0)
	s_barrier
	s_setprio 1
	s_waitcnt lgkmcnt(0)
	v_mfma_f32_16x16x32_bf16 v[162:165], v[114:117], v[166:169], v[162:165]
	v_mfma_f32_16x16x32_bf16 v[146:149], v[122:125], v[166:169], v[146:149]
	v_mfma_f32_16x16x32_bf16 v[110:113], v[114:117], v[174:177], v[110:113]
	v_mfma_f32_16x16x32_bf16 v[106:109], v[122:125], v[174:177], v[106:109]
	v_mfma_f32_16x16x32_bf16 v[94:97], v[114:117], v[208:211], v[94:97]
	v_mfma_f32_16x16x32_bf16 v[90:93], v[122:125], v[208:211], v[90:93]
	v_mfma_f32_16x16x32_bf16 v[78:81], v[114:117], v[216:219], v[78:81]
	v_mfma_f32_16x16x32_bf16 v[74:77], v[122:125], v[216:219], v[74:77]
	v_mfma_f32_16x16x32_bf16 v[162:165], v[118:121], v[170:173], v[162:165]
	v_mfma_f32_16x16x32_bf16 v[146:149], v[138:141], v[170:173], v[146:149]
	v_mfma_f32_16x16x32_bf16 v[110:113], v[118:121], v[178:181], v[110:113]
	v_mfma_f32_16x16x32_bf16 v[106:109], v[138:141], v[178:181], v[106:109]
	v_mfma_f32_16x16x32_bf16 v[94:97], v[118:121], v[212:215], v[94:97]
	v_mfma_f32_16x16x32_bf16 v[90:93], v[138:141], v[212:215], v[90:93]
	v_mfma_f32_16x16x32_bf16 v[78:81], v[118:121], v[220:223], v[78:81]
	v_mfma_f32_16x16x32_bf16 v[74:77], v[138:141], v[220:223], v[74:77]
	v_mfma_f32_16x16x32_bf16 v[134:137], v[142:145], v[166:169], v[134:137]
	v_mfma_f32_16x16x32_bf16 v[126:129], v[154:157], v[166:169], v[126:129]
	v_mfma_f32_16x16x32_bf16 v[102:105], v[142:145], v[174:177], v[102:105]
	v_mfma_f32_16x16x32_bf16 v[98:101], v[154:157], v[174:177], v[98:101]
	v_mfma_f32_16x16x32_bf16 v[86:89], v[142:145], v[208:211], v[86:89]
	v_mfma_f32_16x16x32_bf16 v[82:85], v[154:157], v[208:211], v[82:85]
	v_mfma_f32_16x16x32_bf16 v[70:73], v[142:145], v[216:219], v[70:73]
	v_mfma_f32_16x16x32_bf16 v[66:69], v[154:157], v[216:219], v[66:69]
	v_mfma_f32_16x16x32_bf16 v[134:137], v[150:153], v[170:173], v[134:137]
	v_mfma_f32_16x16x32_bf16 v[126:129], v[158:161], v[170:173], v[126:129]
	v_mfma_f32_16x16x32_bf16 v[102:105], v[150:153], v[178:181], v[102:105]
	v_mfma_f32_16x16x32_bf16 v[98:101], v[158:161], v[178:181], v[98:101]
	v_mfma_f32_16x16x32_bf16 v[86:89], v[150:153], v[212:215], v[86:89]
	v_mfma_f32_16x16x32_bf16 v[82:85], v[158:161], v[212:215], v[82:85]
	v_mfma_f32_16x16x32_bf16 v[70:73], v[150:153], v[220:223], v[70:73]
	v_mfma_f32_16x16x32_bf16 v[66:69], v[158:161], v[220:223], v[66:69]
	s_setprio 0
	s_barrier
; #define PG8_STAGE(bufoff, gbase, voff) do { _Pragma("unroll") for (int _i = 0; _i < 2; ++_i) \
;         __builtin_amdgcn_global_load_lds((const unsigned*)((const char*)(gbase) + (voff)[_i]), (PG8_LAS unsigned*)(lds + (bufoff) + ldsw + _i * 8192), 16, 0, 0); } while (0)
; #define PG8_LDA(dst, b, h) do { _Pragma("unroll") for (int m = 0; m < 4; ++m) _Pragma("unroll") for (int k = 0; k < 2; ++k) dst[m][k] = *(const PG8_LAS bf16x8*)(lds + PG8_SA(b, h) + aoff + m * 2048 + k * 1024); } while (0)
; #define PG8_MMA(ai, bj, At, Bt) do { __builtin_amdgcn_s_setprio(1); _Pragma("unroll") for (int m = 0; m < 4; ++m) _Pragma("unroll") for (int n = 0; n < 2; ++n) _Pragma("unroll") for (int k = 0; k < 2; ++k) \
;         acc[ai][bj][m][n] = __builtin_amdgcn_mfma_f32_16x16x32_bf16(Bt[n][k], At[m][k], acc[ai][bj][m][n], 0, 0, 0); __builtin_amdgcn_s_setprio(0); } while (0)
; #define PG8_WAIT_V(n) asm volatile("s_waitcnt vmcnt(" #n ")" ::: "memory")
; #define PG8_WAIT_L(n) asm volatile("s_waitcnt lgkmcnt(" #n ")" ::: "memory")
; #define PG8_BAR __builtin_amdgcn_s_barrier()
; #define PG8_SCHED __builtin_amdgcn_sched_barrier(0)
; template <class Epi, class Sched, bool ALIGN_EPI = false, bool SP2 = false>
; __device__ __forceinline__ void gemm_phase(PG8_LAS unsigned char* lds, const Gemm g, const Sched& S, const Epi& E) {
;     ...
;             PG8_LDA(At, 1, 1); PG8_STAGE(PG8_SB(1, 0), b3, voffB); PG8_STAGE(PG8_SB(1, 1), b3 + hstep, voffB); PG8_STAGE(PG8_SA(1, 0), a3, voffA);
;             PG8_WAIT_V(8); PG8_WAIT_L(0); PG8_BAR; PG8_MMA(1, 0, At, B0); PG8_MMA(1, 1, At, B1); PG8_BAR; PG8_SCHED;
	s_add_i32 s6, s64, s15
	v_lshl_add_u64 v[192:193], v[192:193], 0, s[26:27]
	s_mov_b32 m0, s6
	ds_read_b128 v[166:169], v239 offset:49152
	ds_read_b128 v[170:173], v239 offset:50176
	ds_read_b128 v[174:177], v239 offset:51200
	ds_read_b128 v[178:181], v239 offset:52224
	ds_read_b128 v[208:211], v239 offset:53248
	ds_read_b128 v[212:215], v239 offset:54272
	ds_read_b128 v[216:219], v239 offset:55296
	ds_read_b128 v[220:223], v239 offset:56320
	global_load_lds_dwordx4 v[192:193], off
	v_lshl_add_u64 v[192:193], v[198:199], 0, s[26:27]
	s_add_i32 m0, s6, 0x2000
	s_add_i32 s6, s65, s15
	global_load_lds_dwordx4 v[192:193], off
	v_lshl_add_u64 v[192:193], v[200:201], 0, s[26:27]
	s_mov_b32 m0, s6
	s_nop 0
	global_load_lds_dwordx4 v[192:193], off
	v_lshl_add_u64 v[192:193], v[202:203], 0, s[26:27]
	s_add_i32 m0, s6, 0x2000
	s_nop 0
	global_load_lds_dwordx4 v[192:193], off
	v_lshl_add_u64 v[192:193], v[204:205], 0, s[26:27]
	s_mov_b32 m0, s80
	s_nop 0
	global_load_lds_dwordx4 v[192:193], off
	v_lshl_add_u64 v[192:193], v[224:225], 0, s[26:27]
	s_mov_b32 m0, s81
	s_nop 0
	global_load_lds_dwordx4 v[192:193], off
	s_waitcnt vmcnt(8)
	s_waitcnt lgkmcnt(0)
	s_barrier
	s_setprio 1
	s_waitcnt lgkmcnt(0)
	v_mfma_f32_16x16x32_bf16 v[62:65], v[114:117], v[166:169], v[62:65]
	v_mfma_f32_16x16x32_bf16 v[58:61], v[122:125], v[166:169], v[58:61]
	v_mfma_f32_16x16x32_bf16 v[46:49], v[114:117], v[174:177], v[46:49]
	v_mfma_f32_16x16x32_bf16 v[42:45], v[122:125], v[174:177], v[42:45]
	v_mfma_f32_16x16x32_bf16 v[30:33], v[114:117], v[208:211], v[30:33]
	v_mfma_f32_16x16x32_bf16 v[26:29], v[122:125], v[208:211], v[26:29]
	v_mfma_f32_16x16x32_bf16 v[14:17], v[114:117], v[216:219], v[14:17]
	v_mfma_f32_16x16x32_bf16 v[10:13], v[122:125], v[216:219], v[10:13]
	v_mfma_f32_16x16x32_bf16 v[62:65], v[118:121], v[170:173], v[62:65]
	v_mfma_f32_16x16x32_bf16 v[58:61], v[138:141], v[170:173], v[58:61]
	v_mfma_f32_16x16x32_bf16 v[46:49], v[118:121], v[178:181], v[46:49]
	v_mfma_f32_16x16x32_bf16 v[42:45], v[138:141], v[178:181], v[42:45]
	v_mfma_f32_16x16x32_bf16 v[30:33], v[118:121], v[212:215], v[30:33]
	v_mfma_f32_16x16x32_bf16 v[26:29], v[138:141], v[212:215], v[26:29]
	v_mfma_f32_16x16x32_bf16 v[14:17], v[118:121], v[220:223], v[14:17]
	v_mfma_f32_16x16x32_bf16 v[10:13], v[138:141], v[220:223], v[10:13]
	v_mfma_f32_16x16x32_bf16 v[54:57], v[142:145], v[166:169], v[54:57]
	v_mfma_f32_16x16x32_bf16 v[50:53], v[154:157], v[166:169], v[50:53]
	v_mfma_f32_16x16x32_bf16 v[38:41], v[142:145], v[174:177], v[38:41]
	v_mfma_f32_16x16x32_bf16 v[34:37], v[154:157], v[174:177], v[34:37]
	v_mfma_f32_16x16x32_bf16 v[22:25], v[142:145], v[208:211], v[22:25]
	v_mfma_f32_16x16x32_bf16 v[18:21], v[154:157], v[208:211], v[18:21]
	v_mfma_f32_16x16x32_bf16 v[6:9], v[142:145], v[216:219], v[6:9]
	v_mfma_f32_16x16x32_bf16 v[2:5], v[154:157], v[216:219], v[2:5]
	v_mfma_f32_16x16x32_bf16 v[54:57], v[150:153], v[170:173], v[54:57]
	v_mfma_f32_16x16x32_bf16 v[50:53], v[158:161], v[170:173], v[50:53]
	v_mfma_f32_16x16x32_bf16 v[38:41], v[150:153], v[178:181], v[38:41]
	v_mfma_f32_16x16x32_bf16 v[34:37], v[158:161], v[178:181], v[34:37]
	v_mfma_f32_16x16x32_bf16 v[22:25], v[150:153], v[212:215], v[22:25]
	v_mfma_f32_16x16x32_bf16 v[18:21], v[158:161], v[212:215], v[18:21]
	v_mfma_f32_16x16x32_bf16 v[6:9], v[150:153], v[220:223], v[6:9]
	v_mfma_f32_16x16x32_bf16 v[2:5], v[158:161], v[220:223], v[2:5]
	s_setprio 0
	s_barrier
	s_add_u32 s4, s4, 0x100
	s_addc_u32 s5, s5, 0
	s_add_u32 s8, s8, 0x100
	s_addc_u32 s9, s9, 0
	s_cmp_ge_i32 s78, s97
	s_mov_b32 s6, s78
	s_cbranch_scc0 .LBB0_579
